# hipcc GEMM K-steps (phases 3,9,10,13): B-fragment reads first and counted lgkmcnt waits at the first consuming MFMA
# speedup vs baseline: 1.0017x; 1.0002x over previous
.LBB0_397:
	v_add_u32_e32 v6, 64, v18
	v_mad_i64_i32 v[8:9], s[18:19], v6, s8, v[0:1]
	v_add_u32_e32 v6, 32, v18
	v_mov_b32_e32 v19, v199
	v_add_u32_e32 v4, 0x60, v18
	v_mad_i64_i32 v[12:13], s[18:19], v6, s8, v[0:1]
	v_mad_i64_i32 v[116:117], s[18:19], v18, s8, v[0:1]
	v_add_u32_e32 v6, 0x60, v15
	v_add_u32_e32 v10, 64, v15
	v_add_u32_e32 v18, 32, v15
	v_mad_i64_i32 v[4:5], s[18:19], v4, s8, v[0:1]
	v_lshlrev_b32_e32 v23, 4, v19
	v_mad_i64_i32 v[6:7], s[18:19], v6, s8, v[2:3]
	v_mad_i64_i32 v[10:11], s[18:19], v10, s8, v[2:3]
	v_mad_i64_i32 v[118:119], s[18:19], v18, s8, v[2:3]
	v_mad_i64_i32 v[120:121], s[18:19], v15, s8, v[2:3]
	v_add_u32_e32 v24, 0x8000, v23
	v_readfirstlane_b32 s25, v23
	v_readfirstlane_b32 s18, v24
	v_add_u32_e32 v24, 0x1000, v23
	s_mov_b32 m0, s25
	v_readfirstlane_b32 s19, v24
	v_add_u32_e32 v24, 0x9000, v23
	s_barrier
	global_load_lds_dwordx4 v[116:117], off
	s_mov_b32 m0, s18
	v_readfirstlane_b32 s20, v24
	v_add_u32_e32 v24, 0x2000, v23
	global_load_lds_dwordx4 v[120:121], off
	s_mov_b32 m0, s19
	v_readfirstlane_b32 s21, v24
	v_add_u32_e32 v24, 0xa000, v23
	global_load_lds_dwordx4 v[12:13], off
	s_mov_b32 m0, s20
	v_readfirstlane_b32 s22, v24
	v_add_u32_e32 v24, 0x3000, v23
	global_load_lds_dwordx4 v[118:119], off
	s_mov_b32 m0, s21
	v_readfirstlane_b32 s23, v24
	v_add_u32_e32 v24, 0xb000, v23
	v_bfe_u32 v22, v19, 4, 2
	global_load_lds_dwordx4 v[8:9], off
	s_mov_b32 m0, s22
	v_readfirstlane_b32 s33, v24
	v_bfe_u32 v24, v19, 1, 3
	v_and_b32_e32 v20, 15, v19
	global_load_lds_dwordx4 v[10:11], off
	s_mov_b32 m0, s23
	v_lshrrev_b32_e32 v25, 1, v19
	s_mov_b32 s56, 0x1ffffc0
	v_bitop3_b32 v89, v22, v24, 4 bitop3:0x36
	v_add_u32_e32 v22, 0x4000, v23
	v_lshrrev_b32_e32 v21, 4, v19
	global_load_lds_dwordx4 v[4:5], off
	s_mov_b32 m0, s33
	v_and_or_b32 v20, v25, s56, v20
	v_readfirstlane_b32 s56, v22
	v_add_u32_e32 v22, 0xc000, v23
	global_load_lds_dwordx4 v[6:7], off
	v_lshlrev_b32_e32 v88, 7, v20
	v_bitop3_b32 v25, v21, v24, 3 bitop3:0x6c
	v_lshl_add_u64 v[20:21], v[116:117], 0, s[0:1]
	s_mov_b32 m0, s56
	v_readfirstlane_b32 s56, v22
	v_add_u32_e32 v22, 0x5000, v23
	s_waitcnt vmcnt(0)
	s_waitcnt vmcnt(0) lgkmcnt(0)
	s_barrier
	global_load_lds_dwordx4 v[20:21], off
	v_lshl_add_u64 v[20:21], v[120:121], 0, s[0:1]
	s_mov_b32 m0, s56
	v_readfirstlane_b32 s56, v22
	v_add_u32_e32 v22, 0xd000, v23
	global_load_lds_dwordx4 v[20:21], off
	v_lshl_add_u64 v[20:21], v[12:13], 0, s[0:1]
	s_mov_b32 m0, s56
	v_readfirstlane_b32 s56, v22
	v_add_u32_e32 v22, 0x6000, v23
	global_load_lds_dwordx4 v[20:21], off
	v_lshl_add_u64 v[20:21], v[118:119], 0, s[0:1]
	s_mov_b32 m0, s56
	v_readfirstlane_b32 s56, v22
	v_add_u32_e32 v22, 0xe000, v23
	global_load_lds_dwordx4 v[20:21], off
	v_lshl_add_u64 v[20:21], v[8:9], 0, s[0:1]
	s_mov_b32 m0, s56
	v_readfirstlane_b32 s56, v22
	v_add_u32_e32 v22, 0x7000, v23
	global_load_lds_dwordx4 v[20:21], off
	v_lshl_add_u64 v[20:21], v[10:11], 0, s[0:1]
	s_mov_b32 m0, s56
	v_readfirstlane_b32 s56, v22
	v_add_u32_e32 v22, 0xf000, v23
	global_load_lds_dwordx4 v[20:21], off
	v_lshl_add_u64 v[20:21], v[4:5], 0, s[0:1]
	s_mov_b32 m0, s56
	v_readfirstlane_b32 s56, v22
	global_load_lds_dwordx4 v[20:21], off
	v_lshl_add_u64 v[20:21], v[6:7], 0, s[0:1]
	s_mov_b32 m0, s56
	v_add_u32_e32 v18, s14, v14
	global_load_lds_dwordx4 v[20:21], off
	v_add_u32_e32 v15, s15, v14
	v_lshlrev_b32_e32 v19, 7, v19
	v_and_b32_e32 v19, 0x2780, v19
	v_lshlrev_b32_e32 v36, 4, v25
	v_or_b32_e32 v122, v88, v36
	v_or_b32_e32 v123, v19, v36
	ds_read_b128 v[20:23], v122
	ds_read_b128 v[24:27], v122 offset:2048
	ds_read_b128 v[28:31], v122 offset:4096
	ds_read_b128 v[32:35], v122 offset:6144
	ds_read_b128 v[36:39], v123 offset:32768
	ds_read_b128 v[40:43], v123 offset:34816
	ds_read_b128 v[44:47], v123 offset:36864
	ds_read_b128 v[48:51], v123 offset:38912
	s_setprio 1
	s_waitcnt lgkmcnt(0)
	v_mfma_f32_16x16x32_bf16 v[52:55], v[36:39], v[20:23], 0
	v_mfma_f32_16x16x32_bf16 v[56:59], v[40:43], v[20:23], 0
	v_mfma_f32_16x16x32_bf16 v[60:63], v[44:47], v[20:23], 0
	v_mfma_f32_16x16x32_bf16 v[20:23], v[48:51], v[20:23], 0
	v_mfma_f32_16x16x32_bf16 v[64:67], v[36:39], v[24:27], 0
	v_mfma_f32_16x16x32_bf16 v[68:71], v[40:43], v[24:27], 0
	v_mfma_f32_16x16x32_bf16 v[72:75], v[44:47], v[24:27], 0
	v_mfma_f32_16x16x32_bf16 v[24:27], v[48:51], v[24:27], 0
	v_mfma_f32_16x16x32_bf16 v[76:79], v[36:39], v[28:31], 0
	v_mfma_f32_16x16x32_bf16 v[80:83], v[40:43], v[28:31], 0
	v_mfma_f32_16x16x32_bf16 v[84:87], v[44:47], v[28:31], 0
	v_mfma_f32_16x16x32_bf16 v[28:31], v[48:51], v[28:31], 0
	v_mfma_f32_16x16x32_bf16 v[36:39], v[36:39], v[32:35], 0
	v_mfma_f32_16x16x32_bf16 v[40:43], v[40:43], v[32:35], 0
	v_mfma_f32_16x16x32_bf16 v[44:47], v[44:47], v[32:35], 0
	v_mfma_f32_16x16x32_bf16 v[32:35], v[48:51], v[32:35], 0
	s_setprio 0
	v_lshlrev_b32_e32 v100, 4, v89
	v_or_b32_e32 v124, v88, v100
	v_or_b32_e32 v19, v19, v100
	ds_read_b128 v[100:103], v19 offset:32768
	ds_read_b128 v[104:107], v19 offset:34816
	ds_read_b128 v[108:111], v19 offset:36864
	ds_read_b128 v[112:115], v19 offset:38912
	ds_read_b128 v[48:51], v124
	ds_read_b128 v[88:91], v124 offset:2048
	ds_read_b128 v[92:95], v124 offset:4096
	ds_read_b128 v[96:99], v124 offset:6144
	s_setprio 1
	s_waitcnt lgkmcnt(3)
	v_mfma_f32_16x16x32_bf16 v[52:55], v[100:103], v[48:51], v[52:55]
	v_mfma_f32_16x16x32_bf16 v[56:59], v[104:107], v[48:51], v[56:59]
	v_mfma_f32_16x16x32_bf16 v[60:63], v[108:111], v[48:51], v[60:63]
	v_mfma_f32_16x16x32_bf16 v[20:23], v[112:115], v[48:51], v[20:23]
	s_waitcnt lgkmcnt(2)
	v_mfma_f32_16x16x32_bf16 v[48:51], v[100:103], v[88:91], v[64:67]
	v_mfma_f32_16x16x32_bf16 v[64:67], v[104:107], v[88:91], v[68:71]
	v_mfma_f32_16x16x32_bf16 v[68:71], v[108:111], v[88:91], v[72:75]
	v_mfma_f32_16x16x32_bf16 v[24:27], v[112:115], v[88:91], v[24:27]
	s_waitcnt lgkmcnt(1)
	v_mfma_f32_16x16x32_bf16 v[72:75], v[100:103], v[92:95], v[76:79]
	v_mfma_f32_16x16x32_bf16 v[76:79], v[104:107], v[92:95], v[80:83]
	v_mfma_f32_16x16x32_bf16 v[80:83], v[108:111], v[92:95], v[84:87]
	v_mfma_f32_16x16x32_bf16 v[28:31], v[112:115], v[92:95], v[28:31]
	s_waitcnt lgkmcnt(0)
	v_mfma_f32_16x16x32_bf16 v[36:39], v[100:103], v[96:99], v[36:39]
	v_mfma_f32_16x16x32_bf16 v[40:43], v[104:107], v[96:99], v[40:43]
	v_mfma_f32_16x16x32_bf16 v[44:47], v[108:111], v[96:99], v[44:47]
	v_mfma_f32_16x16x32_bf16 v[32:35], v[112:115], v[96:99], v[32:35]
	s_setprio 0
	s_mov_b32 m0, s25
	v_lshl_add_u64 v[84:85], v[116:117], 0, s[2:3]
	s_waitcnt vmcnt(0)
	s_waitcnt vmcnt(0)
	s_barrier
	global_load_lds_dwordx4 v[84:85], off
	v_lshl_add_u64 v[84:85], v[120:121], 0, s[2:3]
	s_mov_b32 m0, s18
	v_lshl_add_u64 v[12:13], v[12:13], 0, s[2:3]
	global_load_lds_dwordx4 v[84:85], off
	s_mov_b32 m0, s19
	v_lshl_add_u64 v[8:9], v[8:9], 0, s[2:3]
	global_load_lds_dwordx4 v[12:13], off
	v_lshl_add_u64 v[12:13], v[118:119], 0, s[2:3]
	s_mov_b32 m0, s20
	v_lshl_add_u64 v[4:5], v[4:5], 0, s[2:3]
	global_load_lds_dwordx4 v[12:13], off
	s_mov_b32 m0, s21
	s_nop 0
	global_load_lds_dwordx4 v[8:9], off
	v_lshl_add_u64 v[8:9], v[10:11], 0, s[2:3]
	s_mov_b32 m0, s22
	s_nop 0
	global_load_lds_dwordx4 v[8:9], off
	s_mov_b32 m0, s23
	s_nop 0
	global_load_lds_dwordx4 v[4:5], off
	v_lshl_add_u64 v[4:5], v[6:7], 0, s[2:3]
	s_mov_b32 m0, s33
	s_nop 0
	global_load_lds_dwordx4 v[4:5], off
	ds_read_b128 v[92:95], v123 offset:49152
	ds_read_b128 v[96:99], v123 offset:51200
	ds_read_b128 v[100:103], v123 offset:53248
	ds_read_b128 v[104:107], v123 offset:55296
	ds_read_b128 v[4:7], v122 offset:16384
	ds_read_b128 v[8:11], v122 offset:18432
	ds_read_b128 v[84:87], v122 offset:20480
	ds_read_b128 v[88:91], v122 offset:22528
	s_setprio 1
	s_waitcnt lgkmcnt(3)
	v_mfma_f32_16x16x32_bf16 v[52:55], v[92:95], v[4:7], v[52:55]
	v_mfma_f32_16x16x32_bf16 v[56:59], v[96:99], v[4:7], v[56:59]
	v_mfma_f32_16x16x32_bf16 v[60:63], v[100:103], v[4:7], v[60:63]
	v_mfma_f32_16x16x32_bf16 v[4:7], v[104:107], v[4:7], v[20:23]
	s_waitcnt lgkmcnt(2)
	v_mfma_f32_16x16x32_bf16 v[20:23], v[92:95], v[8:11], v[48:51]
	v_mfma_f32_16x16x32_bf16 v[48:51], v[96:99], v[8:11], v[64:67]
	v_mfma_f32_16x16x32_bf16 v[64:67], v[100:103], v[8:11], v[68:71]
	v_mfma_f32_16x16x32_bf16 v[8:11], v[104:107], v[8:11], v[24:27]
	s_waitcnt lgkmcnt(1)
	v_mfma_f32_16x16x32_bf16 v[24:27], v[92:95], v[84:87], v[72:75]
	v_mfma_f32_16x16x32_bf16 v[68:71], v[96:99], v[84:87], v[76:79]
	v_mfma_f32_16x16x32_bf16 v[72:75], v[100:103], v[84:87], v[80:83]
	v_mfma_f32_16x16x32_bf16 v[28:31], v[104:107], v[84:87], v[28:31]
	s_waitcnt lgkmcnt(0)
	v_mfma_f32_16x16x32_bf16 v[36:39], v[92:95], v[88:91], v[36:39]
	v_mfma_f32_16x16x32_bf16 v[40:43], v[96:99], v[88:91], v[40:43]
	v_mfma_f32_16x16x32_bf16 v[44:47], v[100:103], v[88:91], v[44:47]
	v_mfma_f32_16x16x32_bf16 v[32:35], v[104:107], v[88:91], v[32:35]
	s_setprio 0
	ds_read_b128 v[92:95], v19 offset:49152
	ds_read_b128 v[96:99], v19 offset:51200
	ds_read_b128 v[100:103], v19 offset:53248
	ds_read_b128 v[104:107], v19 offset:55296
	ds_read_b128 v[76:79], v124 offset:16384
	ds_read_b128 v[80:83], v124 offset:18432
	ds_read_b128 v[84:87], v124 offset:20480
	ds_read_b128 v[88:91], v124 offset:22528
	s_setprio 1
	s_waitcnt lgkmcnt(3)
	v_mfma_f32_16x16x32_bf16 v[52:55], v[92:95], v[76:79], v[52:55]
	v_mfma_f32_16x16x32_bf16 v[56:59], v[96:99], v[76:79], v[56:59]
	v_mfma_f32_16x16x32_bf16 v[60:63], v[100:103], v[76:79], v[60:63]
	v_mfma_f32_16x16x32_bf16 v[4:7], v[104:107], v[76:79], v[4:7]
	s_waitcnt lgkmcnt(2)
	v_mfma_f32_16x16x32_bf16 v[20:23], v[92:95], v[80:83], v[20:23]
	v_mfma_f32_16x16x32_bf16 v[48:51], v[96:99], v[80:83], v[48:51]
	v_mfma_f32_16x16x32_bf16 v[64:67], v[100:103], v[80:83], v[64:67]
	v_mfma_f32_16x16x32_bf16 v[8:11], v[104:107], v[80:83], v[8:11]
	s_waitcnt lgkmcnt(1)
	v_mfma_f32_16x16x32_bf16 v[24:27], v[92:95], v[84:87], v[24:27]
	v_mfma_f32_16x16x32_bf16 v[68:71], v[96:99], v[84:87], v[68:71]
	v_mfma_f32_16x16x32_bf16 v[72:75], v[100:103], v[84:87], v[72:75]
	v_mfma_f32_16x16x32_bf16 v[28:31], v[104:107], v[84:87], v[28:31]
	s_waitcnt lgkmcnt(0)
	v_mfma_f32_16x16x32_bf16 v[36:39], v[92:95], v[88:91], v[36:39]
	v_mfma_f32_16x16x32_bf16 v[40:43], v[96:99], v[88:91], v[40:43]
	v_mfma_f32_16x16x32_bf16 v[44:47], v[100:103], v[88:91], v[44:47]
	v_mfma_f32_16x16x32_bf16 v[32:35], v[104:107], v[88:91], v[32:35]
	s_setprio 0
	s_waitcnt vmcnt(0)
	s_waitcnt vmcnt(0)
	s_barrier
	ds_read_b128 v[76:79], v122
	ds_read_b128 v[80:83], v122 offset:2048
	ds_read_b128 v[84:87], v122 offset:4096
	ds_read_b128 v[88:91], v122 offset:6144
	ds_read_b128 v[92:95], v123 offset:32768
	ds_read_b128 v[96:99], v123 offset:34816
	ds_read_b128 v[100:103], v123 offset:36864
	ds_read_b128 v[104:107], v123 offset:38912
	s_setprio 1
	s_waitcnt lgkmcnt(3)
	v_mfma_f32_16x16x32_bf16 v[52:55], v[92:95], v[76:79], v[52:55]
	s_waitcnt lgkmcnt(2)
	v_mfma_f32_16x16x32_bf16 v[56:59], v[96:99], v[76:79], v[56:59]
	s_waitcnt lgkmcnt(1)
	v_mfma_f32_16x16x32_bf16 v[60:63], v[100:103], v[76:79], v[60:63]
	s_waitcnt lgkmcnt(0)
	v_mfma_f32_16x16x32_bf16 v[4:7], v[104:107], v[76:79], v[4:7]
	v_mfma_f32_16x16x32_bf16 v[20:23], v[92:95], v[80:83], v[20:23]
	v_mfma_f32_16x16x32_bf16 v[48:51], v[96:99], v[80:83], v[48:51]
	v_mfma_f32_16x16x32_bf16 v[64:67], v[100:103], v[80:83], v[64:67]
	v_mfma_f32_16x16x32_bf16 v[8:11], v[104:107], v[80:83], v[8:11]
	v_mfma_f32_16x16x32_bf16 v[24:27], v[92:95], v[84:87], v[24:27]
	v_mfma_f32_16x16x32_bf16 v[68:71], v[96:99], v[84:87], v[68:71]
	v_mfma_f32_16x16x32_bf16 v[72:75], v[100:103], v[84:87], v[72:75]
	v_mfma_f32_16x16x32_bf16 v[28:31], v[104:107], v[84:87], v[28:31]
	v_mfma_f32_16x16x32_bf16 v[36:39], v[92:95], v[88:91], v[36:39]
	v_mfma_f32_16x16x32_bf16 v[40:43], v[96:99], v[88:91], v[40:43]
	v_mfma_f32_16x16x32_bf16 v[44:47], v[100:103], v[88:91], v[44:47]
	v_mfma_f32_16x16x32_bf16 v[32:35], v[104:107], v[88:91], v[32:35]
	s_setprio 0
	ds_read_b128 v[76:79], v124
	ds_read_b128 v[80:83], v124 offset:2048
	ds_read_b128 v[84:87], v124 offset:4096
	ds_read_b128 v[88:91], v124 offset:6144
	ds_read_b128 v[92:95], v19 offset:32768
	ds_read_b128 v[96:99], v19 offset:34816
	ds_read_b128 v[100:103], v19 offset:36864
	ds_read_b128 v[104:107], v19 offset:38912
	s_setprio 1
	s_waitcnt lgkmcnt(3)
	v_mfma_f32_16x16x32_bf16 v[52:55], v[92:95], v[76:79], v[52:55]
	s_waitcnt lgkmcnt(2)
	v_mfma_f32_16x16x32_bf16 v[56:59], v[96:99], v[76:79], v[56:59]
	s_waitcnt lgkmcnt(1)
	v_mfma_f32_16x16x32_bf16 v[60:63], v[100:103], v[76:79], v[60:63]
	s_waitcnt lgkmcnt(0)
	v_mfma_f32_16x16x32_bf16 v[4:7], v[104:107], v[76:79], v[4:7]
	v_mfma_f32_16x16x32_bf16 v[20:23], v[92:95], v[80:83], v[20:23]
	v_mfma_f32_16x16x32_bf16 v[48:51], v[96:99], v[80:83], v[48:51]
	v_mfma_f32_16x16x32_bf16 v[64:67], v[100:103], v[80:83], v[64:67]
	v_mfma_f32_16x16x32_bf16 v[8:11], v[104:107], v[80:83], v[8:11]
	v_mfma_f32_16x16x32_bf16 v[24:27], v[92:95], v[84:87], v[24:27]
	v_mfma_f32_16x16x32_bf16 v[68:71], v[96:99], v[84:87], v[68:71]
	v_mfma_f32_16x16x32_bf16 v[72:75], v[100:103], v[84:87], v[72:75]
	v_mfma_f32_16x16x32_bf16 v[28:31], v[104:107], v[84:87], v[28:31]
	v_mfma_f32_16x16x32_bf16 v[36:39], v[92:95], v[88:91], v[36:39]
	v_mfma_f32_16x16x32_bf16 v[40:43], v[96:99], v[88:91], v[40:43]
	v_mfma_f32_16x16x32_bf16 v[44:47], v[100:103], v[88:91], v[44:47]
	v_mfma_f32_16x16x32_bf16 v[32:35], v[104:107], v[88:91], v[32:35]
	s_setprio 0
	v_add_u32_e32 v12, s17, v16
	v_ashrrev_i32_e32 v13, 31, v12
	v_or_b32_e32 v76, s16, v17
	v_lshlrev_b64 v[12:13], 11, v[12:13]
	v_lshl_add_u64 v[12:13], s[54:55], 0, v[12:13]
	v_ashrrev_i32_e32 v77, 31, v76
	v_lshl_add_u64 v[12:13], v[76:77], 1, v[12:13]
	s_mov_b64 s[16:17], 0x8000
	v_cvt_pk_bf16_f32 v4, v4, v5
	v_cvt_pk_bf16_f32 v5, v6, v7
	v_lshl_add_u64 v[6:7], v[12:13], 0, s[16:17]
	s_mov_b32 s16, 0x8000
	global_store_dwordx2 v[12:13], v[4:5], off offset:96
	v_cvt_pk_bf16_f32 v4, v20, v21
	v_add_co_u32_e32 v20, vcc, s16, v12
	v_cvt_pk_bf16_f32 v5, v22, v23
	s_nop 0
	v_addc_co_u32_e32 v21, vcc, 0, v13, vcc
	global_store_dwordx2 v[20:21], v[4:5], off
	v_cvt_pk_bf16_f32 v4, v48, v49
	v_cvt_pk_bf16_f32 v5, v50, v51
	global_store_dwordx2 v[6:7], v[4:5], off offset:32
	v_cvt_pk_bf16_f32 v4, v64, v65
	v_cvt_pk_bf16_f32 v5, v66, v67
	global_store_dwordx2 v[6:7], v[4:5], off offset:64
	v_cvt_pk_bf16_f32 v4, v8, v9
	v_cvt_pk_bf16_f32 v5, v10, v11
	s_mov_b64 s[16:17], 0x10000
	global_store_dwordx2 v[6:7], v[4:5], off offset:96
	v_lshl_add_u64 v[6:7], v[12:13], 0, s[16:17]
	s_mov_b32 s16, 0x10000
	v_add_co_u32_e32 v8, vcc, s16, v12
	v_cvt_pk_bf16_f32 v4, v24, v25
	v_cvt_pk_bf16_f32 v5, v26, v27
	v_addc_co_u32_e32 v9, vcc, 0, v13, vcc
	global_store_dwordx2 v[8:9], v[4:5], off
	v_cvt_pk_bf16_f32 v4, v68, v69
	v_cvt_pk_bf16_f32 v5, v70, v71
	global_store_dwordx2 v[6:7], v[4:5], off offset:32
	v_cvt_pk_bf16_f32 v4, v72, v73
	v_cvt_pk_bf16_f32 v5, v74, v75
	global_store_dwordx2 v[6:7], v[4:5], off offset:64
	v_cvt_pk_bf16_f32 v4, v28, v29
	v_cvt_pk_bf16_f32 v5, v30, v31
	s_mov_b64 s[16:17], 0x18000
	global_store_dwordx2 v[6:7], v[4:5], off offset:96
	v_lshl_add_u64 v[6:7], v[12:13], 0, s[16:17]
	s_mov_b32 s16, 0x18000
	v_add_co_u32_e32 v8, vcc, s16, v12
	v_cvt_pk_bf16_f32 v4, v36, v37
	v_cvt_pk_bf16_f32 v5, v38, v39
	v_addc_co_u32_e32 v9, vcc, 0, v13, vcc
	v_cvt_pk_bf16_f32 v52, v52, v53
	v_cvt_pk_bf16_f32 v53, v54, v55
	global_store_dwordx2 v[8:9], v[4:5], off
	v_cvt_pk_bf16_f32 v4, v40, v41
	v_cvt_pk_bf16_f32 v5, v42, v43
	global_store_dwordx2 v[12:13], v[52:53], off
	v_cvt_pk_bf16_f32 v52, v56, v57
	v_cvt_pk_bf16_f32 v53, v58, v59
	global_store_dwordx2 v[6:7], v[4:5], off offset:32
	v_cvt_pk_bf16_f32 v4, v44, v45
	v_cvt_pk_bf16_f32 v5, v46, v47
	global_store_dwordx2 v[12:13], v[52:53], off offset:32
	v_cvt_pk_bf16_f32 v52, v60, v61
	v_cvt_pk_bf16_f32 v53, v62, v63
	global_store_dwordx2 v[6:7], v[4:5], off offset:64
	v_cvt_pk_bf16_f32 v4, v32, v33
	v_cvt_pk_bf16_f32 v5, v34, v35
	s_add_i32 s6, s6, s7
	s_and_b64 vcc, exec, s[4:5]
	s_mov_b32 s16, s15
	s_mov_b32 s17, s14
	global_store_dwordx2 v[12:13], v[52:53], off offset:64
	global_store_dwordx2 v[6:7], v[4:5], off offset:96
	s_cbranch_vccnz .LBB0_400

.LBB0_711:
	v_cvt_pk_bf16_f32 v177, v2, v3
	v_cvt_pk_bf16_f32 v178, v6, v7
	v_cvt_pk_bf16_f32 v179, v10, v11
	v_cvt_pk_bf16_f32 v173, v14, v15
	v_cvt_pk_bf16_f32 v169, v18, v19
	v_cvt_pk_bf16_f32 v167, v22, v23
	v_cvt_pk_bf16_f32 v165, v26, v27
	v_cvt_pk_bf16_f32 v163, v30, v31
	v_cvt_pk_bf16_f32 v158, v34, v35
	v_cvt_pk_bf16_f32 v156, v38, v39
	v_cvt_pk_bf16_f32 v154, v42, v43
	v_cvt_pk_bf16_f32 v152, v46, v47
	v_cvt_pk_bf16_f32 v150, v50, v51
	v_cvt_pk_bf16_f32 v148, v54, v55
	v_cvt_pk_bf16_f32 v146, v58, v59
	v_cvt_pk_bf16_f32 v144, v62, v63
	v_cvt_pk_bf16_f32 v180, v0, v1
	v_cvt_pk_bf16_f32 v181, v4, v5
	v_cvt_pk_bf16_f32 v182, v8, v9
	v_cvt_pk_bf16_f32 v175, v12, v13
	v_cvt_pk_bf16_f32 v170, v16, v17
	v_cvt_pk_bf16_f32 v168, v20, v21
	v_cvt_pk_bf16_f32 v166, v24, v25
	v_cvt_pk_bf16_f32 v164, v28, v29
	v_cvt_pk_bf16_f32 v159, v32, v33
	v_cvt_pk_bf16_f32 v157, v36, v37
	v_cvt_pk_bf16_f32 v155, v40, v41
	v_cvt_pk_bf16_f32 v153, v44, v45
	v_cvt_pk_bf16_f32 v151, v48, v49
	v_cvt_pk_bf16_f32 v149, v52, v53
	v_cvt_pk_bf16_f32 v147, v56, v57
	v_cvt_pk_bf16_f32 v145, v60, v61
	v_add_u32_e32 v12, v172, v176
	v_add_u32_e32 v28, v171, v176
	ds_read_b128 v[16:19], v28 offset:49152
	ds_read_b128 v[20:23], v28 offset:51200
	ds_read_b128 v[24:27], v28 offset:53248
	ds_read_b128 v[28:31], v28 offset:55296
	ds_read_b128 v[0:3], v12 offset:16384
	ds_read_b128 v[4:7], v12 offset:18432
	ds_read_b128 v[8:11], v12 offset:20480
	ds_read_b128 v[12:15], v12 offset:22528
	s_setprio 1
	s_waitcnt lgkmcnt(3)
	v_mfma_f32_16x16x32_bf16 v[32:35], v[16:19], v[0:3], v[64:67]
	v_mfma_f32_16x16x32_bf16 v[36:39], v[20:23], v[0:3], v[68:71]
	v_mfma_f32_16x16x32_bf16 v[40:43], v[24:27], v[0:3], v[72:75]
	v_mfma_f32_16x16x32_bf16 v[0:3], v[28:31], v[0:3], v[76:79]
	s_waitcnt lgkmcnt(2)
	v_mfma_f32_16x16x32_bf16 v[44:47], v[16:19], v[4:7], v[80:83]
	v_mfma_f32_16x16x32_bf16 v[64:67], v[20:23], v[4:7], v[84:87]
	v_mfma_f32_16x16x32_bf16 v[68:71], v[24:27], v[4:7], v[88:91]
	v_mfma_f32_16x16x32_bf16 v[4:7], v[28:31], v[4:7], v[92:95]
	s_waitcnt lgkmcnt(1)
	v_mfma_f32_16x16x32_bf16 v[72:75], v[16:19], v[8:11], v[96:99]
	v_mfma_f32_16x16x32_bf16 v[76:79], v[20:23], v[8:11], v[100:103]
	v_mfma_f32_16x16x32_bf16 v[80:83], v[24:27], v[8:11], v[104:107]
	v_mfma_f32_16x16x32_bf16 v[8:11], v[28:31], v[8:11], v[108:111]
	s_waitcnt lgkmcnt(0)
	v_mfma_f32_16x16x32_bf16 v[84:87], v[16:19], v[12:15], v[112:115]
	v_mfma_f32_16x16x32_bf16 v[88:91], v[20:23], v[12:15], v[116:119]
	v_mfma_f32_16x16x32_bf16 v[92:95], v[24:27], v[12:15], v[120:123]
	v_mfma_f32_16x16x32_bf16 v[96:99], v[28:31], v[12:15], v[124:127]
	s_setprio 0
	v_add_u32_e32 v20, v172, v174
	ds_read_b128 v[12:15], v20 offset:16384
	ds_read_b128 v[16:19], v20 offset:18432
	ds_read_b128 v[100:103], v20 offset:20480
	ds_read_b128 v[104:107], v20 offset:22528
	v_add_u32_e32 v20, v171, v174
	ds_read_b128 v[108:111], v20 offset:49152
	ds_read_b128 v[112:115], v20 offset:51200
	ds_read_b128 v[116:119], v20 offset:53248
	ds_read_b128 v[120:123], v20 offset:55296
	s_setprio 1
	s_waitcnt lgkmcnt(0)
	v_mfma_f32_16x16x32_bf16 v[60:63], v[108:111], v[12:15], v[32:35]
	v_mfma_f32_16x16x32_bf16 v[56:59], v[112:115], v[12:15], v[36:39]
	v_mfma_f32_16x16x32_bf16 v[52:55], v[116:119], v[12:15], v[40:43]
	v_mfma_f32_16x16x32_bf16 v[48:51], v[120:123], v[12:15], v[0:3]
	v_mfma_f32_16x16x32_bf16 v[44:47], v[108:111], v[16:19], v[44:47]
	v_mfma_f32_16x16x32_bf16 v[40:43], v[112:115], v[16:19], v[64:67]
	v_mfma_f32_16x16x32_bf16 v[36:39], v[116:119], v[16:19], v[68:71]
	v_mfma_f32_16x16x32_bf16 v[32:35], v[120:123], v[16:19], v[4:7]
	v_mfma_f32_16x16x32_bf16 v[28:31], v[108:111], v[100:103], v[72:75]
	v_mfma_f32_16x16x32_bf16 v[24:27], v[112:115], v[100:103], v[76:79]
	v_mfma_f32_16x16x32_bf16 v[20:23], v[116:119], v[100:103], v[80:83]
	v_mfma_f32_16x16x32_bf16 v[16:19], v[120:123], v[100:103], v[8:11]
	v_mfma_f32_16x16x32_bf16 v[12:15], v[108:111], v[104:107], v[84:87]
	v_mfma_f32_16x16x32_bf16 v[8:11], v[112:115], v[104:107], v[88:91]
	v_mfma_f32_16x16x32_bf16 v[4:7], v[116:119], v[104:107], v[92:95]
	v_mfma_f32_16x16x32_bf16 v[0:3], v[120:123], v[104:107], v[96:99]
	s_setprio 0
	v_add_u32_e32 v82, s22, v161
	v_ashrrev_i32_e32 v83, 31, v82
	v_readlane_b32 s2, v242, 52
	v_or_b32_e32 v86, s23, v162
	v_lshlrev_b64 v[64:65], 13, v[82:83]
	v_readlane_b32 s3, v242, 53
	v_ashrrev_i32_e32 v87, 31, v86
	v_lshlrev_b64 v[76:77], 1, v[86:87]
	v_lshl_add_u64 v[64:65], s[2:3], 0, v[64:65]
	v_lshl_add_u64 v[88:89], v[64:65], 0, s[12:13]
	v_lshl_add_u64 v[94:95], v[64:65], 0, v[76:77]
	v_lshl_add_u64 v[64:65], v[88:89], 0, v[76:77]
	global_load_dwordx2 v[96:97], v[94:95], off
	global_load_dwordx2 v[98:99], v[64:65], off
	v_lshlrev_b64 v[64:65], 2, v[86:87]
	v_lshl_add_u64 v[72:73], s[46:47], 0, v[64:65]
	v_lshl_add_u64 v[78:79], s[0:1], 0, v[64:65]
	global_load_dwordx4 v[68:71], v[72:73], off
	global_load_dwordx4 v[64:67], v[78:79], off
	v_lshlrev_b64 v[80:81], 12, v[82:83]
	v_lshlrev_b32_e32 v90, 16, v180
	v_and_b32_e32 v91, 0xffff0000, v180
	v_lshlrev_b32_e32 v92, 16, v177
	v_and_b32_e32 v93, 0xffff0000, v177
	v_or_b32_e32 v74, 16, v86
	v_readlane_b32 s16, v242, 50
	v_ashrrev_i32_e32 v75, 31, v74
	v_readlane_b32 s17, v242, 51
	s_andn2_b64 vcc, exec, s[14:15]
	s_waitcnt vmcnt(0)
	v_lshlrev_b32_e32 v83, 16, v96
	v_and_b32_e32 v87, 0xffff0000, v96
	v_lshlrev_b32_e32 v106, 16, v98
	v_and_b32_e32 v98, 0xffff0000, v98
	v_lshlrev_b32_e32 v107, 16, v99
	v_and_b32_e32 v99, 0xffff0000, v99
	v_lshlrev_b32_e32 v96, 16, v97
	v_and_b32_e32 v97, 0xffff0000, v97
	v_add_f32_e32 v68, v68, v83
	v_add_f32_e32 v69, v69, v87
	v_add_f32_e32 v64, v64, v106
	v_add_f32_e32 v65, v65, v98
	v_add_f32_e32 v66, v66, v107
	v_add_f32_e32 v67, v67, v99
	v_add_f32_e32 v70, v70, v96
	v_add_f32_e32 v71, v71, v97
	v_mul_f32_e32 v68, 0xbfb8aa3b, v68
	v_mul_f32_e32 v69, 0xbfb8aa3b, v69
	v_mul_f32_e32 v64, 0xbfb8aa3b, v64
	v_mul_f32_e32 v65, 0xbfb8aa3b, v65
	v_mul_f32_e32 v66, 0xbfb8aa3b, v66
	v_mul_f32_e32 v67, 0xbfb8aa3b, v67
	v_mul_f32_e32 v70, 0xbfb8aa3b, v70
	v_mul_f32_e32 v71, 0xbfb8aa3b, v71
	v_exp_f32_e32 v68, v68
	v_exp_f32_e32 v69, v69
	v_exp_f32_e32 v83, v64
	v_exp_f32_e32 v87, v65
	v_exp_f32_e32 v66, v66
	v_exp_f32_e32 v67, v67
	v_exp_f32_e32 v70, v70
	v_exp_f32_e32 v71, v71
	v_add_f32_e32 v64, 1.0, v68
	v_add_f32_e32 v65, 1.0, v69
	v_add_f32_e32 v68, 1.0, v83
	v_add_f32_e32 v69, 1.0, v87
	v_add_f32_e32 v83, 1.0, v66
	v_add_f32_e32 v87, 1.0, v67
	v_add_f32_e32 v70, 1.0, v70
	v_add_f32_e32 v71, 1.0, v71
	v_rcp_f32_e32 v66, v68
	v_rcp_f32_e32 v67, v69
	v_rcp_f32_e32 v68, v83
	v_rcp_f32_e32 v69, v87
	v_rcp_f32_e32 v64, v64
	v_rcp_f32_e32 v65, v65
	v_rcp_f32_e32 v70, v70
	v_rcp_f32_e32 v71, v71
	v_pk_mul_f32 v[66:67], v[66:67], v[90:91]
	v_pk_mul_f32 v[68:69], v[68:69], v[92:93]
	v_lshl_add_u64 v[84:85], s[16:17], 0, v[80:81]
	v_lshlrev_b64 v[80:81], 1, v[74:75]
	v_pk_fma_f32 v[60:61], v[60:61], v[64:65], v[66:67]
	v_pk_fma_f32 v[62:63], v[62:63], v[70:71], v[68:69]
	v_lshl_add_u64 v[84:85], v[84:85], 0, v[76:77]
	v_lshl_add_u64 v[100:101], v[88:89], 0, v[80:81]
	v_cvt_pk_bf16_f32 v60, v60, v61
	v_cvt_pk_bf16_f32 v61, v62, v63
	global_load_dwordx2 v[102:103], v[94:95], off offset:32
	global_load_dwordx2 v[104:105], v[94:95], off offset:64
	s_nop 0
	global_load_dwordx2 v[94:95], v[94:95], off offset:96
	s_nop 0
	global_load_dwordx2 v[100:101], v[100:101], off
	v_lshl_add_u64 v[74:75], v[74:75], 2, s[0:1]
	global_store_dwordx2 v[84:85], v[60:61], off
	global_load_dwordx4 v[64:67], v[72:73], off offset:64
	global_load_dwordx4 v[68:71], v[74:75], off
	v_lshlrev_b32_e32 v90, 16, v181
	v_and_b32_e32 v91, 0xffff0000, v181
	v_lshlrev_b32_e32 v92, 16, v178
	v_and_b32_e32 v93, 0xffff0000, v178
	v_or_b32_e32 v60, 32, v86
	v_ashrrev_i32_e32 v61, 31, v60
	v_lshlrev_b64 v[62:63], 1, v[60:61]
	v_lshl_add_u64 v[96:97], v[88:89], 0, v[62:63]
	global_load_dwordx2 v[96:97], v[96:97], off
	v_lshl_add_u64 v[60:61], v[60:61], 2, s[0:1]
	s_waitcnt vmcnt(7)
	v_lshlrev_b32_e32 v83, 16, v102
	v_and_b32_e32 v87, 0xffff0000, v102
	v_lshlrev_b32_e32 v98, 16, v103
	v_and_b32_e32 v99, 0xffff0000, v103
	s_waitcnt vmcnt(4)
	v_lshlrev_b32_e32 v102, 16, v100
	v_and_b32_e32 v100, 0xffff0000, v100
	v_lshlrev_b32_e32 v103, 16, v101
	v_and_b32_e32 v101, 0xffff0000, v101
	s_waitcnt vmcnt(1)
	v_add_f32_e32 v68, v68, v102
	v_add_f32_e32 v69, v69, v100
	v_add_f32_e32 v70, v70, v103
	v_add_f32_e32 v71, v71, v101
	v_add_f32_e32 v64, v64, v83
	v_add_f32_e32 v65, v65, v87
	v_add_f32_e32 v66, v66, v98
	v_add_f32_e32 v67, v67, v99
	v_mul_f32_e32 v68, 0xbfb8aa3b, v68
	v_mul_f32_e32 v69, 0xbfb8aa3b, v69
	v_mul_f32_e32 v70, 0xbfb8aa3b, v70
	v_mul_f32_e32 v71, 0xbfb8aa3b, v71
	v_mul_f32_e32 v64, 0xbfb8aa3b, v64
	v_mul_f32_e32 v65, 0xbfb8aa3b, v65
	v_mul_f32_e32 v66, 0xbfb8aa3b, v66
	v_mul_f32_e32 v67, 0xbfb8aa3b, v67
	v_exp_f32_e32 v68, v68
	v_exp_f32_e32 v69, v69
	v_exp_f32_e32 v70, v70
	v_exp_f32_e32 v71, v71
	v_exp_f32_e32 v64, v64
	v_exp_f32_e32 v65, v65
	v_exp_f32_e32 v66, v66
	v_exp_f32_e32 v67, v67
	v_add_f32_e32 v68, 1.0, v68
	v_add_f32_e32 v69, 1.0, v69
	v_add_f32_e32 v70, 1.0, v70
	v_add_f32_e32 v71, 1.0, v71
	v_add_f32_e32 v64, 1.0, v64
	v_add_f32_e32 v65, 1.0, v65
	v_add_f32_e32 v83, 1.0, v66
	v_add_f32_e32 v87, 1.0, v67
	v_rcp_f32_e32 v66, v68
	v_rcp_f32_e32 v67, v69
	v_rcp_f32_e32 v68, v70
	v_rcp_f32_e32 v69, v71
	v_rcp_f32_e32 v64, v64
	v_rcp_f32_e32 v65, v65
	v_rcp_f32_e32 v70, v83
	v_rcp_f32_e32 v71, v87
	v_pk_mul_f32 v[66:67], v[66:67], v[90:91]
	v_pk_mul_f32 v[68:69], v[68:69], v[92:93]
	v_pk_fma_f32 v[56:57], v[56:57], v[64:65], v[66:67]
	v_pk_fma_f32 v[58:59], v[58:59], v[70:71], v[68:69]
	v_cvt_pk_bf16_f32 v56, v56, v57
	v_cvt_pk_bf16_f32 v57, v58, v59
	global_store_dwordx2 v[84:85], v[56:57], off offset:32
	global_load_dwordx4 v[64:67], v[72:73], off offset:128
	global_load_dwordx4 v[68:71], v[60:61], off
	v_or_b32_e32 v56, 48, v86
	v_ashrrev_i32_e32 v57, 31, v56
	v_lshlrev_b64 v[58:59], 1, v[56:57]
	s_waitcnt vmcnt(3)
	v_lshlrev_b32_e32 v99, 16, v96
	v_and_b32_e32 v96, 0xffff0000, v96
	v_lshlrev_b32_e32 v100, 16, v97
	v_and_b32_e32 v97, 0xffff0000, v97
	v_lshl_add_u64 v[86:87], v[88:89], 0, v[58:59]
	v_lshlrev_b32_e32 v83, 16, v104
	v_and_b32_e32 v88, 0xffff0000, v104
	v_lshlrev_b32_e32 v89, 16, v105
	v_and_b32_e32 v98, 0xffff0000, v105
	v_lshlrev_b32_e32 v90, 16, v182
	v_and_b32_e32 v91, 0xffff0000, v182
	v_lshlrev_b32_e32 v92, 16, v179
	v_and_b32_e32 v93, 0xffff0000, v179
	global_load_dwordx2 v[86:87], v[86:87], off
	v_lshl_add_u64 v[56:57], v[56:57], 2, s[0:1]
	s_waitcnt vmcnt(2)
	v_add_f32_e32 v64, v64, v83
	s_waitcnt vmcnt(1)
	v_add_f32_e32 v68, v68, v99
	v_add_f32_e32 v69, v69, v96
	v_add_f32_e32 v70, v70, v100
	v_add_f32_e32 v71, v71, v97
	v_add_f32_e32 v65, v65, v88
	v_add_f32_e32 v66, v66, v89
	v_add_f32_e32 v67, v67, v98
	v_mul_f32_e32 v68, 0xbfb8aa3b, v68
	v_mul_f32_e32 v69, 0xbfb8aa3b, v69
	v_mul_f32_e32 v70, 0xbfb8aa3b, v70
	v_mul_f32_e32 v71, 0xbfb8aa3b, v71
	v_mul_f32_e32 v64, 0xbfb8aa3b, v64
	v_mul_f32_e32 v65, 0xbfb8aa3b, v65
	v_mul_f32_e32 v66, 0xbfb8aa3b, v66
	v_mul_f32_e32 v67, 0xbfb8aa3b, v67
	v_exp_f32_e32 v68, v68
	v_exp_f32_e32 v69, v69
	v_exp_f32_e32 v70, v70
	v_exp_f32_e32 v71, v71
	v_exp_f32_e32 v64, v64
	v_exp_f32_e32 v65, v65
	v_exp_f32_e32 v66, v66
	v_exp_f32_e32 v67, v67
	v_add_f32_e32 v68, 1.0, v68
	v_add_f32_e32 v69, 1.0, v69
	v_add_f32_e32 v70, 1.0, v70
	v_add_f32_e32 v71, 1.0, v71
	v_add_f32_e32 v64, 1.0, v64
	v_add_f32_e32 v65, 1.0, v65
	v_add_f32_e32 v83, 1.0, v66
	v_add_f32_e32 v88, 1.0, v67
	v_rcp_f32_e32 v66, v68
	v_rcp_f32_e32 v67, v69
	v_rcp_f32_e32 v68, v70
	v_rcp_f32_e32 v69, v71
	v_rcp_f32_e32 v64, v64
	v_rcp_f32_e32 v65, v65
	v_rcp_f32_e32 v70, v83
	v_rcp_f32_e32 v71, v88
	v_pk_mul_f32 v[66:67], v[66:67], v[90:91]
	v_pk_mul_f32 v[68:69], v[68:69], v[92:93]
	v_pk_fma_f32 v[52:53], v[52:53], v[64:65], v[66:67]
	v_pk_fma_f32 v[54:55], v[54:55], v[70:71], v[68:69]
	v_cvt_pk_bf16_f32 v52, v52, v53
	v_cvt_pk_bf16_f32 v53, v54, v55
	global_store_dwordx2 v[84:85], v[52:53], off offset:64
	global_load_dwordx4 v[52:55], v[72:73], off offset:192
	s_nop 0
	global_load_dwordx4 v[88:91], v[56:57], off
	v_lshlrev_b32_e32 v83, 16, v94
	s_waitcnt vmcnt(3)
	v_lshlrev_b32_e32 v99, 16, v86
	v_and_b32_e32 v100, 0xffff0000, v86
	v_lshlrev_b32_e32 v101, 16, v87
	v_and_b32_e32 v102, 0xffff0000, v87
	v_and_b32_e32 v94, 0xffff0000, v94
	v_lshlrev_b32_e32 v98, 16, v95
	v_and_b32_e32 v95, 0xffff0000, v95
	v_or_b32_e32 v96, 16, v82
	v_ashrrev_i32_e32 v97, 31, v96
	v_lshlrev_b32_e32 v64, 16, v175
	v_and_b32_e32 v65, 0xffff0000, v175
	v_lshlrev_b32_e32 v92, 16, v173
	v_and_b32_e32 v93, 0xffff0000, v173
	v_lshlrev_b64 v[66:67], 13, v[96:97]
	v_lshl_add_u64 v[68:69], s[2:3], 0, v[66:67]
	v_lshl_add_u64 v[66:67], v[68:69], 0, s[12:13]
	v_lshl_add_u64 v[68:69], v[68:69], 0, v[76:77]
	v_lshl_add_u64 v[70:71], v[66:67], 0, v[76:77]
	global_load_dwordx2 v[86:87], v[68:69], off
	s_nop 0
	global_load_dwordx2 v[70:71], v[70:71], off
	s_waitcnt vmcnt(3)
	v_add_f32_e32 v52, v52, v83
	s_waitcnt vmcnt(2)
	v_add_f32_e32 v83, v88, v99
	v_add_f32_e32 v88, v89, v100
	v_add_f32_e32 v89, v90, v101
	v_add_f32_e32 v90, v91, v102
	v_add_f32_e32 v53, v53, v94
	v_add_f32_e32 v54, v54, v98
	v_add_f32_e32 v55, v55, v95
	v_mul_f32_e32 v83, 0xbfb8aa3b, v83
	v_mul_f32_e32 v88, 0xbfb8aa3b, v88
	v_mul_f32_e32 v89, 0xbfb8aa3b, v89
	v_mul_f32_e32 v90, 0xbfb8aa3b, v90
	v_mul_f32_e32 v52, 0xbfb8aa3b, v52
	v_mul_f32_e32 v53, 0xbfb8aa3b, v53
	v_mul_f32_e32 v54, 0xbfb8aa3b, v54
	v_mul_f32_e32 v55, 0xbfb8aa3b, v55
	v_exp_f32_e32 v83, v83
	v_exp_f32_e32 v88, v88
	v_exp_f32_e32 v89, v89
	v_exp_f32_e32 v90, v90
	v_exp_f32_e32 v52, v52
	v_exp_f32_e32 v53, v53
	v_exp_f32_e32 v54, v54
	v_exp_f32_e32 v55, v55
	v_add_f32_e32 v83, 1.0, v83
	v_add_f32_e32 v88, 1.0, v88
	v_add_f32_e32 v89, 1.0, v89
	v_add_f32_e32 v90, 1.0, v90
	v_add_f32_e32 v52, 1.0, v52
	v_add_f32_e32 v53, 1.0, v53
	v_add_f32_e32 v91, 1.0, v54
	v_add_f32_e32 v94, 1.0, v55
	v_rcp_f32_e32 v54, v83
	v_rcp_f32_e32 v55, v88
	v_rcp_f32_e32 v88, v89
	v_rcp_f32_e32 v89, v90
	v_rcp_f32_e32 v52, v52
	v_rcp_f32_e32 v53, v53
	v_rcp_f32_e32 v90, v91
	v_rcp_f32_e32 v91, v94
	v_pk_mul_f32 v[54:55], v[54:55], v[64:65]
	v_pk_mul_f32 v[64:65], v[88:89], v[92:93]
	v_pk_fma_f32 v[48:49], v[48:49], v[52:53], v[54:55]
	v_pk_fma_f32 v[50:51], v[50:51], v[90:91], v[64:65]
	v_cvt_pk_bf16_f32 v48, v48, v49
	v_cvt_pk_bf16_f32 v49, v50, v51
	global_store_dwordx2 v[84:85], v[48:49], off offset:96
	global_load_dwordx4 v[48:51], v[72:73], off
	s_nop 0
	global_load_dwordx4 v[52:55], v[78:79], off
	v_lshl_add_u64 v[90:91], v[66:67], 0, v[80:81]
	v_lshl_add_u64 v[92:93], v[66:67], 0, v[62:63]
	v_lshlrev_b64 v[64:65], 12, v[96:97]
	v_lshl_add_u64 v[94:95], v[66:67], 0, v[58:59]
	global_load_dwordx2 v[96:97], v[68:69], off offset:32
	global_load_dwordx2 v[98:99], v[68:69], off offset:64
	global_load_dwordx2 v[66:67], v[68:69], off offset:96
	s_waitcnt vmcnt(7)
	v_lshlrev_b32_e32 v83, 16, v86
	v_and_b32_e32 v100, 0xffff0000, v86
	v_lshlrev_b32_e32 v101, 16, v87
	v_and_b32_e32 v102, 0xffff0000, v87
	global_load_dwordx2 v[86:87], v[90:91], off
	s_nop 0
	global_load_dwordx2 v[90:91], v[92:93], off
	global_load_dwordx2 v[68:69], v[94:95], off
	s_waitcnt vmcnt(9)
	v_lshlrev_b32_e32 v92, 16, v70
	v_and_b32_e32 v70, 0xffff0000, v70
	v_lshlrev_b32_e32 v93, 16, v71
	v_and_b32_e32 v71, 0xffff0000, v71
	v_lshlrev_b32_e32 v84, 16, v170
	v_and_b32_e32 v85, 0xffff0000, v170
	v_lshlrev_b32_e32 v88, 16, v169
	v_and_b32_e32 v89, 0xffff0000, v169
	v_lshl_add_u64 v[64:65], s[16:17], 0, v[64:65]
	v_lshl_add_u64 v[64:65], v[64:65], 0, v[76:77]
	s_waitcnt vmcnt(7)
	v_add_f32_e32 v48, v48, v83
	s_waitcnt vmcnt(6)
	v_add_f32_e32 v52, v52, v92
	v_add_f32_e32 v53, v53, v70
	v_add_f32_e32 v54, v54, v93
	v_add_f32_e32 v55, v55, v71
	v_add_f32_e32 v49, v49, v100
	v_add_f32_e32 v50, v50, v101
	v_add_f32_e32 v51, v51, v102
	v_mul_f32_e32 v52, 0xbfb8aa3b, v52
	v_mul_f32_e32 v53, 0xbfb8aa3b, v53
	v_mul_f32_e32 v54, 0xbfb8aa3b, v54
	v_mul_f32_e32 v55, 0xbfb8aa3b, v55
	v_mul_f32_e32 v48, 0xbfb8aa3b, v48
	v_mul_f32_e32 v49, 0xbfb8aa3b, v49
	v_mul_f32_e32 v50, 0xbfb8aa3b, v50
	v_mul_f32_e32 v51, 0xbfb8aa3b, v51
	v_exp_f32_e32 v52, v52
	v_exp_f32_e32 v53, v53
	v_exp_f32_e32 v54, v54
	v_exp_f32_e32 v55, v55
	v_exp_f32_e32 v48, v48
	v_exp_f32_e32 v49, v49
	v_exp_f32_e32 v50, v50
	v_exp_f32_e32 v51, v51
	v_add_f32_e32 v52, 1.0, v52
	v_add_f32_e32 v53, 1.0, v53
	v_add_f32_e32 v54, 1.0, v54
	v_add_f32_e32 v55, 1.0, v55
	v_add_f32_e32 v48, 1.0, v48
	v_add_f32_e32 v49, 1.0, v49
	v_add_f32_e32 v70, 1.0, v50
	v_add_f32_e32 v71, 1.0, v51
	v_rcp_f32_e32 v50, v52
	v_rcp_f32_e32 v51, v53
	v_rcp_f32_e32 v52, v54
	v_rcp_f32_e32 v53, v55
	v_rcp_f32_e32 v48, v48
	v_rcp_f32_e32 v49, v49
	v_rcp_f32_e32 v54, v70
	v_rcp_f32_e32 v55, v71
	v_pk_mul_f32 v[50:51], v[50:51], v[84:85]
	v_pk_mul_f32 v[52:53], v[52:53], v[88:89]
	v_pk_fma_f32 v[44:45], v[44:45], v[48:49], v[50:51]
	v_pk_fma_f32 v[46:47], v[46:47], v[54:55], v[52:53]
	v_cvt_pk_bf16_f32 v44, v44, v45
	v_cvt_pk_bf16_f32 v45, v46, v47
	global_store_dwordx2 v[64:65], v[44:45], off
	global_load_dwordx4 v[44:47], v[72:73], off offset:64
	s_nop 0
	global_load_dwordx4 v[48:51], v[74:75], off
	s_waitcnt vmcnt(5)
	v_lshlrev_b32_e32 v85, 16, v86
	v_and_b32_e32 v86, 0xffff0000, v86
	v_lshlrev_b32_e32 v88, 16, v87
	v_and_b32_e32 v87, 0xffff0000, v87
	v_lshlrev_b32_e32 v70, 16, v96
	v_and_b32_e32 v71, 0xffff0000, v96
	v_lshlrev_b32_e32 v83, 16, v97
	v_and_b32_e32 v84, 0xffff0000, v97
	v_lshlrev_b32_e32 v52, 16, v168
	v_and_b32_e32 v53, 0xffff0000, v168
	v_lshlrev_b32_e32 v54, 16, v167
	v_and_b32_e32 v55, 0xffff0000, v167
	s_waitcnt vmcnt(1)
	v_add_f32_e32 v44, v44, v70
	s_waitcnt vmcnt(0)
	v_add_f32_e32 v48, v48, v85
	v_add_f32_e32 v49, v49, v86
	v_add_f32_e32 v50, v50, v88
	v_add_f32_e32 v51, v51, v87
	v_add_f32_e32 v45, v45, v71
	v_add_f32_e32 v46, v46, v83
	v_add_f32_e32 v47, v47, v84
	v_mul_f32_e32 v48, 0xbfb8aa3b, v48
	v_mul_f32_e32 v49, 0xbfb8aa3b, v49
	v_mul_f32_e32 v50, 0xbfb8aa3b, v50
	v_mul_f32_e32 v51, 0xbfb8aa3b, v51
	v_mul_f32_e32 v44, 0xbfb8aa3b, v44
	v_mul_f32_e32 v45, 0xbfb8aa3b, v45
	v_mul_f32_e32 v46, 0xbfb8aa3b, v46
	v_mul_f32_e32 v47, 0xbfb8aa3b, v47
	v_exp_f32_e32 v48, v48
	v_exp_f32_e32 v49, v49
	v_exp_f32_e32 v50, v50
	v_exp_f32_e32 v51, v51
	v_exp_f32_e32 v44, v44
	v_exp_f32_e32 v45, v45
	v_exp_f32_e32 v46, v46
	v_exp_f32_e32 v47, v47
	v_add_f32_e32 v48, 1.0, v48
	v_add_f32_e32 v49, 1.0, v49
	v_add_f32_e32 v50, 1.0, v50
	v_add_f32_e32 v51, 1.0, v51
	v_add_f32_e32 v44, 1.0, v44
	v_add_f32_e32 v45, 1.0, v45
	v_add_f32_e32 v70, 1.0, v46
	v_add_f32_e32 v71, 1.0, v47
	v_rcp_f32_e32 v46, v48
	v_rcp_f32_e32 v47, v49
	v_rcp_f32_e32 v48, v50
	v_rcp_f32_e32 v49, v51
	v_rcp_f32_e32 v44, v44
	v_rcp_f32_e32 v45, v45
	v_rcp_f32_e32 v50, v70
	v_rcp_f32_e32 v51, v71
	v_pk_mul_f32 v[46:47], v[46:47], v[52:53]
	v_pk_mul_f32 v[48:49], v[48:49], v[54:55]
	v_pk_fma_f32 v[40:41], v[40:41], v[44:45], v[46:47]
	v_pk_fma_f32 v[42:43], v[42:43], v[50:51], v[48:49]
	v_cvt_pk_bf16_f32 v40, v40, v41
	v_cvt_pk_bf16_f32 v41, v42, v43
	global_store_dwordx2 v[64:65], v[40:41], off offset:32
	global_load_dwordx4 v[40:43], v[72:73], off offset:128
	s_nop 0
	global_load_dwordx4 v[44:47], v[60:61], off
	v_lshlrev_b32_e32 v70, 16, v90
	v_and_b32_e32 v71, 0xffff0000, v90
	v_lshlrev_b32_e32 v83, 16, v91
	v_and_b32_e32 v84, 0xffff0000, v91
	v_lshlrev_b32_e32 v52, 16, v98
	v_and_b32_e32 v53, 0xffff0000, v98
	v_lshlrev_b32_e32 v54, 16, v99
	v_and_b32_e32 v55, 0xffff0000, v99
	v_lshlrev_b32_e32 v48, 16, v166
	v_and_b32_e32 v49, 0xffff0000, v166
	v_lshlrev_b32_e32 v50, 16, v165
	v_and_b32_e32 v51, 0xffff0000, v165
	v_lshlrev_b32_e32 v85, 16, v68
	v_and_b32_e32 v68, 0xffff0000, v68
	v_lshlrev_b32_e32 v86, 16, v69
	v_and_b32_e32 v69, 0xffff0000, v69
	s_waitcnt vmcnt(1)
	v_add_f32_e32 v40, v40, v52
	s_waitcnt vmcnt(0)
	v_add_f32_e32 v44, v44, v70
	v_add_f32_e32 v45, v45, v71
	v_add_f32_e32 v46, v46, v83
	v_add_f32_e32 v47, v47, v84
	v_add_f32_e32 v41, v41, v53
	v_add_f32_e32 v42, v42, v54
	v_add_f32_e32 v43, v43, v55
	v_mul_f32_e32 v44, 0xbfb8aa3b, v44
	v_mul_f32_e32 v45, 0xbfb8aa3b, v45
	v_mul_f32_e32 v46, 0xbfb8aa3b, v46
	v_mul_f32_e32 v47, 0xbfb8aa3b, v47
	v_mul_f32_e32 v40, 0xbfb8aa3b, v40
	v_mul_f32_e32 v41, 0xbfb8aa3b, v41
	v_mul_f32_e32 v42, 0xbfb8aa3b, v42
	v_mul_f32_e32 v43, 0xbfb8aa3b, v43
	v_exp_f32_e32 v44, v44
	v_exp_f32_e32 v45, v45
	v_exp_f32_e32 v46, v46
	v_exp_f32_e32 v47, v47
	v_exp_f32_e32 v40, v40
	v_exp_f32_e32 v41, v41
	v_exp_f32_e32 v42, v42
	v_exp_f32_e32 v43, v43
	v_add_f32_e32 v44, 1.0, v44
	v_add_f32_e32 v45, 1.0, v45
	v_add_f32_e32 v46, 1.0, v46
	v_add_f32_e32 v47, 1.0, v47
	v_add_f32_e32 v40, 1.0, v40
	v_add_f32_e32 v41, 1.0, v41
	v_add_f32_e32 v52, 1.0, v42
	v_add_f32_e32 v53, 1.0, v43
	v_rcp_f32_e32 v42, v44
	v_rcp_f32_e32 v43, v45
	v_rcp_f32_e32 v44, v46
	v_rcp_f32_e32 v45, v47
	v_rcp_f32_e32 v40, v40
	v_rcp_f32_e32 v41, v41
	v_rcp_f32_e32 v46, v52
	v_rcp_f32_e32 v47, v53
	v_pk_mul_f32 v[42:43], v[42:43], v[48:49]
	v_pk_mul_f32 v[44:45], v[44:45], v[50:51]
	v_pk_fma_f32 v[36:37], v[36:37], v[40:41], v[42:43]
	v_pk_fma_f32 v[38:39], v[38:39], v[46:47], v[44:45]
	v_cvt_pk_bf16_f32 v36, v36, v37
	v_cvt_pk_bf16_f32 v37, v38, v39
	global_store_dwordx2 v[64:65], v[36:37], off offset:64
	global_load_dwordx4 v[36:39], v[72:73], off offset:192
	s_nop 0
	global_load_dwordx4 v[50:53], v[56:57], off
	v_lshlrev_b32_e32 v83, 16, v66
	v_and_b32_e32 v66, 0xffff0000, v66
	v_lshlrev_b32_e32 v84, 16, v67
	v_and_b32_e32 v67, 0xffff0000, v67
	v_or_b32_e32 v70, 32, v82
	v_ashrrev_i32_e32 v71, 31, v70
	v_lshlrev_b32_e32 v40, 16, v164
	v_and_b32_e32 v41, 0xffff0000, v164
	v_lshlrev_b32_e32 v54, 16, v163
	v_and_b32_e32 v55, 0xffff0000, v163
	v_lshlrev_b64 v[42:43], 13, v[70:71]
	v_lshl_add_u64 v[44:45], s[2:3], 0, v[42:43]
	v_lshl_add_u64 v[42:43], v[44:45], 0, s[12:13]
	v_lshl_add_u64 v[44:45], v[44:45], 0, v[76:77]
	v_lshl_add_u64 v[46:47], v[42:43], 0, v[76:77]
	global_load_dwordx2 v[48:49], v[44:45], off
	s_nop 0
	global_load_dwordx2 v[46:47], v[46:47], off
	s_waitcnt vmcnt(3)
	v_add_f32_e32 v36, v36, v83
	s_waitcnt vmcnt(2)
	v_add_f32_e32 v50, v50, v85
	v_add_f32_e32 v51, v51, v68
	v_add_f32_e32 v52, v52, v86
	v_add_f32_e32 v53, v53, v69
	v_add_f32_e32 v37, v37, v66
	v_add_f32_e32 v38, v38, v84
	v_add_f32_e32 v39, v39, v67
	v_mul_f32_e32 v50, 0xbfb8aa3b, v50
	v_mul_f32_e32 v51, 0xbfb8aa3b, v51
	v_mul_f32_e32 v52, 0xbfb8aa3b, v52
	v_mul_f32_e32 v53, 0xbfb8aa3b, v53
	v_mul_f32_e32 v36, 0xbfb8aa3b, v36
	v_mul_f32_e32 v37, 0xbfb8aa3b, v37
	v_mul_f32_e32 v38, 0xbfb8aa3b, v38
	v_mul_f32_e32 v39, 0xbfb8aa3b, v39
	v_exp_f32_e32 v50, v50
	v_exp_f32_e32 v51, v51
	v_exp_f32_e32 v52, v52
	v_exp_f32_e32 v53, v53
	v_exp_f32_e32 v36, v36
	v_exp_f32_e32 v37, v37
	v_exp_f32_e32 v38, v38
	v_exp_f32_e32 v39, v39
	v_add_f32_e32 v50, 1.0, v50
	v_add_f32_e32 v51, 1.0, v51
	v_add_f32_e32 v52, 1.0, v52
	v_add_f32_e32 v53, 1.0, v53
	v_add_f32_e32 v36, 1.0, v36
	v_add_f32_e32 v37, 1.0, v37
	v_add_f32_e32 v66, 1.0, v38
	v_add_f32_e32 v67, 1.0, v39
	v_rcp_f32_e32 v38, v50
	v_rcp_f32_e32 v39, v51
	v_rcp_f32_e32 v50, v52
	v_rcp_f32_e32 v51, v53
	v_rcp_f32_e32 v36, v36
	v_rcp_f32_e32 v37, v37
	v_rcp_f32_e32 v52, v66
	v_rcp_f32_e32 v53, v67
	v_pk_mul_f32 v[38:39], v[38:39], v[40:41]
	v_pk_mul_f32 v[40:41], v[50:51], v[54:55]
	v_pk_fma_f32 v[32:33], v[32:33], v[36:37], v[38:39]
	v_pk_fma_f32 v[34:35], v[34:35], v[52:53], v[40:41]
	v_cvt_pk_bf16_f32 v32, v32, v33
	v_cvt_pk_bf16_f32 v33, v34, v35
	global_store_dwordx2 v[64:65], v[32:33], off offset:96
	global_load_dwordx4 v[32:35], v[72:73], off
	s_nop 0
	global_load_dwordx4 v[36:39], v[78:79], off
	v_lshl_add_u64 v[54:55], v[42:43], 0, v[80:81]
	v_lshl_add_u64 v[64:65], v[42:43], 0, v[62:63]
	v_lshlrev_b64 v[40:41], 12, v[70:71]
	v_lshl_add_u64 v[66:67], v[42:43], 0, v[58:59]
	global_load_dwordx2 v[68:69], v[44:45], off offset:32
	global_load_dwordx2 v[70:71], v[44:45], off offset:64
	global_load_dwordx2 v[42:43], v[44:45], off offset:96
	s_waitcnt vmcnt(7)
	v_lshlrev_b32_e32 v83, 16, v48
	v_and_b32_e32 v84, 0xffff0000, v48
	v_lshlrev_b32_e32 v85, 16, v49
	v_and_b32_e32 v86, 0xffff0000, v49
	global_load_dwordx2 v[48:49], v[54:55], off
	s_nop 0
	global_load_dwordx2 v[54:55], v[64:65], off
	global_load_dwordx2 v[44:45], v[66:67], off
	s_waitcnt vmcnt(9)
	v_lshlrev_b32_e32 v64, 16, v46
	v_and_b32_e32 v46, 0xffff0000, v46
	v_lshlrev_b32_e32 v65, 16, v47
	v_and_b32_e32 v47, 0xffff0000, v47
	v_lshlrev_b32_e32 v50, 16, v159
	v_and_b32_e32 v51, 0xffff0000, v159
	v_lshlrev_b32_e32 v52, 16, v158
	v_and_b32_e32 v53, 0xffff0000, v158
	v_lshl_add_u64 v[40:41], s[16:17], 0, v[40:41]
	v_lshl_add_u64 v[40:41], v[40:41], 0, v[76:77]
	s_waitcnt vmcnt(7)
	v_add_f32_e32 v32, v32, v83
	s_waitcnt vmcnt(6)
	v_add_f32_e32 v36, v36, v64
	v_add_f32_e32 v37, v37, v46
	v_add_f32_e32 v38, v38, v65
	v_add_f32_e32 v39, v39, v47
	v_add_f32_e32 v33, v33, v84
	v_add_f32_e32 v34, v34, v85
	v_add_f32_e32 v35, v35, v86
	v_mul_f32_e32 v36, 0xbfb8aa3b, v36
	v_mul_f32_e32 v37, 0xbfb8aa3b, v37
	v_mul_f32_e32 v38, 0xbfb8aa3b, v38
	v_mul_f32_e32 v39, 0xbfb8aa3b, v39
	v_mul_f32_e32 v32, 0xbfb8aa3b, v32
	v_mul_f32_e32 v33, 0xbfb8aa3b, v33
	v_mul_f32_e32 v34, 0xbfb8aa3b, v34
	v_mul_f32_e32 v35, 0xbfb8aa3b, v35
	v_exp_f32_e32 v36, v36
	v_exp_f32_e32 v37, v37
	v_exp_f32_e32 v38, v38
	v_exp_f32_e32 v39, v39
	v_exp_f32_e32 v32, v32
	v_exp_f32_e32 v33, v33
	v_exp_f32_e32 v34, v34
	v_exp_f32_e32 v35, v35
	v_add_f32_e32 v36, 1.0, v36
	v_add_f32_e32 v37, 1.0, v37
	v_add_f32_e32 v38, 1.0, v38
	v_add_f32_e32 v39, 1.0, v39
	v_add_f32_e32 v32, 1.0, v32
	v_add_f32_e32 v33, 1.0, v33
	v_add_f32_e32 v46, 1.0, v34
	v_add_f32_e32 v47, 1.0, v35
	v_rcp_f32_e32 v34, v36
	v_rcp_f32_e32 v35, v37
	v_rcp_f32_e32 v36, v38
	v_rcp_f32_e32 v37, v39
	v_rcp_f32_e32 v32, v32
	v_rcp_f32_e32 v33, v33
	v_rcp_f32_e32 v38, v46
	v_rcp_f32_e32 v39, v47
	v_pk_mul_f32 v[34:35], v[34:35], v[50:51]
	v_pk_mul_f32 v[36:37], v[36:37], v[52:53]
	v_pk_fma_f32 v[28:29], v[28:29], v[32:33], v[34:35]
	v_pk_fma_f32 v[30:31], v[30:31], v[38:39], v[36:37]
	v_cvt_pk_bf16_f32 v28, v28, v29
	v_cvt_pk_bf16_f32 v29, v30, v31
	global_store_dwordx2 v[40:41], v[28:29], off
	global_load_dwordx4 v[28:31], v[72:73], off offset:64
	s_nop 0
	global_load_dwordx4 v[32:35], v[74:75], off
	s_waitcnt vmcnt(5)
	v_lshlrev_b32_e32 v52, 16, v48
	v_and_b32_e32 v48, 0xffff0000, v48
	v_lshlrev_b32_e32 v53, 16, v49
	v_and_b32_e32 v49, 0xffff0000, v49
	v_lshlrev_b32_e32 v46, 16, v68
	v_and_b32_e32 v47, 0xffff0000, v68
	v_lshlrev_b32_e32 v50, 16, v69
	v_and_b32_e32 v51, 0xffff0000, v69
	v_lshlrev_b32_e32 v36, 16, v157
	v_and_b32_e32 v37, 0xffff0000, v157
	v_lshlrev_b32_e32 v38, 16, v156
	v_and_b32_e32 v39, 0xffff0000, v156
	s_waitcnt vmcnt(1)
	v_add_f32_e32 v28, v28, v46
	s_waitcnt vmcnt(0)
	v_add_f32_e32 v32, v32, v52
	v_add_f32_e32 v33, v33, v48
	v_add_f32_e32 v34, v34, v53
	v_add_f32_e32 v35, v35, v49
	v_add_f32_e32 v29, v29, v47
	v_add_f32_e32 v30, v30, v50
	v_add_f32_e32 v31, v31, v51
	v_mul_f32_e32 v32, 0xbfb8aa3b, v32
	v_mul_f32_e32 v33, 0xbfb8aa3b, v33
	v_mul_f32_e32 v34, 0xbfb8aa3b, v34
	v_mul_f32_e32 v35, 0xbfb8aa3b, v35
	v_mul_f32_e32 v28, 0xbfb8aa3b, v28
	v_mul_f32_e32 v29, 0xbfb8aa3b, v29
	v_mul_f32_e32 v30, 0xbfb8aa3b, v30
	v_mul_f32_e32 v31, 0xbfb8aa3b, v31
	v_exp_f32_e32 v32, v32
	v_exp_f32_e32 v33, v33
	v_exp_f32_e32 v34, v34
	v_exp_f32_e32 v35, v35
	v_exp_f32_e32 v28, v28
	v_exp_f32_e32 v29, v29
	v_exp_f32_e32 v30, v30
	v_exp_f32_e32 v31, v31
	v_add_f32_e32 v32, 1.0, v32
	v_add_f32_e32 v33, 1.0, v33
	v_add_f32_e32 v34, 1.0, v34
	v_add_f32_e32 v35, 1.0, v35
	v_add_f32_e32 v28, 1.0, v28
	v_add_f32_e32 v29, 1.0, v29
	v_add_f32_e32 v46, 1.0, v30
	v_add_f32_e32 v47, 1.0, v31
	v_rcp_f32_e32 v30, v32
	v_rcp_f32_e32 v31, v33
	v_rcp_f32_e32 v32, v34
	v_rcp_f32_e32 v33, v35
	v_rcp_f32_e32 v28, v28
	v_rcp_f32_e32 v29, v29
	v_rcp_f32_e32 v34, v46
	v_rcp_f32_e32 v35, v47
	v_pk_mul_f32 v[30:31], v[30:31], v[36:37]
	v_pk_mul_f32 v[32:33], v[32:33], v[38:39]
	v_pk_fma_f32 v[24:25], v[24:25], v[28:29], v[30:31]
	v_pk_fma_f32 v[26:27], v[26:27], v[34:35], v[32:33]
	v_cvt_pk_bf16_f32 v24, v24, v25
	v_cvt_pk_bf16_f32 v25, v26, v27
	global_store_dwordx2 v[40:41], v[24:25], off offset:32
	global_load_dwordx4 v[24:27], v[72:73], off offset:128
	s_nop 0
	global_load_dwordx4 v[28:31], v[60:61], off
	v_lshlrev_b32_e32 v46, 16, v54
	v_and_b32_e32 v47, 0xffff0000, v54
	v_lshlrev_b32_e32 v48, 16, v55
	v_and_b32_e32 v49, 0xffff0000, v55
	v_lshlrev_b32_e32 v36, 16, v70
	v_and_b32_e32 v37, 0xffff0000, v70
	v_lshlrev_b32_e32 v38, 16, v71
	v_and_b32_e32 v39, 0xffff0000, v71
	v_lshlrev_b32_e32 v32, 16, v155
	v_and_b32_e32 v33, 0xffff0000, v155
	v_lshlrev_b32_e32 v34, 16, v154
	v_and_b32_e32 v35, 0xffff0000, v154
	v_lshlrev_b32_e32 v50, 16, v44
	v_and_b32_e32 v44, 0xffff0000, v44
	v_lshlrev_b32_e32 v51, 16, v45
	v_and_b32_e32 v45, 0xffff0000, v45
	s_waitcnt vmcnt(1)
	v_add_f32_e32 v24, v24, v36
	s_waitcnt vmcnt(0)
	v_add_f32_e32 v28, v28, v46
	v_add_f32_e32 v29, v29, v47
	v_add_f32_e32 v30, v30, v48
	v_add_f32_e32 v31, v31, v49
	v_add_f32_e32 v25, v25, v37
	v_add_f32_e32 v26, v26, v38
	v_add_f32_e32 v27, v27, v39
	v_mul_f32_e32 v28, 0xbfb8aa3b, v28
	v_mul_f32_e32 v29, 0xbfb8aa3b, v29
	v_mul_f32_e32 v30, 0xbfb8aa3b, v30
	v_mul_f32_e32 v31, 0xbfb8aa3b, v31
	v_mul_f32_e32 v24, 0xbfb8aa3b, v24
	v_mul_f32_e32 v25, 0xbfb8aa3b, v25
	v_mul_f32_e32 v26, 0xbfb8aa3b, v26
	v_mul_f32_e32 v27, 0xbfb8aa3b, v27
	v_exp_f32_e32 v28, v28
	v_exp_f32_e32 v29, v29
	v_exp_f32_e32 v30, v30
	v_exp_f32_e32 v31, v31
	v_exp_f32_e32 v24, v24
	v_exp_f32_e32 v25, v25
	v_exp_f32_e32 v26, v26
	v_exp_f32_e32 v27, v27
	v_add_f32_e32 v28, 1.0, v28
	v_add_f32_e32 v29, 1.0, v29
	v_add_f32_e32 v30, 1.0, v30
	v_add_f32_e32 v31, 1.0, v31
	v_add_f32_e32 v24, 1.0, v24
	v_add_f32_e32 v25, 1.0, v25
	v_add_f32_e32 v36, 1.0, v26
	v_add_f32_e32 v37, 1.0, v27
	v_rcp_f32_e32 v26, v28
	v_rcp_f32_e32 v27, v29
	v_rcp_f32_e32 v28, v30
	v_rcp_f32_e32 v29, v31
	v_rcp_f32_e32 v24, v24
	v_rcp_f32_e32 v25, v25
	v_rcp_f32_e32 v30, v36
	v_rcp_f32_e32 v31, v37
	v_pk_mul_f32 v[26:27], v[26:27], v[32:33]
	v_pk_mul_f32 v[28:29], v[28:29], v[34:35]
	v_pk_fma_f32 v[20:21], v[20:21], v[24:25], v[26:27]
	v_pk_fma_f32 v[22:23], v[22:23], v[30:31], v[28:29]
	v_cvt_pk_bf16_f32 v20, v20, v21
	v_cvt_pk_bf16_f32 v21, v22, v23
	global_store_dwordx2 v[40:41], v[20:21], off offset:64
	global_load_dwordx4 v[20:23], v[72:73], off offset:192
	s_nop 0
	global_load_dwordx4 v[34:37], v[56:57], off
	v_lshlrev_b32_e32 v48, 16, v42
	v_and_b32_e32 v42, 0xffff0000, v42
	v_lshlrev_b32_e32 v49, 16, v43
	v_and_b32_e32 v43, 0xffff0000, v43
	v_or_b32_e32 v46, 48, v82
	v_ashrrev_i32_e32 v47, 31, v46
	v_lshlrev_b32_e32 v24, 16, v153
	v_and_b32_e32 v25, 0xffff0000, v153
	v_lshlrev_b32_e32 v38, 16, v152
	v_and_b32_e32 v39, 0xffff0000, v152
	v_lshlrev_b64 v[26:27], 13, v[46:47]
	v_lshl_add_u64 v[28:29], s[2:3], 0, v[26:27]
	v_lshl_add_u64 v[26:27], v[28:29], 0, s[12:13]
	v_lshl_add_u64 v[28:29], v[28:29], 0, v[76:77]
	v_lshl_add_u64 v[30:31], v[26:27], 0, v[76:77]
	global_load_dwordx2 v[32:33], v[28:29], off
	s_nop 0
	global_load_dwordx2 v[30:31], v[30:31], off
	s_waitcnt vmcnt(3)
	v_add_f32_e32 v20, v20, v48
	s_waitcnt vmcnt(2)
	v_add_f32_e32 v34, v34, v50
	v_add_f32_e32 v35, v35, v44
	v_add_f32_e32 v36, v36, v51
	v_add_f32_e32 v37, v37, v45
	v_add_f32_e32 v21, v21, v42
	v_add_f32_e32 v22, v22, v49
	v_add_f32_e32 v23, v23, v43
	v_mul_f32_e32 v34, 0xbfb8aa3b, v34
	v_mul_f32_e32 v35, 0xbfb8aa3b, v35
	v_mul_f32_e32 v36, 0xbfb8aa3b, v36
	v_mul_f32_e32 v37, 0xbfb8aa3b, v37
	v_mul_f32_e32 v20, 0xbfb8aa3b, v20
	v_mul_f32_e32 v21, 0xbfb8aa3b, v21
	v_mul_f32_e32 v22, 0xbfb8aa3b, v22
	v_mul_f32_e32 v23, 0xbfb8aa3b, v23
	v_exp_f32_e32 v34, v34
	v_exp_f32_e32 v35, v35
	v_exp_f32_e32 v36, v36
	v_exp_f32_e32 v37, v37
	v_exp_f32_e32 v20, v20
	v_exp_f32_e32 v21, v21
	v_exp_f32_e32 v22, v22
	v_exp_f32_e32 v23, v23
	v_add_f32_e32 v34, 1.0, v34
	v_add_f32_e32 v35, 1.0, v35
	v_add_f32_e32 v36, 1.0, v36
	v_add_f32_e32 v37, 1.0, v37
	v_add_f32_e32 v20, 1.0, v20
	v_add_f32_e32 v21, 1.0, v21
	v_add_f32_e32 v42, 1.0, v22
	v_add_f32_e32 v43, 1.0, v23
	v_rcp_f32_e32 v22, v34
	v_rcp_f32_e32 v23, v35
	v_rcp_f32_e32 v34, v36
	v_rcp_f32_e32 v35, v37
	v_rcp_f32_e32 v20, v20
	v_rcp_f32_e32 v21, v21
	v_rcp_f32_e32 v36, v42
	v_rcp_f32_e32 v37, v43
	v_pk_mul_f32 v[22:23], v[22:23], v[24:25]
	v_pk_mul_f32 v[24:25], v[34:35], v[38:39]
	v_pk_fma_f32 v[16:17], v[16:17], v[20:21], v[22:23]
	v_pk_fma_f32 v[18:19], v[18:19], v[36:37], v[24:25]
	v_cvt_pk_bf16_f32 v16, v16, v17
	v_cvt_pk_bf16_f32 v17, v18, v19
	global_store_dwordx2 v[40:41], v[16:17], off offset:96
	global_load_dwordx4 v[16:19], v[72:73], off
	s_nop 0
	global_load_dwordx4 v[20:23], v[78:79], off
	v_lshl_add_u64 v[38:39], v[26:27], 0, v[80:81]
	v_lshl_add_u64 v[40:41], v[26:27], 0, v[62:63]
	v_lshlrev_b64 v[24:25], 12, v[46:47]
	v_lshl_add_u64 v[42:43], v[26:27], 0, v[58:59]
	global_load_dwordx2 v[44:45], v[28:29], off offset:32
	global_load_dwordx2 v[46:47], v[28:29], off offset:64
	global_load_dwordx2 v[26:27], v[28:29], off offset:96
	s_waitcnt vmcnt(7)
	v_lshlrev_b32_e32 v48, 16, v32
	v_and_b32_e32 v49, 0xffff0000, v32
	v_lshlrev_b32_e32 v50, 16, v33
	v_and_b32_e32 v51, 0xffff0000, v33
	global_load_dwordx2 v[32:33], v[38:39], off
	s_nop 0
	global_load_dwordx2 v[38:39], v[40:41], off
	global_load_dwordx2 v[28:29], v[42:43], off
	s_waitcnt vmcnt(9)
	v_lshlrev_b32_e32 v40, 16, v30
	v_and_b32_e32 v30, 0xffff0000, v30
	v_lshlrev_b32_e32 v41, 16, v31
	v_and_b32_e32 v31, 0xffff0000, v31
	v_lshlrev_b32_e32 v34, 16, v151
	v_and_b32_e32 v35, 0xffff0000, v151
	v_lshlrev_b32_e32 v36, 16, v150
	v_and_b32_e32 v37, 0xffff0000, v150
	v_lshl_add_u64 v[24:25], s[16:17], 0, v[24:25]
	v_lshl_add_u64 v[24:25], v[24:25], 0, v[76:77]
	s_mov_b64 s[16:17], 0
	s_waitcnt vmcnt(7)
	v_add_f32_e32 v16, v16, v48
	s_waitcnt vmcnt(6)
	v_add_f32_e32 v20, v20, v40
	v_add_f32_e32 v21, v21, v30
	v_add_f32_e32 v22, v22, v41
	v_add_f32_e32 v23, v23, v31
	v_add_f32_e32 v17, v17, v49
	v_add_f32_e32 v18, v18, v50
	v_add_f32_e32 v19, v19, v51
	v_mul_f32_e32 v20, 0xbfb8aa3b, v20
	v_mul_f32_e32 v21, 0xbfb8aa3b, v21
	v_mul_f32_e32 v22, 0xbfb8aa3b, v22
	v_mul_f32_e32 v23, 0xbfb8aa3b, v23
	v_mul_f32_e32 v16, 0xbfb8aa3b, v16
	v_mul_f32_e32 v17, 0xbfb8aa3b, v17
	v_mul_f32_e32 v18, 0xbfb8aa3b, v18
	v_mul_f32_e32 v19, 0xbfb8aa3b, v19
	v_exp_f32_e32 v20, v20
	v_exp_f32_e32 v21, v21
	v_exp_f32_e32 v22, v22
	v_exp_f32_e32 v23, v23
	v_exp_f32_e32 v16, v16
	v_exp_f32_e32 v17, v17
	v_exp_f32_e32 v18, v18
	v_exp_f32_e32 v19, v19
	v_add_f32_e32 v20, 1.0, v20
	v_add_f32_e32 v21, 1.0, v21
	v_add_f32_e32 v22, 1.0, v22
	v_add_f32_e32 v23, 1.0, v23
	v_add_f32_e32 v16, 1.0, v16
	v_add_f32_e32 v17, 1.0, v17
	v_add_f32_e32 v30, 1.0, v18
	v_add_f32_e32 v31, 1.0, v19
	v_rcp_f32_e32 v18, v20
	v_rcp_f32_e32 v19, v21
	v_rcp_f32_e32 v20, v22
	v_rcp_f32_e32 v21, v23
	v_rcp_f32_e32 v16, v16
	v_rcp_f32_e32 v17, v17
	v_rcp_f32_e32 v22, v30
	v_rcp_f32_e32 v23, v31
	v_pk_mul_f32 v[18:19], v[18:19], v[34:35]
	v_pk_mul_f32 v[20:21], v[20:21], v[36:37]
	v_pk_fma_f32 v[12:13], v[12:13], v[16:17], v[18:19]
	v_pk_fma_f32 v[14:15], v[14:15], v[22:23], v[20:21]
	v_cvt_pk_bf16_f32 v12, v12, v13
	v_cvt_pk_bf16_f32 v13, v14, v15
	global_store_dwordx2 v[24:25], v[12:13], off
	global_load_dwordx4 v[12:15], v[72:73], off offset:64
	s_nop 0
	global_load_dwordx4 v[16:19], v[74:75], off
	s_waitcnt vmcnt(5)
	v_lshlrev_b32_e32 v36, 16, v32
	v_and_b32_e32 v32, 0xffff0000, v32
	v_lshlrev_b32_e32 v37, 16, v33
	v_and_b32_e32 v33, 0xffff0000, v33
	v_lshlrev_b32_e32 v30, 16, v44
	v_and_b32_e32 v31, 0xffff0000, v44
	v_lshlrev_b32_e32 v34, 16, v45
	v_and_b32_e32 v35, 0xffff0000, v45
	v_lshlrev_b32_e32 v20, 16, v149
	v_and_b32_e32 v21, 0xffff0000, v149
	v_lshlrev_b32_e32 v22, 16, v148
	v_and_b32_e32 v23, 0xffff0000, v148
	s_waitcnt vmcnt(1)
	v_add_f32_e32 v12, v12, v30
	s_waitcnt vmcnt(0)
	v_add_f32_e32 v16, v16, v36
	v_add_f32_e32 v17, v17, v32
	v_add_f32_e32 v18, v18, v37
	v_add_f32_e32 v19, v19, v33
	v_add_f32_e32 v13, v13, v31
	v_add_f32_e32 v14, v14, v34
	v_add_f32_e32 v15, v15, v35
	v_mul_f32_e32 v16, 0xbfb8aa3b, v16
	v_mul_f32_e32 v17, 0xbfb8aa3b, v17
	v_mul_f32_e32 v18, 0xbfb8aa3b, v18
	v_mul_f32_e32 v19, 0xbfb8aa3b, v19
	v_mul_f32_e32 v12, 0xbfb8aa3b, v12
	v_mul_f32_e32 v13, 0xbfb8aa3b, v13
	v_mul_f32_e32 v14, 0xbfb8aa3b, v14
	v_mul_f32_e32 v15, 0xbfb8aa3b, v15
	v_exp_f32_e32 v16, v16
	v_exp_f32_e32 v17, v17
	v_exp_f32_e32 v18, v18
	v_exp_f32_e32 v19, v19
	v_exp_f32_e32 v12, v12
	v_exp_f32_e32 v13, v13
	v_exp_f32_e32 v14, v14
	v_exp_f32_e32 v15, v15
	v_add_f32_e32 v16, 1.0, v16
	v_add_f32_e32 v17, 1.0, v17
	v_add_f32_e32 v18, 1.0, v18
	v_add_f32_e32 v19, 1.0, v19
	v_add_f32_e32 v12, 1.0, v12
	v_add_f32_e32 v13, 1.0, v13
	v_add_f32_e32 v30, 1.0, v14
	v_add_f32_e32 v31, 1.0, v15
	v_rcp_f32_e32 v14, v16
	v_rcp_f32_e32 v15, v17
	v_rcp_f32_e32 v16, v18
	v_rcp_f32_e32 v17, v19
	v_rcp_f32_e32 v12, v12
	v_rcp_f32_e32 v13, v13
	v_rcp_f32_e32 v18, v30
	v_rcp_f32_e32 v19, v31
	v_pk_mul_f32 v[14:15], v[14:15], v[20:21]
	v_pk_mul_f32 v[16:17], v[16:17], v[22:23]
	v_pk_fma_f32 v[8:9], v[8:9], v[12:13], v[14:15]
	v_pk_fma_f32 v[10:11], v[10:11], v[18:19], v[16:17]
	v_cvt_pk_bf16_f32 v8, v8, v9
	v_cvt_pk_bf16_f32 v9, v10, v11
	global_store_dwordx2 v[24:25], v[8:9], off offset:32
	global_load_dwordx4 v[8:11], v[72:73], off offset:128
	s_nop 0
	global_load_dwordx4 v[12:15], v[60:61], off
	v_lshlrev_b32_e32 v30, 16, v38
	v_and_b32_e32 v31, 0xffff0000, v38
	v_lshlrev_b32_e32 v32, 16, v39
	v_and_b32_e32 v33, 0xffff0000, v39
	v_lshlrev_b32_e32 v20, 16, v46
	v_and_b32_e32 v21, 0xffff0000, v46
	v_lshlrev_b32_e32 v22, 16, v47
	v_and_b32_e32 v23, 0xffff0000, v47
	v_lshlrev_b32_e32 v16, 16, v147
	v_and_b32_e32 v17, 0xffff0000, v147
	v_lshlrev_b32_e32 v18, 16, v146
	v_and_b32_e32 v19, 0xffff0000, v146
	s_waitcnt vmcnt(1)
	v_add_f32_e32 v8, v8, v20
	s_waitcnt vmcnt(0)
	v_add_f32_e32 v12, v12, v30
	v_add_f32_e32 v13, v13, v31
	v_add_f32_e32 v14, v14, v32
	v_add_f32_e32 v15, v15, v33
	v_add_f32_e32 v9, v9, v21
	v_add_f32_e32 v10, v10, v22
	v_add_f32_e32 v11, v11, v23
	v_mul_f32_e32 v12, 0xbfb8aa3b, v12
	v_mul_f32_e32 v13, 0xbfb8aa3b, v13
	v_mul_f32_e32 v14, 0xbfb8aa3b, v14
	v_mul_f32_e32 v15, 0xbfb8aa3b, v15
	v_mul_f32_e32 v8, 0xbfb8aa3b, v8
	v_mul_f32_e32 v9, 0xbfb8aa3b, v9
	v_mul_f32_e32 v10, 0xbfb8aa3b, v10
	v_mul_f32_e32 v11, 0xbfb8aa3b, v11
	v_exp_f32_e32 v12, v12
	v_exp_f32_e32 v13, v13
	v_exp_f32_e32 v14, v14
	v_exp_f32_e32 v15, v15
	v_exp_f32_e32 v8, v8
	v_exp_f32_e32 v9, v9
	v_exp_f32_e32 v10, v10
	v_exp_f32_e32 v11, v11
	v_add_f32_e32 v12, 1.0, v12
	v_add_f32_e32 v13, 1.0, v13
	v_add_f32_e32 v14, 1.0, v14
	v_add_f32_e32 v15, 1.0, v15
	v_add_f32_e32 v8, 1.0, v8
	v_add_f32_e32 v9, 1.0, v9
	v_add_f32_e32 v20, 1.0, v10
	v_add_f32_e32 v21, 1.0, v11
	v_rcp_f32_e32 v10, v12
	v_rcp_f32_e32 v11, v13
	v_rcp_f32_e32 v12, v14
	v_rcp_f32_e32 v13, v15
	v_rcp_f32_e32 v8, v8
	v_rcp_f32_e32 v9, v9
	v_rcp_f32_e32 v14, v20
	v_rcp_f32_e32 v15, v21
	v_pk_mul_f32 v[10:11], v[10:11], v[16:17]
	v_pk_mul_f32 v[12:13], v[12:13], v[18:19]
	v_pk_fma_f32 v[4:5], v[4:5], v[8:9], v[10:11]
	v_pk_fma_f32 v[6:7], v[6:7], v[14:15], v[12:13]
	v_cvt_pk_bf16_f32 v4, v4, v5
	v_cvt_pk_bf16_f32 v5, v6, v7
	global_store_dwordx2 v[24:25], v[4:5], off offset:64
	global_load_dwordx4 v[4:7], v[72:73], off offset:192
	s_nop 0
	global_load_dwordx4 v[8:11], v[56:57], off
	v_lshlrev_b32_e32 v20, 16, v28
	v_and_b32_e32 v21, 0xffff0000, v28
	v_lshlrev_b32_e32 v22, 16, v29
	v_and_b32_e32 v23, 0xffff0000, v29
	v_lshlrev_b32_e32 v16, 16, v26
	v_and_b32_e32 v17, 0xffff0000, v26
	v_lshlrev_b32_e32 v18, 16, v27
	v_and_b32_e32 v19, 0xffff0000, v27
	v_lshlrev_b32_e32 v12, 16, v145
	v_and_b32_e32 v13, 0xffff0000, v145
	v_lshlrev_b32_e32 v14, 16, v144
	v_and_b32_e32 v15, 0xffff0000, v144
	s_waitcnt vmcnt(1)
	v_add_f32_e32 v4, v4, v16
	s_waitcnt vmcnt(0)
	v_add_f32_e32 v8, v8, v20
	v_add_f32_e32 v9, v9, v21
	v_add_f32_e32 v10, v10, v22
	v_add_f32_e32 v11, v11, v23
	v_add_f32_e32 v5, v5, v17
	v_add_f32_e32 v6, v6, v18
	v_add_f32_e32 v7, v7, v19
	v_mul_f32_e32 v8, 0xbfb8aa3b, v8
	v_mul_f32_e32 v9, 0xbfb8aa3b, v9
	v_mul_f32_e32 v10, 0xbfb8aa3b, v10
	v_mul_f32_e32 v11, 0xbfb8aa3b, v11
	v_mul_f32_e32 v4, 0xbfb8aa3b, v4
	v_mul_f32_e32 v5, 0xbfb8aa3b, v5
	v_mul_f32_e32 v6, 0xbfb8aa3b, v6
	v_mul_f32_e32 v7, 0xbfb8aa3b, v7
	v_exp_f32_e32 v8, v8
	v_exp_f32_e32 v9, v9
	v_exp_f32_e32 v10, v10
	v_exp_f32_e32 v11, v11
	v_exp_f32_e32 v4, v4
	v_exp_f32_e32 v5, v5
	v_exp_f32_e32 v6, v6
	v_exp_f32_e32 v7, v7
	v_add_f32_e32 v8, 1.0, v8
	v_add_f32_e32 v9, 1.0, v9
	v_add_f32_e32 v10, 1.0, v10
	v_add_f32_e32 v11, 1.0, v11
	v_add_f32_e32 v4, 1.0, v4
	v_add_f32_e32 v5, 1.0, v5
	v_add_f32_e32 v16, 1.0, v6
	v_add_f32_e32 v17, 1.0, v7
	v_rcp_f32_e32 v6, v8
	v_rcp_f32_e32 v7, v9
	v_rcp_f32_e32 v8, v10
	v_rcp_f32_e32 v9, v11
	v_rcp_f32_e32 v4, v4
	v_rcp_f32_e32 v5, v5
	v_rcp_f32_e32 v10, v16
	v_rcp_f32_e32 v11, v17
	v_pk_mul_f32 v[6:7], v[6:7], v[12:13]
	v_pk_mul_f32 v[8:9], v[8:9], v[14:15]
	v_pk_fma_f32 v[0:1], v[0:1], v[4:5], v[6:7]
	v_pk_fma_f32 v[2:3], v[2:3], v[10:11], v[8:9]
	v_cvt_pk_bf16_f32 v0, v0, v1
	v_cvt_pk_bf16_f32 v1, v2, v3
	global_store_dwordx2 v[24:25], v[0:1], off offset:96
	s_cbranch_vccz .LBB0_724

.LBB0_719:
	s_and_b32 s19, s18, 0x2000
	s_xor_b32 s26, s19, 0x2000
	s_lshl_b32 s26, s26, 1
	v_lshl_add_u32 v122, v115, 1, s26
	v_lshl_add_u64 v[120:121], v[96:97], 0, s[16:17]
	v_readfirstlane_b32 s27, v122
	v_add_u32_e32 v122, 0x8000, v122
	s_mov_b32 m0, s27
	v_readfirstlane_b32 s27, v122
	v_lshl_add_u32 v122, v114, 1, s26
	s_waitcnt vmcnt(0)
	s_waitcnt vmcnt(0) lgkmcnt(0)
	s_barrier
	global_load_lds_dwordx4 v[120:121], off
	v_lshl_add_u64 v[120:121], v[98:99], 0, s[16:17]
	s_mov_b32 m0, s27
	v_readfirstlane_b32 s27, v122
	v_add_u32_e32 v122, 0x8000, v122
	global_load_lds_dwordx4 v[120:121], off
	v_lshl_add_u64 v[120:121], v[100:101], 0, s[16:17]
	s_mov_b32 m0, s27
	v_readfirstlane_b32 s27, v122
	v_lshl_add_u32 v122, v113, 1, s26
	global_load_lds_dwordx4 v[120:121], off
	v_lshl_add_u64 v[120:121], v[102:103], 0, s[16:17]
	s_mov_b32 m0, s27
	v_readfirstlane_b32 s27, v122
	v_add_u32_e32 v122, 0x8000, v122
	global_load_lds_dwordx4 v[120:121], off
	v_lshl_add_u64 v[120:121], v[104:105], 0, s[16:17]
	s_mov_b32 m0, s27
	v_readfirstlane_b32 s27, v122
	v_lshl_add_u32 v122, v112, 1, s26
	global_load_lds_dwordx4 v[120:121], off
	v_lshl_add_u64 v[120:121], v[106:107], 0, s[16:17]
	s_mov_b32 m0, s27
	v_readfirstlane_b32 s26, v122
	v_add_u32_e32 v122, 0x8000, v122
	global_load_lds_dwordx4 v[120:121], off
	v_lshl_add_u64 v[120:121], v[108:109], 0, s[16:17]
	s_mov_b32 m0, s26
	v_readfirstlane_b32 s26, v122
	global_load_lds_dwordx4 v[120:121], off
	v_lshl_add_u64 v[120:121], v[110:111], 0, s[16:17]
	s_mov_b32 m0, s26
	s_nop 0
	global_load_lds_dwordx4 v[120:121], off
	s_lshl_b32 s19, s19, 1
	v_add_u32_e32 v163, s19, v117
	v_or_b32_e32 v172, s19, v116
	v_add_u32_e32 v148, v163, v119
	v_add_u32_e32 v168, v172, v119
	ds_read_b128 v[152:155], v168 offset:32768
	ds_read_b128 v[156:159], v168 offset:34816
	ds_read_b128 v[164:167], v168 offset:36864
	ds_read_b128 v[168:171], v168 offset:38912
	ds_read_b128 v[120:123], v148
	ds_read_b128 v[124:127], v148 offset:2048
	ds_read_b128 v[144:147], v148 offset:4096
	ds_read_b128 v[148:151], v148 offset:6144
	s_setprio 1
	s_waitcnt lgkmcnt(3)
	v_mfma_f32_16x16x32_bf16 v[0:3], v[152:155], v[120:123], v[0:3]
	v_mfma_f32_16x16x32_bf16 v[4:7], v[156:159], v[120:123], v[4:7]
	v_mfma_f32_16x16x32_bf16 v[8:11], v[164:167], v[120:123], v[8:11]
	v_mfma_f32_16x16x32_bf16 v[12:15], v[168:171], v[120:123], v[12:15]
	s_waitcnt lgkmcnt(2)
	v_mfma_f32_16x16x32_bf16 v[16:19], v[152:155], v[124:127], v[16:19]
	v_mfma_f32_16x16x32_bf16 v[20:23], v[156:159], v[124:127], v[20:23]
	v_mfma_f32_16x16x32_bf16 v[24:27], v[164:167], v[124:127], v[24:27]
	v_mfma_f32_16x16x32_bf16 v[28:31], v[168:171], v[124:127], v[28:31]
	s_waitcnt lgkmcnt(1)
	v_mfma_f32_16x16x32_bf16 v[32:35], v[152:155], v[144:147], v[32:35]
	v_mfma_f32_16x16x32_bf16 v[36:39], v[156:159], v[144:147], v[36:39]
	v_mfma_f32_16x16x32_bf16 v[40:43], v[164:167], v[144:147], v[40:43]
	v_mfma_f32_16x16x32_bf16 v[44:47], v[168:171], v[144:147], v[44:47]
	s_waitcnt lgkmcnt(0)
	v_mfma_f32_16x16x32_bf16 v[48:51], v[152:155], v[148:151], v[48:51]
	v_mfma_f32_16x16x32_bf16 v[52:55], v[156:159], v[148:151], v[52:55]
	v_mfma_f32_16x16x32_bf16 v[56:59], v[164:167], v[148:151], v[56:59]
	v_mfma_f32_16x16x32_bf16 v[60:63], v[168:171], v[148:151], v[60:63]
	s_setprio 0
	v_add_u32_e32 v148, v163, v118
	v_add_u32_e32 v163, v172, v118
	ds_read_b128 v[152:155], v163 offset:32768
	ds_read_b128 v[156:159], v163 offset:34816
	ds_read_b128 v[164:167], v163 offset:36864
	ds_read_b128 v[168:171], v163 offset:38912
	ds_read_b128 v[120:123], v148
	ds_read_b128 v[124:127], v148 offset:2048
	ds_read_b128 v[144:147], v148 offset:4096
	ds_read_b128 v[148:151], v148 offset:6144
	s_setprio 1
	s_waitcnt lgkmcnt(3)
	v_mfma_f32_16x16x32_bf16 v[0:3], v[152:155], v[120:123], v[0:3]
	v_mfma_f32_16x16x32_bf16 v[4:7], v[156:159], v[120:123], v[4:7]
	v_mfma_f32_16x16x32_bf16 v[8:11], v[164:167], v[120:123], v[8:11]
	v_mfma_f32_16x16x32_bf16 v[12:15], v[168:171], v[120:123], v[12:15]
	s_waitcnt lgkmcnt(2)
	v_mfma_f32_16x16x32_bf16 v[16:19], v[152:155], v[124:127], v[16:19]
	v_mfma_f32_16x16x32_bf16 v[20:23], v[156:159], v[124:127], v[20:23]
	v_mfma_f32_16x16x32_bf16 v[24:27], v[164:167], v[124:127], v[24:27]
	v_mfma_f32_16x16x32_bf16 v[28:31], v[168:171], v[124:127], v[28:31]
	s_waitcnt lgkmcnt(1)
	v_mfma_f32_16x16x32_bf16 v[32:35], v[152:155], v[144:147], v[32:35]
	v_mfma_f32_16x16x32_bf16 v[36:39], v[156:159], v[144:147], v[36:39]
	v_mfma_f32_16x16x32_bf16 v[40:43], v[164:167], v[144:147], v[40:43]
	v_mfma_f32_16x16x32_bf16 v[44:47], v[168:171], v[144:147], v[44:47]
	s_waitcnt lgkmcnt(0)
	v_mfma_f32_16x16x32_bf16 v[48:51], v[152:155], v[148:151], v[48:51]
	v_mfma_f32_16x16x32_bf16 v[52:55], v[156:159], v[148:151], v[52:55]
	v_mfma_f32_16x16x32_bf16 v[56:59], v[164:167], v[148:151], v[56:59]
	v_mfma_f32_16x16x32_bf16 v[60:63], v[168:171], v[148:151], v[60:63]
	s_setprio 0
	s_add_u32 s16, s16, 0x80
	s_addc_u32 s17, s17, 0
	s_addk_i32 s18, 0x2000
	s_cmpk_lg_i32 s16, 0x780
	s_cbranch_scc1 .LBB0_719
	v_lshlrev_b32_e32 v96, 1, v115
	v_lshl_add_u64 v[64:65], v[64:65], 1, v[132:133]
	v_readfirstlane_b32 s16, v96
	s_mov_b32 m0, s16
	s_waitcnt vmcnt(0)
	s_waitcnt vmcnt(0)
	s_barrier
	global_load_lds_dwordx4 v[64:65], off
	v_add_u32_e32 v64, 0x8000, v96
	v_lshl_add_u64 v[70:71], v[70:71], 1, v[134:135]
	v_readfirstlane_b32 s16, v64
	v_lshlrev_b32_e32 v64, 1, v114
	s_mov_b32 m0, s16
	v_readfirstlane_b32 s16, v64
	v_add_u32_e32 v64, 0x8000, v64
	v_lshl_add_u64 v[80:81], v[80:81], 1, v[132:133]
	global_load_lds_dwordx4 v[70:71], off
	s_mov_b32 m0, s16
	v_readfirstlane_b32 s16, v64
	v_lshlrev_b32_e32 v64, 1, v113
	v_lshl_add_u64 v[86:87], v[86:87], 1, v[134:135]
	global_load_lds_dwordx4 v[80:81], off
	s_mov_b32 m0, s16
	v_readfirstlane_b32 s16, v64
	v_add_u32_e32 v64, 0x8000, v64
	v_lshl_add_u64 v[88:89], v[88:89], 1, v[132:133]
	global_load_lds_dwordx4 v[86:87], off
	s_mov_b32 m0, s16
	v_readfirstlane_b32 s16, v64
	v_lshlrev_b32_e32 v64, 1, v112
	v_lshl_add_u64 v[90:91], v[90:91], 1, v[134:135]
	global_load_lds_dwordx4 v[88:89], off
	s_mov_b32 m0, s16
	v_readfirstlane_b32 s16, v64
	v_add_u32_e32 v64, 0x8000, v64
	v_lshl_add_u64 v[92:93], v[92:93], 1, v[132:133]
	global_load_lds_dwordx4 v[90:91], off
	s_mov_b32 m0, s16
	v_readfirstlane_b32 s16, v64
	v_lshl_add_u64 v[94:95], v[94:95], 1, v[134:135]
	global_load_lds_dwordx4 v[92:93], off
	s_mov_b32 m0, s16
	s_nop 0
	global_load_lds_dwordx4 v[94:95], off
	v_add_u32_e32 v64, v117, v119
	ds_read_b128 v[86:89], v64 offset:16384
	ds_read_b128 v[90:93], v64 offset:18432
	ds_read_b128 v[94:97], v64 offset:20480
	ds_read_b128 v[98:101], v64 offset:22528
	v_add_u32_e32 v64, v116, v119
	ds_read_b128 v[102:105], v64 offset:49152
	ds_read_b128 v[106:109], v64 offset:51200
	ds_read_b128 v[110:113], v64 offset:53248
	ds_read_b128 v[120:123], v64 offset:55296
	s_setprio 1
	s_waitcnt lgkmcnt(0)
	v_mfma_f32_16x16x32_bf16 v[0:3], v[102:105], v[86:89], v[0:3]
	v_mfma_f32_16x16x32_bf16 v[4:7], v[106:109], v[86:89], v[4:7]
	v_mfma_f32_16x16x32_bf16 v[8:11], v[110:113], v[86:89], v[8:11]
	v_mfma_f32_16x16x32_bf16 v[12:15], v[120:123], v[86:89], v[12:15]
	v_mfma_f32_16x16x32_bf16 v[16:19], v[102:105], v[90:93], v[16:19]
	v_mfma_f32_16x16x32_bf16 v[20:23], v[106:109], v[90:93], v[20:23]
	v_mfma_f32_16x16x32_bf16 v[24:27], v[110:113], v[90:93], v[24:27]
	v_mfma_f32_16x16x32_bf16 v[28:31], v[120:123], v[90:93], v[28:31]
	v_mfma_f32_16x16x32_bf16 v[32:35], v[102:105], v[94:97], v[32:35]
	v_mfma_f32_16x16x32_bf16 v[36:39], v[106:109], v[94:97], v[36:39]
	v_mfma_f32_16x16x32_bf16 v[40:43], v[110:113], v[94:97], v[40:43]
	v_mfma_f32_16x16x32_bf16 v[44:47], v[120:123], v[94:97], v[44:47]
	v_mfma_f32_16x16x32_bf16 v[48:51], v[102:105], v[98:101], v[48:51]
	v_mfma_f32_16x16x32_bf16 v[52:55], v[106:109], v[98:101], v[52:55]
	v_mfma_f32_16x16x32_bf16 v[56:59], v[110:113], v[98:101], v[56:59]
	v_mfma_f32_16x16x32_bf16 v[60:63], v[120:123], v[98:101], v[60:63]
	s_setprio 0
	v_add_u32_e32 v64, v117, v118
	ds_read_b128 v[86:89], v64 offset:16384
	ds_read_b128 v[90:93], v64 offset:18432
	ds_read_b128 v[94:97], v64 offset:20480
	ds_read_b128 v[98:101], v64 offset:22528
	v_add_u32_e32 v64, v116, v118
	ds_read_b128 v[102:105], v64 offset:49152
	ds_read_b128 v[106:109], v64 offset:51200
	ds_read_b128 v[110:113], v64 offset:53248
	ds_read_b128 v[114:117], v64 offset:55296
	s_setprio 1
	s_waitcnt lgkmcnt(0)
	v_mfma_f32_16x16x32_bf16 v[0:3], v[102:105], v[86:89], v[0:3]
	v_mfma_f32_16x16x32_bf16 v[4:7], v[106:109], v[86:89], v[4:7]
	v_mfma_f32_16x16x32_bf16 v[8:11], v[110:113], v[86:89], v[8:11]
	v_mfma_f32_16x16x32_bf16 v[12:15], v[114:117], v[86:89], v[12:15]
	v_mfma_f32_16x16x32_bf16 v[16:19], v[102:105], v[90:93], v[16:19]
	v_mfma_f32_16x16x32_bf16 v[20:23], v[106:109], v[90:93], v[20:23]
	v_mfma_f32_16x16x32_bf16 v[24:27], v[110:113], v[90:93], v[24:27]
	v_mfma_f32_16x16x32_bf16 v[28:31], v[114:117], v[90:93], v[28:31]
	v_mfma_f32_16x16x32_bf16 v[32:35], v[102:105], v[94:97], v[32:35]
	v_mfma_f32_16x16x32_bf16 v[36:39], v[106:109], v[94:97], v[36:39]
	v_mfma_f32_16x16x32_bf16 v[40:43], v[110:113], v[94:97], v[40:43]
	v_mfma_f32_16x16x32_bf16 v[44:47], v[114:117], v[94:97], v[44:47]
	v_mfma_f32_16x16x32_bf16 v[48:51], v[102:105], v[98:101], v[48:51]
	v_mfma_f32_16x16x32_bf16 v[52:55], v[106:109], v[98:101], v[52:55]
	v_mfma_f32_16x16x32_bf16 v[56:59], v[110:113], v[98:101], v[56:59]
	v_mfma_f32_16x16x32_bf16 v[60:63], v[114:117], v[98:101], v[60:63]
	s_setprio 0
	v_mov_b32_e32 v64, v199
	v_lshl_add_u64 v[144:145], v[140:141], 0, v[66:67]
	v_and_b32_e32 v65, 15, v64
	v_lshrrev_b32_e32 v81, 1, v64
	v_and_or_b32 v65, v81, s20, v65
	v_lshrrev_b32_e32 v70, 4, v64
	v_bfe_u32 v71, v64, 4, 2
	v_bfe_u32 v80, v64, 1, 3
	v_lshlrev_b32_e32 v172, 7, v65
	v_lshlrev_b32_e32 v65, 7, v64
	v_and_b32_e32 v171, 0x2780, v65
	v_bitop3_b32 v65, v70, v80, 3 bitop3:0x6c
	v_bitop3_b32 v70, v71, v80, 4 bitop3:0x36
	v_lshlrev_b32_e32 v65, 3, v65
	v_lshlrev_b32_e32 v70, 3, v70
	v_lshlrev_b32_e32 v163, 4, v64
	v_mov_b32_e32 v64, 0
	v_lshl_add_u64 v[146:147], v[142:143], 0, v[68:69]
	v_lshl_add_u64 v[148:149], v[140:141], 0, v[72:73]
	v_lshl_add_u64 v[150:151], v[142:143], 0, v[74:75]
	v_lshl_add_u64 v[152:153], v[140:141], 0, v[76:77]
	v_lshl_add_u64 v[154:155], v[142:143], 0, v[78:79]
	v_lshl_add_u64 v[156:157], v[140:141], 0, v[82:83]
	v_lshl_add_u64 v[158:159], v[142:143], 0, v[84:85]
	s_mov_b64 s[16:17], 0
	s_mov_b32 s18, 0
	v_lshlrev_b32_e32 v176, 1, v65
	v_lshlrev_b32_e32 v174, 1, v70
	v_mov_b32_e32 v65, v64
	v_mov_b32_e32 v66, v64
	v_mov_b32_e32 v67, v64
	v_mov_b32_e32 v68, v64
	v_mov_b32_e32 v69, v64
	v_mov_b32_e32 v70, v64
	v_mov_b32_e32 v71, v64
	v_mov_b32_e32 v72, v64
	v_mov_b32_e32 v73, v64
	v_mov_b32_e32 v74, v64
	v_mov_b32_e32 v75, v64
	v_mov_b32_e32 v76, v64
	v_mov_b32_e32 v77, v64
	v_mov_b32_e32 v78, v64
	v_mov_b32_e32 v79, v64
	v_mov_b32_e32 v80, v64
	v_mov_b32_e32 v81, v64
	v_mov_b32_e32 v82, v64
	v_mov_b32_e32 v83, v64
	v_mov_b32_e32 v84, v64
	v_mov_b32_e32 v85, v64
	v_mov_b32_e32 v86, v64
	v_mov_b32_e32 v87, v64
	v_mov_b32_e32 v88, v64
	v_mov_b32_e32 v89, v64
	v_mov_b32_e32 v90, v64
	v_mov_b32_e32 v91, v64
	v_mov_b32_e32 v92, v64
	v_mov_b32_e32 v93, v64
	v_mov_b32_e32 v94, v64
	v_mov_b32_e32 v95, v64
	v_mov_b32_e32 v96, v64
	v_mov_b32_e32 v97, v64
	v_mov_b32_e32 v98, v64
	v_mov_b32_e32 v99, v64
	v_mov_b32_e32 v100, v64
	v_mov_b32_e32 v101, v64
	v_mov_b32_e32 v102, v64
	v_mov_b32_e32 v103, v64
	v_mov_b32_e32 v104, v64
	v_mov_b32_e32 v105, v64
	v_mov_b32_e32 v106, v64
	v_mov_b32_e32 v107, v64
	v_mov_b32_e32 v108, v64
	v_mov_b32_e32 v109, v64
	v_mov_b32_e32 v110, v64
	v_mov_b32_e32 v111, v64
	v_mov_b32_e32 v112, v64
	v_mov_b32_e32 v113, v64
	v_mov_b32_e32 v114, v64
	v_mov_b32_e32 v115, v64
	v_mov_b32_e32 v116, v64
	v_mov_b32_e32 v117, v64
	v_mov_b32_e32 v118, v64
	v_mov_b32_e32 v119, v64
	v_mov_b32_e32 v120, v64
	v_mov_b32_e32 v121, v64
	v_mov_b32_e32 v122, v64
	v_mov_b32_e32 v123, v64
	v_mov_b32_e32 v124, v64
	v_mov_b32_e32 v125, v64
	v_mov_b32_e32 v126, v64
	v_mov_b32_e32 v127, v64

.LBB0_805:
	s_and_b32 s31, s30, 0x2000
	s_xor_b32 s48, s31, 0x2000
	s_lshl_b32 s48, s48, 1
	v_lshl_add_u32 v103, v101, 1, s48
	v_lshl_add_u64 v[104:105], v[82:83], 0, s[26:27]
	v_readfirstlane_b32 s49, v103
	v_add_u32_e32 v103, 0x8000, v103
	s_mov_b32 m0, s49
	v_readfirstlane_b32 s49, v103
	v_lshl_add_u32 v103, v99, 1, s48
	s_waitcnt vmcnt(0)
	s_waitcnt vmcnt(0) lgkmcnt(0)
	s_barrier
	global_load_lds_dwordx4 v[104:105], off
	v_lshl_add_u64 v[104:105], v[78:79], 0, s[26:27]
	s_mov_b32 m0, s49
	v_readfirstlane_b32 s49, v103
	v_add_u32_e32 v103, 0x8000, v103
	global_load_lds_dwordx4 v[104:105], off
	v_lshl_add_u64 v[104:105], v[92:93], 0, s[26:27]
	s_mov_b32 m0, s49
	v_readfirstlane_b32 s49, v103
	v_lshl_add_u32 v103, v98, 1, s48
	global_load_lds_dwordx4 v[104:105], off
	v_lshl_add_u64 v[104:105], v[90:91], 0, s[26:27]
	s_mov_b32 m0, s49
	v_readfirstlane_b32 s49, v103
	v_add_u32_e32 v103, 0x8000, v103
	global_load_lds_dwordx4 v[104:105], off
	v_lshl_add_u64 v[104:105], v[88:89], 0, s[26:27]
	s_mov_b32 m0, s49
	v_readfirstlane_b32 s49, v103
	v_lshl_add_u32 v103, v95, 1, s48
	global_load_lds_dwordx4 v[104:105], off
	v_lshl_add_u64 v[104:105], v[86:87], 0, s[26:27]
	s_mov_b32 m0, s49
	v_readfirstlane_b32 s48, v103
	v_add_u32_e32 v103, 0x8000, v103
	global_load_lds_dwordx4 v[104:105], off
	v_lshl_add_u64 v[104:105], v[84:85], 0, s[26:27]
	s_mov_b32 m0, s48
	v_readfirstlane_b32 s48, v103
	global_load_lds_dwordx4 v[104:105], off
	v_lshl_add_u64 v[104:105], v[80:81], 0, s[26:27]
	s_mov_b32 m0, s48
	s_nop 0
	global_load_lds_dwordx4 v[104:105], off
	s_lshl_b32 s31, s31, 1
	v_add_u32_e32 v103, s31, v97
	v_or_b32_e32 v136, s31, v96
	v_add_u32_e32 v116, v103, v102
	v_add_u32_e32 v132, v136, v102
	ds_read_b128 v[120:123], v132 offset:32768
	ds_read_b128 v[124:127], v132 offset:34816
	ds_read_b128 v[128:131], v132 offset:36864
	ds_read_b128 v[132:135], v132 offset:38912
	ds_read_b128 v[104:107], v116
	ds_read_b128 v[108:111], v116 offset:2048
	ds_read_b128 v[112:115], v116 offset:4096
	ds_read_b128 v[116:119], v116 offset:6144
	s_setprio 1
	s_waitcnt lgkmcnt(3)
	v_mfma_f32_16x16x32_bf16 v[64:67], v[120:123], v[104:107], v[64:67]
	v_mfma_f32_16x16x32_bf16 v[60:63], v[124:127], v[104:107], v[60:63]
	v_mfma_f32_16x16x32_bf16 v[56:59], v[128:131], v[104:107], v[56:59]
	v_mfma_f32_16x16x32_bf16 v[52:55], v[132:135], v[104:107], v[52:55]
	s_waitcnt lgkmcnt(2)
	v_mfma_f32_16x16x32_bf16 v[48:51], v[120:123], v[108:111], v[48:51]
	v_mfma_f32_16x16x32_bf16 v[44:47], v[124:127], v[108:111], v[44:47]
	v_mfma_f32_16x16x32_bf16 v[40:43], v[128:131], v[108:111], v[40:43]
	v_mfma_f32_16x16x32_bf16 v[36:39], v[132:135], v[108:111], v[36:39]
	s_waitcnt lgkmcnt(1)
	v_mfma_f32_16x16x32_bf16 v[32:35], v[120:123], v[112:115], v[32:35]
	v_mfma_f32_16x16x32_bf16 v[28:31], v[124:127], v[112:115], v[28:31]
	v_mfma_f32_16x16x32_bf16 v[24:27], v[128:131], v[112:115], v[24:27]
	v_mfma_f32_16x16x32_bf16 v[20:23], v[132:135], v[112:115], v[20:23]
	s_waitcnt lgkmcnt(0)
	v_mfma_f32_16x16x32_bf16 v[16:19], v[120:123], v[116:119], v[16:19]
	v_mfma_f32_16x16x32_bf16 v[12:15], v[124:127], v[116:119], v[12:15]
	v_mfma_f32_16x16x32_bf16 v[8:11], v[128:131], v[116:119], v[8:11]
	v_mfma_f32_16x16x32_bf16 v[4:7], v[132:135], v[116:119], v[4:7]
	s_setprio 0
	v_add_u32_e32 v103, v103, v100
	ds_read_b128 v[104:107], v103
	ds_read_b128 v[108:111], v103 offset:2048
	ds_read_b128 v[112:115], v103 offset:4096
	ds_read_b128 v[116:119], v103 offset:6144
	v_add_u32_e32 v103, v136, v100
	ds_read_b128 v[120:123], v103 offset:32768
	ds_read_b128 v[124:127], v103 offset:34816
	ds_read_b128 v[128:131], v103 offset:36864
	ds_read_b128 v[132:135], v103 offset:38912
	s_setprio 1
	s_waitcnt lgkmcnt(0)
	v_mfma_f32_16x16x32_bf16 v[64:67], v[120:123], v[104:107], v[64:67]
	v_mfma_f32_16x16x32_bf16 v[60:63], v[124:127], v[104:107], v[60:63]
	v_mfma_f32_16x16x32_bf16 v[56:59], v[128:131], v[104:107], v[56:59]
	v_mfma_f32_16x16x32_bf16 v[52:55], v[132:135], v[104:107], v[52:55]
	v_mfma_f32_16x16x32_bf16 v[48:51], v[120:123], v[108:111], v[48:51]
	v_mfma_f32_16x16x32_bf16 v[44:47], v[124:127], v[108:111], v[44:47]
	v_mfma_f32_16x16x32_bf16 v[40:43], v[128:131], v[108:111], v[40:43]
	v_mfma_f32_16x16x32_bf16 v[36:39], v[132:135], v[108:111], v[36:39]
	v_mfma_f32_16x16x32_bf16 v[32:35], v[120:123], v[112:115], v[32:35]
	v_mfma_f32_16x16x32_bf16 v[28:31], v[124:127], v[112:115], v[28:31]
	v_mfma_f32_16x16x32_bf16 v[24:27], v[128:131], v[112:115], v[24:27]
	v_mfma_f32_16x16x32_bf16 v[20:23], v[132:135], v[112:115], v[20:23]
	v_mfma_f32_16x16x32_bf16 v[16:19], v[120:123], v[116:119], v[16:19]
	v_mfma_f32_16x16x32_bf16 v[12:15], v[124:127], v[116:119], v[12:15]
	v_mfma_f32_16x16x32_bf16 v[8:11], v[128:131], v[116:119], v[8:11]
	v_mfma_f32_16x16x32_bf16 v[4:7], v[132:135], v[116:119], v[4:7]
	s_setprio 0
	s_add_u32 s26, s26, 0x80
	s_addc_u32 s27, s27, 0
	s_addk_i32 s30, 0x2000
	s_cmpk_lg_i32 s26, 0xf80
	s_cbranch_scc1 .LBB0_805
	v_add_u32_e32 v78, s35, v73
	v_add_u32_e32 v80, s43, v73
	v_ashrrev_i32_e32 v79, 31, v78
	v_lshlrev_b64 v[78:79], 12, v[78:79]
	v_ashrrev_i32_e32 v81, 31, v80
	v_lshl_add_u64 v[82:83], v[74:75], 0, v[78:79]
	v_lshlrev_b64 v[78:79], 12, v[80:81]
	s_waitcnt vmcnt(0)
	v_lshl_add_u64 v[78:79], v[76:77], 0, v[78:79]
	v_lshl_add_u64 v[92:93], v[82:83], 0, s[18:19]
	v_lshl_add_u64 v[90:91], v[78:79], 0, s[18:19]
	v_lshl_add_u64 v[88:89], v[82:83], 0, s[16:17]
	v_lshl_add_u64 v[86:87], v[78:79], 0, s[16:17]
	v_lshl_add_u64 v[84:85], v[82:83], 0, s[14:15]
	v_lshl_add_u64 v[80:81], v[78:79], 0, s[14:15]
	s_andn2_b64 vcc, exec, s[24:25]
	s_waitcnt vmcnt(0)
	s_barrier
	s_cbranch_vccnz .LBB0_797
	v_lshlrev_b32_e32 v101, 1, v101
	v_lshlrev_b32_e32 v99, 1, v99
	v_readfirstlane_b32 s24, v101
	v_add_u32_e32 v101, 0x8000, v101
	s_mov_b32 m0, s24
	v_readfirstlane_b32 s24, v101
	global_load_lds_dwordx4 v[82:83], off
	s_mov_b32 m0, s24
	v_readfirstlane_b32 s24, v99
	v_add_u32_e32 v99, 0x8000, v99
	global_load_lds_dwordx4 v[78:79], off
	s_mov_b32 m0, s24
	v_readfirstlane_b32 s24, v99
	v_lshlrev_b32_e32 v98, 1, v98
	global_load_lds_dwordx4 v[92:93], off
	s_mov_b32 m0, s24
	v_readfirstlane_b32 s24, v98
	v_add_u32_e32 v98, 0x8000, v98
	global_load_lds_dwordx4 v[90:91], off
	s_mov_b32 m0, s24
	v_readfirstlane_b32 s24, v98
	v_lshlrev_b32_e32 v95, 1, v95
	global_load_lds_dwordx4 v[88:89], off
	s_mov_b32 m0, s24
	v_readfirstlane_b32 s24, v95
	v_add_u32_e32 v95, 0x8000, v95
	global_load_lds_dwordx4 v[86:87], off
	s_mov_b32 m0, s24
	v_readfirstlane_b32 s24, v95
	global_load_lds_dwordx4 v[84:85], off
	s_mov_b32 m0, s24
	s_nop 0
	global_load_lds_dwordx4 v[80:81], off
	s_branch .LBB0_797

.LBB0_959:
	s_nop 0
	global_load_dwordx4 v[0:3], v93, s[64:65] offset:48
	global_load_dwordx4 v[4:7], v93, s[64:65] offset:32
	global_load_dwordx4 v[8:11], v93, s[64:65] offset:16
	global_load_dwordx4 v[12:15], v93, s[64:65]
	s_ashr_i32 s74, s62, 4
	s_cmp_gt_i32 s74, -1
	s_cselect_b64 s[0:1], -1, 0
	s_mov_b64 s[66:67], 0x18080
	s_waitcnt vmcnt(1)
	v_readfirstlane_b32 s96, v8
	s_waitcnt vmcnt(0)
	v_readfirstlane_b32 s97, v15
	v_readfirstlane_b32 s56, v14
	v_readfirstlane_b32 s57, v13
	v_readfirstlane_b32 s80, v12
	global_load_dwordx4 v[12:15], v93, s[68:69] offset:48
	global_load_dwordx4 v[16:19], v93, s[68:69] offset:32
	global_load_dwordx4 v[20:23], v93, s[68:69] offset:16
	global_load_dwordx4 v[24:27], v93, s[68:69]
	s_add_i32 s2, s80, 0x7f
	s_add_i32 s3, s57, 0x7f
	s_ashr_i32 s3, s3, 7
	s_ashr_i32 s2, s2, 7
	s_cmp_lt_i32 s74, s2
	s_cselect_b64 s[4:5], -1, 0
	s_and_b64 s[76:77], s[0:1], s[4:5]
	s_cmp_ge_i32 s74, s2
	s_cselect_b64 s[0:1], -1, 0
	s_add_i32 s3, s3, s2
	s_cmp_lt_i32 s74, s3
	s_cselect_b64 s[4:5], -1, 0
	s_and_b64 s[78:79], s[0:1], s[4:5]
	s_add_i32 s0, s56, 0x7f
	s_ashr_i32 s33, s0, 7
	s_cmp_ge_i32 s74, s3
	s_cselect_b64 s[0:1], -1, 0
	s_add_i32 s33, s33, s3
	s_cmp_lt_i32 s74, s33
	s_cselect_b64 s[4:5], -1, 0
	s_and_b64 s[82:83], s[0:1], s[4:5]
	s_add_i32 s0, s97, 0x7f
	s_ashr_i32 s58, s0, 7
	s_cmp_ge_i32 s74, s33
	s_cselect_b64 s[0:1], -1, 0
	s_add_i32 s58, s58, s33
	s_cmp_lt_i32 s74, s58
	s_cselect_b64 s[4:5], -1, 0
	s_and_b64 s[84:85], s[0:1], s[4:5]
	s_add_i32 s0, s96, 0x7f
	s_ashr_i32 s60, s0, 7
	s_cmp_ge_i32 s74, s58
	s_cselect_b64 s[0:1], -1, 0
	s_add_i32 s60, s60, s58
	s_cmp_lt_i32 s74, s60
	v_readfirstlane_b32 s63, v9
	s_cselect_b64 s[4:5], -1, 0
	s_and_b64 s[88:89], s[0:1], s[4:5]
	s_add_i32 s0, s63, 0x7f
	s_ashr_i32 s61, s0, 7
	s_cmp_ge_i32 s74, s60
	v_add_u32_e32 v9, 0x7f, v10
	s_cselect_b64 s[0:1], -1, 0
	s_add_i32 s61, s61, s60
	v_ashrrev_i32_e32 v9, 7, v9
	v_add_u32_e32 v42, s61, v9
	v_add_u32_e32 v9, 0x7f, v11
	v_ashrrev_i32_e32 v9, 7, v9
	v_add_u32_e32 v43, v9, v42
	v_add_u32_e32 v9, 0x7f, v4
	v_ashrrev_i32_e32 v9, 7, v9
	v_add_u32_e32 v44, v9, v43
	v_add_u32_e32 v9, 0x7f, v5
	v_ashrrev_i32_e32 v9, 7, v9
	v_add_u32_e32 v45, v9, v44
	v_add_u32_e32 v9, 0x7f, v6
	v_ashrrev_i32_e32 v9, 7, v9
	v_add_u32_e32 v46, v9, v45
	v_add_u32_e32 v9, 0x7f, v7
	v_ashrrev_i32_e32 v9, 7, v9
	v_add_u32_e32 v47, v9, v46
	v_add_u32_e32 v9, 0x7f, v0
	v_ashrrev_i32_e32 v9, 7, v9
	v_add_u32_e32 v48, v9, v47
	v_add_u32_e32 v9, 0x7f, v1
	v_ashrrev_i32_e32 v9, 7, v9
	v_add_u32_e32 v49, v9, v48
	v_add_u32_e32 v9, 0x7f, v2
	v_ashrrev_i32_e32 v9, 7, v9
	v_add_u32_e32 v50, v9, v49
	v_add_u32_e32 v9, 0x7f, v3
	v_ashrrev_i32_e32 v9, 7, v9
	v_add_u32_e32 v51, v9, v50
	s_cmp_lt_i32 s74, s61
	v_cndmask_b32_e64 v8, 0, 1, s[78:79]
	s_cselect_b64 s[4:5], -1, 0
	v_cndmask_b32_e64 v8, v8, 2, s[82:83]
	s_and_b64 s[90:91], s[0:1], s[4:5]
	v_cndmask_b32_e64 v8, v8, 3, s[84:85]
	s_waitcnt vmcnt(0)
	v_add_u32_e32 v9, 0x7f, v24
	v_ashrrev_i32_e32 v9, 7, v9
	v_add_u32_e32 v52, v9, v51
	v_add_u32_e32 v9, 0x7f, v25
	v_ashrrev_i32_e32 v9, 7, v9
	v_add_u32_e32 v53, v9, v52
	v_add_u32_e32 v9, 0x7f, v26
	v_ashrrev_i32_e32 v9, 7, v9
	v_add_u32_e32 v54, v9, v53
	v_add_u32_e32 v9, 0x7f, v27
	s_cmp_ge_i32 s74, s61
	v_ashrrev_i32_e32 v9, 7, v9
	v_cndmask_b32_e64 v8, v8, 4, s[88:89]
	s_cselect_b64 s[0:1], -1, 0
	v_cmp_lt_i32_e32 vcc, s74, v42
	v_add_u32_e32 v55, v9, v54
	v_add_u32_e32 v9, 0x7f, v20
	v_cndmask_b32_e64 v8, v8, 5, s[90:91]
	s_and_b64 vcc, s[0:1], vcc
	v_cmp_ge_i32_e64 s[0:1], s74, v42
	v_cmp_lt_i32_e64 s[4:5], s74, v43
	v_ashrrev_i32_e32 v9, 7, v9
	v_cndmask_b32_e64 v8, v8, 6, vcc
	s_and_b64 s[4:5], s[0:1], s[4:5]
	v_cmp_ge_i32_e64 s[0:1], s74, v43
	v_cmp_lt_i32_e64 s[6:7], s74, v44
	v_add_u32_e32 v56, v9, v55
	v_add_u32_e32 v9, 0x7f, v21
	v_cndmask_b32_e64 v8, v8, 7, s[4:5]
	s_and_b64 s[6:7], s[0:1], s[6:7]
	v_cmp_ge_i32_e64 s[0:1], s74, v44
	v_cmp_lt_i32_e64 s[8:9], s74, v45
	v_ashrrev_i32_e32 v9, 7, v9
	v_cndmask_b32_e64 v8, v8, 8, s[6:7]
	s_and_b64 s[8:9], s[0:1], s[8:9]
	v_cmp_ge_i32_e64 s[0:1], s74, v45
	v_cmp_lt_i32_e64 s[10:11], s74, v46
	v_add_u32_e32 v57, v9, v56
	v_add_u32_e32 v9, 0x7f, v22
	v_cndmask_b32_e64 v8, v8, 9, s[8:9]
	s_and_b64 s[10:11], s[0:1], s[10:11]
	v_cmp_ge_i32_e64 s[0:1], s74, v46
	v_cmp_lt_i32_e64 s[12:13], s74, v47
	v_ashrrev_i32_e32 v9, 7, v9
	v_cndmask_b32_e64 v8, v8, 10, s[10:11]
	s_and_b64 s[12:13], s[0:1], s[12:13]
	v_cmp_ge_i32_e64 s[0:1], s74, v47
	v_cmp_lt_i32_e64 s[14:15], s74, v48
	v_add_u32_e32 v58, v9, v57
	v_add_u32_e32 v9, 0x7f, v23
	v_cndmask_b32_e64 v8, v8, 11, s[12:13]
	s_and_b64 s[14:15], s[0:1], s[14:15]
	v_cmp_ge_i32_e64 s[0:1], s74, v48
	v_cmp_lt_i32_e64 s[16:17], s74, v49
	v_ashrrev_i32_e32 v9, 7, v9
	v_cndmask_b32_e64 v8, v8, 12, s[14:15]
	s_and_b64 s[16:17], s[0:1], s[16:17]
	v_cmp_ge_i32_e64 s[0:1], s74, v49
	v_cmp_lt_i32_e64 s[18:19], s74, v50
	v_add_u32_e32 v59, v9, v58
	v_add_u32_e32 v9, 0x7f, v16
	v_cndmask_b32_e64 v8, v8, 13, s[16:17]
	s_and_b64 s[18:19], s[0:1], s[18:19]
	v_cmp_ge_i32_e64 s[0:1], s74, v50
	v_cmp_lt_i32_e64 s[20:21], s74, v51
	v_ashrrev_i32_e32 v9, 7, v9
	v_cndmask_b32_e64 v8, v8, 14, s[18:19]
	s_and_b64 s[20:21], s[0:1], s[20:21]
	v_cmp_ge_i32_e64 s[0:1], s74, v51
	v_cmp_lt_i32_e64 s[22:23], s74, v52
	v_add_u32_e32 v60, v9, v59
	v_add_u32_e32 v9, 0x7f, v17
	v_cndmask_b32_e64 v8, v8, 15, s[20:21]
	s_and_b64 s[22:23], s[0:1], s[22:23]
	v_cmp_ge_i32_e64 s[0:1], s74, v52
	v_cmp_lt_i32_e64 s[24:25], s74, v53
	v_ashrrev_i32_e32 v9, 7, v9
	v_cndmask_b32_e64 v8, v8, 16, s[22:23]
	s_and_b64 s[24:25], s[0:1], s[24:25]
	v_cmp_ge_i32_e64 s[0:1], s74, v53
	v_cmp_lt_i32_e64 s[26:27], s74, v54
	v_add_u32_e32 v61, v9, v60
	v_add_u32_e32 v9, 0x7f, v18
	v_cndmask_b32_e64 v8, v8, 17, s[24:25]
	s_and_b64 s[26:27], s[0:1], s[26:27]
	v_cmp_ge_i32_e64 s[0:1], s74, v54
	v_cmp_lt_i32_e64 s[28:29], s74, v55
	v_ashrrev_i32_e32 v9, 7, v9
	v_cndmask_b32_e64 v8, v8, 18, s[26:27]
	s_and_b64 s[28:29], s[0:1], s[28:29]
	v_cmp_ge_i32_e64 s[0:1], s74, v55
	v_cmp_lt_i32_e64 s[30:31], s74, v56
	v_add_u32_e32 v62, v9, v61
	v_add_u32_e32 v9, 0x7f, v19
	v_cndmask_b32_e64 v8, v8, 19, s[28:29]
	s_and_b64 s[30:31], s[0:1], s[30:31]
	v_cmp_ge_i32_e64 s[0:1], s74, v56
	v_cmp_lt_i32_e64 s[34:35], s74, v57
	v_ashrrev_i32_e32 v9, 7, v9
	v_cndmask_b32_e64 v8, v8, 20, s[30:31]
	s_and_b64 s[34:35], s[0:1], s[34:35]
	v_cmp_ge_i32_e64 s[0:1], s74, v57
	v_cmp_lt_i32_e64 s[36:37], s74, v58
	v_add_u32_e32 v63, v9, v62
	v_add_u32_e32 v9, 0x7f, v12
	v_cndmask_b32_e64 v8, v8, 21, s[34:35]
	s_and_b64 s[36:37], s[0:1], s[36:37]
	v_cmp_ge_i32_e64 s[0:1], s74, v58
	v_cmp_lt_i32_e64 s[38:39], s74, v59
	v_ashrrev_i32_e32 v9, 7, v9
	v_cndmask_b32_e64 v8, v8, 22, s[36:37]
	s_and_b64 s[38:39], s[0:1], s[38:39]
	v_cmp_ge_i32_e64 s[0:1], s74, v59
	v_cmp_lt_i32_e64 s[40:41], s74, v60
	v_add_u32_e32 v64, v9, v63
	v_add_u32_e32 v9, 0x7f, v13
	v_cndmask_b32_e64 v8, v8, 23, s[38:39]
	s_and_b64 s[40:41], s[0:1], s[40:41]
	v_cmp_ge_i32_e64 s[0:1], s74, v60
	v_cmp_lt_i32_e64 s[42:43], s74, v61
	v_ashrrev_i32_e32 v9, 7, v9
	v_cndmask_b32_e64 v8, v8, 24, s[40:41]
	s_and_b64 s[42:43], s[0:1], s[42:43]
	v_cmp_ge_i32_e64 s[0:1], s74, v61
	v_cmp_lt_i32_e64 s[44:45], s74, v62
	v_add_u32_e32 v65, v9, v64
	v_add_u32_e32 v9, 0x7f, v14
	v_cndmask_b32_e64 v8, v8, 25, s[42:43]
	s_and_b64 s[44:45], s[0:1], s[44:45]
	v_cmp_ge_i32_e64 s[0:1], s74, v62
	v_cmp_lt_i32_e64 s[46:47], s74, v63
	v_ashrrev_i32_e32 v9, 7, v9
	v_cndmask_b32_e64 v8, v8, 26, s[44:45]
	s_and_b64 s[46:47], s[0:1], s[46:47]
	v_cmp_ge_i32_e64 s[0:1], s74, v63
	v_cmp_lt_i32_e64 s[48:49], s74, v64
	v_add_u32_e32 v95, v9, v65
	v_add_u32_e32 v9, 0x7f, v15
	v_cndmask_b32_e64 v8, v8, 27, s[46:47]
	s_and_b64 s[48:49], s[0:1], s[48:49]
	v_cmp_ge_i32_e64 s[0:1], s74, v64
	v_cmp_lt_i32_e64 s[50:51], s74, v65
	v_ashrrev_i32_e32 v9, 7, v9
	v_cndmask_b32_e64 v8, v8, 28, s[48:49]
	s_and_b64 s[50:51], s[0:1], s[50:51]
	v_cmp_ge_i32_e64 s[0:1], s74, v65
	v_cmp_lt_i32_e64 s[52:53], s74, v95
	v_add_u32_e32 v9, v9, v95
	v_cndmask_b32_e64 v8, v8, 29, s[50:51]
	s_and_b64 s[52:53], s[0:1], s[52:53]
	v_cmp_ge_i32_e64 s[0:1], s74, v95
	v_cmp_lt_i32_e64 s[54:55], s74, v9
	v_cndmask_b32_e64 v8, v8, 30, s[52:53]
	s_and_b64 s[54:55], s[0:1], s[54:55]
	v_cndmask_b32_e64 v92, v8, 31, s[54:55]
	s_and_b32 s70, s59, 0x780
	s_ashr_i32 s75, s74, 31
	v_lshl_add_u64 v[28:29], s[70:71], 0, v[128:129]
	v_lshlrev_b64 v[30:31], 21, v[92:93]
	s_lshl_b64 s[0:1], s[74:75], 17
	v_lshlrev_b64 v[28:29], 10, v[28:29]
	v_lshl_add_u64 v[30:31], v[96:97], 0, v[30:31]
	v_lshl_add_u64 v[8:9], v[100:101], 0, s[0:1]
	v_lshl_add_u64 v[28:29], v[30:31], 0, v[28:29]
	s_mov_b64 s[0:1], 0x8000
	v_lshl_add_u64 v[40:41], v[8:9], 0, s[0:1]
	v_lshl_add_u64 v[38:39], v[28:29], 0, s[0:1]
	s_mov_b64 s[0:1], 0x10000
	v_lshl_add_u64 v[36:37], v[8:9], 0, s[0:1]
	v_lshl_add_u64 v[34:35], v[28:29], 0, s[0:1]
	s_mov_b64 s[0:1], 0x18000
	s_sub_i32 s2, s74, s2
	s_sub_i32 s3, s74, s3
	s_sub_i32 s33, s74, s33
	s_sub_i32 s58, s74, s58
	s_sub_i32 s60, s74, s60
	s_sub_i32 s61, s74, s61
	v_lshl_add_u64 v[32:33], v[8:9], 0, s[0:1]
	v_lshl_add_u64 v[30:31], v[28:29], 0, s[0:1]
	s_and_b64 s[0:1], s[76:77], exec
	s_cselect_b32 s64, s74, 0
	s_and_b64 s[0:1], s[78:79], exec
	s_cselect_b32 s2, s2, s64
	s_and_b64 s[0:1], s[82:83], exec
	s_cselect_b32 s2, s3, s2
	s_and_b64 s[0:1], s[84:85], exec
	s_cselect_b32 s2, s33, s2
	s_and_b64 s[0:1], s[88:89], exec
	s_cselect_b32 s2, s58, s2
	s_and_b64 s[0:1], s[90:91], exec
	s_cselect_b32 s2, s60, s2
	s_and_b64 s[0:1], vcc, exec
	s_cselect_b32 s0, s61, s2
	v_sub_u32_e32 v42, s74, v42
	v_sub_u32_e32 v106, s74, v65
	v_mov_b32_e32 v65, s0
	v_sub_u32_e32 v43, s74, v43
	v_cndmask_b32_e64 v42, v65, v42, s[4:5]
	v_sub_u32_e32 v44, s74, v44
	v_cndmask_b32_e64 v42, v42, v43, s[6:7]
	v_sub_u32_e32 v45, s74, v45
	v_cndmask_b32_e64 v42, v42, v44, s[8:9]
	v_sub_u32_e32 v46, s74, v46
	v_cndmask_b32_e64 v42, v42, v45, s[10:11]
	v_sub_u32_e32 v47, s74, v47
	v_cndmask_b32_e64 v42, v42, v46, s[12:13]
	v_sub_u32_e32 v48, s74, v48
	v_cndmask_b32_e64 v42, v42, v47, s[14:15]
	v_sub_u32_e32 v49, s74, v49
	v_cndmask_b32_e64 v42, v42, v48, s[16:17]
	v_sub_u32_e32 v50, s74, v50
	v_cndmask_b32_e64 v42, v42, v49, s[18:19]
	v_sub_u32_e32 v51, s74, v51
	v_cndmask_b32_e64 v42, v42, v50, s[20:21]
	v_sub_u32_e32 v52, s74, v52
	v_cndmask_b32_e64 v42, v42, v51, s[22:23]
	v_sub_u32_e32 v53, s74, v53
	v_cndmask_b32_e64 v42, v42, v52, s[24:25]
	v_sub_u32_e32 v54, s74, v54
	v_cndmask_b32_e64 v42, v42, v53, s[26:27]
	v_sub_u32_e32 v55, s74, v55
	v_cndmask_b32_e64 v42, v42, v54, s[28:29]
	v_sub_u32_e32 v56, s74, v56
	v_cndmask_b32_e64 v42, v42, v55, s[30:31]
	v_sub_u32_e32 v57, s74, v57
	v_cndmask_b32_e64 v42, v42, v56, s[34:35]
	v_sub_u32_e32 v58, s74, v58
	v_cndmask_b32_e64 v42, v42, v57, s[36:37]
	v_sub_u32_e32 v59, s74, v59
	v_cndmask_b32_e64 v42, v42, v58, s[38:39]
	v_sub_u32_e32 v60, s74, v60
	v_cndmask_b32_e64 v42, v42, v59, s[40:41]
	v_sub_u32_e32 v61, s74, v61
	v_cndmask_b32_e64 v42, v42, v60, s[42:43]
	v_sub_u32_e32 v62, s74, v62
	v_cndmask_b32_e64 v42, v42, v61, s[44:45]
	v_sub_u32_e32 v63, s74, v63
	v_cndmask_b32_e64 v42, v42, v62, s[46:47]
	v_sub_u32_e32 v64, s74, v64
	v_cndmask_b32_e64 v42, v42, v63, s[48:49]
	v_cndmask_b32_e64 v107, v42, v64, s[50:51]
	v_mov_b32_e32 v42, v199
	s_nop 0
	v_lshlrev_b32_e32 v44, 4, v42
	v_add_u32_e32 v45, 0x8000, v44
	v_readfirstlane_b32 s2, v44
	s_mov_b32 m0, s2
	v_readfirstlane_b32 s3, v45
	v_add_u32_e32 v45, 0x1000, v44
	s_barrier
	global_load_lds_dwordx4 v[8:9], off
	s_mov_b32 m0, s3
	v_readfirstlane_b32 s72, v45
	global_load_lds_dwordx4 v[28:29], off
	s_mov_b32 m0, s72
	v_lshrrev_b32_e32 v43, 4, v42
	global_load_lds_dwordx4 v[40:41], off
	v_add_u32_e32 v40, 0x9000, v44
	s_mov_b32 s0, 0x1ffffc0
	v_readfirstlane_b32 s73, v40
	s_mov_b32 m0, s73
	s_mov_b64 s[60:61], 0x80
	global_load_lds_dwordx4 v[38:39], off
	v_add_u32_e32 v38, 0x2000, v44
	s_nop 0
	v_readfirstlane_b32 s33, v38
	s_mov_b32 m0, s33
	s_nop 0
	global_load_lds_dwordx4 v[36:37], off
	v_add_u32_e32 v36, 0xa000, v44
	s_nop 0
	v_readfirstlane_b32 s64, v36
	s_mov_b32 m0, s64
	s_nop 0
	global_load_lds_dwordx4 v[34:35], off
	v_add_u32_e32 v34, 0x3000, v44
	s_nop 0
	v_readfirstlane_b32 s65, v34
	s_mov_b32 m0, s65
	s_nop 0
	global_load_lds_dwordx4 v[32:33], off
	v_add_u32_e32 v32, 0xb000, v44
	v_lshrrev_b32_e32 v33, 1, v42
	v_readfirstlane_b32 s58, v32
	s_mov_b32 m0, s58
	v_bfe_u32 v32, v42, 1, 3
	global_load_lds_dwordx4 v[30:31], off
	v_and_b32_e32 v30, 15, v42
	v_bfe_u32 v31, v42, 4, 2
	v_and_or_b32 v30, v33, s0, v30
	v_bitop3_b32 v33, v43, v32, 3 bitop3:0x6c
	v_bitop3_b32 v108, v31, v32, 4 bitop3:0x36
	v_add_u32_e32 v32, 0x4000, v44
	v_lshlrev_b32_e32 v90, 7, v30
	v_lshlrev_b32_e32 v30, 7, v42
	v_readfirstlane_b32 s0, v32
	v_add_u32_e32 v32, 0xc000, v44
	v_and_b32_e32 v91, 0x2780, v30
	v_lshl_add_u64 v[30:31], v[8:9], 0, s[60:61]
	s_mov_b32 m0, s0
	v_readfirstlane_b32 s1, v32
	v_add_u32_e32 v32, 0x5000, v44
	s_waitcnt vmcnt(0)
	s_waitcnt vmcnt(0) lgkmcnt(0)
	s_barrier
	global_load_lds_dwordx4 v[30:31], off
	v_lshl_add_u64 v[30:31], v[28:29], 0, s[60:61]
	s_mov_b32 m0, s1
	s_mov_b64 s[60:61], 0x8080
	v_readfirstlane_b32 s75, v32
	v_add_u32_e32 v32, 0xd000, v44
	global_load_lds_dwordx4 v[30:31], off
	v_lshl_add_u64 v[30:31], v[8:9], 0, s[60:61]
	s_mov_b32 m0, s75
	v_readfirstlane_b32 s81, v32
	v_add_u32_e32 v32, 0x6000, v44
	global_load_lds_dwordx4 v[30:31], off
	v_lshl_add_u64 v[30:31], v[28:29], 0, s[60:61]
	s_mov_b32 m0, s81
	s_mov_b64 s[60:61], 0x10080
	v_readfirstlane_b32 s86, v32
	v_add_u32_e32 v32, 0xe000, v44
	global_load_lds_dwordx4 v[30:31], off
	v_lshl_add_u64 v[30:31], v[8:9], 0, s[60:61]
	s_mov_b32 m0, s86
	v_readfirstlane_b32 s87, v32
	v_add_u32_e32 v32, 0x7000, v44
	global_load_lds_dwordx4 v[30:31], off
	v_lshl_add_u64 v[30:31], v[28:29], 0, s[60:61]
	s_mov_b32 m0, s87
	v_readfirstlane_b32 s60, v32
	v_add_u32_e32 v32, 0xf000, v44
	global_load_lds_dwordx4 v[30:31], off
	v_lshl_add_u64 v[30:31], v[8:9], 0, s[66:67]
	s_mov_b32 m0, s60
	v_readfirstlane_b32 s61, v32
	global_load_lds_dwordx4 v[30:31], off
	v_lshl_add_u64 v[30:31], v[28:29], 0, s[66:67]
	s_mov_b32 m0, s61
	v_lshlrev_b32_e32 v46, 4, v33
	global_load_lds_dwordx4 v[30:31], off
	v_or_b32_e32 v110, v90, v46
	v_or_b32_e32 v111, v91, v46
	ds_read_b128 v[30:33], v110
	ds_read_b128 v[34:37], v110 offset:2048
	ds_read_b128 v[38:41], v110 offset:4096
	ds_read_b128 v[42:45], v110 offset:6144
	ds_read_b128 v[46:49], v111 offset:32768
	ds_read_b128 v[50:53], v111 offset:34816
	ds_read_b128 v[54:57], v111 offset:36864
	ds_read_b128 v[58:61], v111 offset:38912
	v_lshlrev_b32_e32 v108, 4, v108
	s_mov_b64 s[66:67], 0x100
	v_or_b32_e32 v109, v90, v108
	v_or_b32_e32 v108, v91, v108
	v_lshl_add_u64 v[90:91], v[8:9], 0, s[66:67]
	s_mov_b32 m0, s2
	s_waitcnt lgkmcnt(0)
	v_mfma_f32_16x16x32_bf16 v[62:65], v[46:49], v[30:33], 0
	v_mfma_f32_16x16x32_bf16 v[66:69], v[50:53], v[30:33], 0
	v_mfma_f32_16x16x32_bf16 v[70:73], v[54:57], v[30:33], 0
	v_mfma_f32_16x16x32_bf16 v[30:33], v[58:61], v[30:33], 0
	v_mfma_f32_16x16x32_bf16 v[74:77], v[46:49], v[34:37], 0
	v_mfma_f32_16x16x32_bf16 v[78:81], v[50:53], v[34:37], 0
	v_mfma_f32_16x16x32_bf16 v[82:85], v[54:57], v[34:37], 0
	v_mfma_f32_16x16x32_bf16 v[34:37], v[58:61], v[34:37], 0
	v_mfma_f32_16x16x32_bf16 v[86:89], v[46:49], v[38:41], 0
	v_mfma_f32_16x16x32_bf16 v[112:115], v[50:53], v[38:41], 0
	v_mfma_f32_16x16x32_bf16 v[116:119], v[54:57], v[38:41], 0
	v_mfma_f32_16x16x32_bf16 v[38:41], v[58:61], v[38:41], 0
	v_mfma_f32_16x16x32_bf16 v[46:49], v[46:49], v[42:45], 0
	v_mfma_f32_16x16x32_bf16 v[50:53], v[50:53], v[42:45], 0
	v_mfma_f32_16x16x32_bf16 v[54:57], v[54:57], v[42:45], 0
	v_mfma_f32_16x16x32_bf16 v[42:45], v[58:61], v[42:45], 0
	ds_read_b128 v[58:61], v109
	ds_read_b128 v[120:123], v109 offset:2048
	ds_read_b128 v[124:127], v109 offset:4096
	ds_read_b128 v[130:133], v109 offset:6144
	ds_read_b128 v[134:137], v108 offset:32768
	ds_read_b128 v[138:141], v108 offset:34816
	ds_read_b128 v[142:145], v108 offset:36864
	ds_read_b128 v[146:149], v108 offset:38912
	s_waitcnt vmcnt(0)
	s_waitcnt vmcnt(0) lgkmcnt(0)
	s_barrier
	global_load_lds_dwordx4 v[90:91], off
	v_lshl_add_u64 v[90:91], v[28:29], 0, s[66:67]
	s_mov_b32 m0, s3
	s_mov_b64 s[66:67], 0x8100
	global_load_lds_dwordx4 v[90:91], off
	v_lshl_add_u64 v[90:91], v[8:9], 0, s[66:67]
	s_mov_b32 m0, s72
	v_mfma_f32_16x16x32_bf16 v[62:65], v[134:137], v[58:61], v[62:65]
	global_load_lds_dwordx4 v[90:91], off
	v_lshl_add_u64 v[90:91], v[28:29], 0, s[66:67]
	s_mov_b32 m0, s73
	s_mov_b64 s[66:67], 0x10100
	global_load_lds_dwordx4 v[90:91], off
	v_lshl_add_u64 v[90:91], v[8:9], 0, s[66:67]
	s_mov_b32 m0, s33
	v_mfma_f32_16x16x32_bf16 v[66:69], v[138:141], v[58:61], v[66:69]
	global_load_lds_dwordx4 v[90:91], off
	v_lshl_add_u64 v[90:91], v[28:29], 0, s[66:67]
	s_mov_b32 m0, s64
	s_mov_b64 s[66:67], 0x18100
	global_load_lds_dwordx4 v[90:91], off
	v_lshl_add_u64 v[90:91], v[8:9], 0, s[66:67]
	s_mov_b32 m0, s65
	v_mfma_f32_16x16x32_bf16 v[70:73], v[142:145], v[58:61], v[70:73]
	global_load_lds_dwordx4 v[90:91], off
	v_lshl_add_u64 v[90:91], v[28:29], 0, s[66:67]
	s_mov_b32 m0, s58
	v_mfma_f32_16x16x32_bf16 v[30:33], v[146:149], v[58:61], v[30:33]
	global_load_lds_dwordx4 v[90:91], off
	s_mov_b64 s[66:67], 0x180
	v_mfma_f32_16x16x32_bf16 v[58:61], v[134:137], v[120:123], v[74:77]
	v_lshl_add_u64 v[90:91], v[8:9], 0, s[66:67]
	s_mov_b32 m0, s0
	v_mfma_f32_16x16x32_bf16 v[74:77], v[138:141], v[120:123], v[78:81]
	v_mfma_f32_16x16x32_bf16 v[78:81], v[142:145], v[120:123], v[82:85]
	v_mfma_f32_16x16x32_bf16 v[34:37], v[146:149], v[120:123], v[34:37]
	v_mfma_f32_16x16x32_bf16 v[82:85], v[134:137], v[124:127], v[86:89]
	v_mfma_f32_16x16x32_bf16 v[86:89], v[138:141], v[124:127], v[112:115]
	v_mfma_f32_16x16x32_bf16 v[112:115], v[142:145], v[124:127], v[116:119]
	v_mfma_f32_16x16x32_bf16 v[38:41], v[146:149], v[124:127], v[38:41]
	v_mfma_f32_16x16x32_bf16 v[46:49], v[134:137], v[130:133], v[46:49]
	v_mfma_f32_16x16x32_bf16 v[50:53], v[138:141], v[130:133], v[50:53]
	v_mfma_f32_16x16x32_bf16 v[54:57], v[142:145], v[130:133], v[54:57]
	v_mfma_f32_16x16x32_bf16 v[42:45], v[146:149], v[130:133], v[42:45]
	ds_read_b128 v[134:137], v111 offset:49152
	ds_read_b128 v[138:141], v111 offset:51200
	ds_read_b128 v[142:145], v111 offset:53248
	ds_read_b128 v[146:149], v111 offset:55296
	ds_read_b128 v[116:119], v110 offset:16384
	ds_read_b128 v[120:123], v110 offset:18432
	ds_read_b128 v[124:127], v110 offset:20480
	ds_read_b128 v[130:133], v110 offset:22528
	s_waitcnt lgkmcnt(3)
	v_mfma_f32_16x16x32_bf16 v[62:65], v[134:137], v[116:119], v[62:65]
	v_mfma_f32_16x16x32_bf16 v[66:69], v[138:141], v[116:119], v[66:69]
	v_mfma_f32_16x16x32_bf16 v[70:73], v[142:145], v[116:119], v[70:73]
	v_mfma_f32_16x16x32_bf16 v[30:33], v[146:149], v[116:119], v[30:33]
	s_waitcnt lgkmcnt(2)
	v_mfma_f32_16x16x32_bf16 v[58:61], v[134:137], v[120:123], v[58:61]
	v_mfma_f32_16x16x32_bf16 v[74:77], v[138:141], v[120:123], v[74:77]
	v_mfma_f32_16x16x32_bf16 v[78:81], v[142:145], v[120:123], v[78:81]
	v_mfma_f32_16x16x32_bf16 v[34:37], v[146:149], v[120:123], v[34:37]
	s_waitcnt lgkmcnt(1)
	v_mfma_f32_16x16x32_bf16 v[82:85], v[134:137], v[124:127], v[82:85]
	v_mfma_f32_16x16x32_bf16 v[86:89], v[138:141], v[124:127], v[86:89]
	v_mfma_f32_16x16x32_bf16 v[112:115], v[142:145], v[124:127], v[112:115]
	v_mfma_f32_16x16x32_bf16 v[38:41], v[146:149], v[124:127], v[38:41]
	s_waitcnt lgkmcnt(0)
	v_mfma_f32_16x16x32_bf16 v[46:49], v[134:137], v[130:133], v[46:49]
	v_mfma_f32_16x16x32_bf16 v[50:53], v[138:141], v[130:133], v[50:53]
	v_mfma_f32_16x16x32_bf16 v[54:57], v[142:145], v[130:133], v[54:57]
	v_mfma_f32_16x16x32_bf16 v[42:45], v[146:149], v[130:133], v[42:45]
	ds_read_b128 v[116:119], v109 offset:16384
	ds_read_b128 v[120:123], v109 offset:18432
	ds_read_b128 v[124:127], v109 offset:20480
	ds_read_b128 v[130:133], v109 offset:22528
	ds_read_b128 v[134:137], v108 offset:49152
	ds_read_b128 v[138:141], v108 offset:51200
	ds_read_b128 v[142:145], v108 offset:53248
	ds_read_b128 v[146:149], v108 offset:55296
	s_waitcnt vmcnt(0)
	s_waitcnt vmcnt(0) lgkmcnt(0)
	s_barrier
	global_load_lds_dwordx4 v[90:91], off
	v_lshl_add_u64 v[90:91], v[28:29], 0, s[66:67]
	s_mov_b32 m0, s1
	s_mov_b64 s[66:67], 0x8180
	global_load_lds_dwordx4 v[90:91], off
	v_lshl_add_u64 v[90:91], v[8:9], 0, s[66:67]
	s_mov_b32 m0, s75
	v_mfma_f32_16x16x32_bf16 v[62:65], v[134:137], v[116:119], v[62:65]
	global_load_lds_dwordx4 v[90:91], off
	v_lshl_add_u64 v[90:91], v[28:29], 0, s[66:67]
	s_mov_b32 m0, s81
	s_mov_b64 s[66:67], 0x10180
	global_load_lds_dwordx4 v[90:91], off
	v_lshl_add_u64 v[90:91], v[8:9], 0, s[66:67]
	s_mov_b32 m0, s86
	v_mfma_f32_16x16x32_bf16 v[66:69], v[138:141], v[116:119], v[66:69]
	global_load_lds_dwordx4 v[90:91], off
	v_lshl_add_u64 v[90:91], v[28:29], 0, s[66:67]
	s_mov_b32 m0, s87
	s_mov_b64 s[66:67], 0x18180
	global_load_lds_dwordx4 v[90:91], off
	v_lshl_add_u64 v[90:91], v[8:9], 0, s[66:67]
	s_mov_b32 m0, s60
	v_mfma_f32_16x16x32_bf16 v[70:73], v[142:145], v[116:119], v[70:73]
	global_load_lds_dwordx4 v[90:91], off
	v_lshl_add_u64 v[90:91], v[28:29], 0, s[66:67]
	s_mov_b32 m0, s61
	v_mfma_f32_16x16x32_bf16 v[30:33], v[146:149], v[116:119], v[30:33]
	global_load_lds_dwordx4 v[90:91], off
	s_mov_b64 s[66:67], 0x200
	v_mfma_f32_16x16x32_bf16 v[58:61], v[134:137], v[120:123], v[58:61]
	v_lshl_add_u64 v[90:91], v[8:9], 0, s[66:67]
	s_mov_b32 m0, s2
	v_mfma_f32_16x16x32_bf16 v[74:77], v[138:141], v[120:123], v[74:77]
	v_mfma_f32_16x16x32_bf16 v[78:81], v[142:145], v[120:123], v[78:81]
	v_mfma_f32_16x16x32_bf16 v[34:37], v[146:149], v[120:123], v[34:37]
	v_mfma_f32_16x16x32_bf16 v[82:85], v[134:137], v[124:127], v[82:85]
	v_mfma_f32_16x16x32_bf16 v[86:89], v[138:141], v[124:127], v[86:89]
	v_mfma_f32_16x16x32_bf16 v[112:115], v[142:145], v[124:127], v[112:115]
	v_mfma_f32_16x16x32_bf16 v[38:41], v[146:149], v[124:127], v[38:41]
	v_mfma_f32_16x16x32_bf16 v[46:49], v[134:137], v[130:133], v[46:49]
	v_mfma_f32_16x16x32_bf16 v[50:53], v[138:141], v[130:133], v[50:53]
	v_mfma_f32_16x16x32_bf16 v[54:57], v[142:145], v[130:133], v[54:57]
	v_mfma_f32_16x16x32_bf16 v[42:45], v[146:149], v[130:133], v[42:45]
	ds_read_b128 v[134:137], v111 offset:32768
	ds_read_b128 v[138:141], v111 offset:34816
	ds_read_b128 v[142:145], v111 offset:36864
	ds_read_b128 v[146:149], v111 offset:38912
	ds_read_b128 v[116:119], v110
	ds_read_b128 v[120:123], v110 offset:2048
	ds_read_b128 v[124:127], v110 offset:4096
	ds_read_b128 v[130:133], v110 offset:6144
	s_waitcnt lgkmcnt(3)
	v_mfma_f32_16x16x32_bf16 v[62:65], v[134:137], v[116:119], v[62:65]
	v_mfma_f32_16x16x32_bf16 v[66:69], v[138:141], v[116:119], v[66:69]
	v_mfma_f32_16x16x32_bf16 v[70:73], v[142:145], v[116:119], v[70:73]
	v_mfma_f32_16x16x32_bf16 v[30:33], v[146:149], v[116:119], v[30:33]
	s_waitcnt lgkmcnt(2)
	v_mfma_f32_16x16x32_bf16 v[58:61], v[134:137], v[120:123], v[58:61]
	v_mfma_f32_16x16x32_bf16 v[74:77], v[138:141], v[120:123], v[74:77]
	v_mfma_f32_16x16x32_bf16 v[78:81], v[142:145], v[120:123], v[78:81]
	v_mfma_f32_16x16x32_bf16 v[34:37], v[146:149], v[120:123], v[34:37]
	s_waitcnt lgkmcnt(1)
	v_mfma_f32_16x16x32_bf16 v[82:85], v[134:137], v[124:127], v[82:85]
	v_mfma_f32_16x16x32_bf16 v[86:89], v[138:141], v[124:127], v[86:89]
	v_mfma_f32_16x16x32_bf16 v[112:115], v[142:145], v[124:127], v[112:115]
	v_mfma_f32_16x16x32_bf16 v[38:41], v[146:149], v[124:127], v[38:41]
	s_waitcnt lgkmcnt(0)
	v_mfma_f32_16x16x32_bf16 v[46:49], v[134:137], v[130:133], v[46:49]
	v_mfma_f32_16x16x32_bf16 v[50:53], v[138:141], v[130:133], v[50:53]
	v_mfma_f32_16x16x32_bf16 v[54:57], v[142:145], v[130:133], v[54:57]
	v_mfma_f32_16x16x32_bf16 v[42:45], v[146:149], v[130:133], v[42:45]
	ds_read_b128 v[116:119], v109
	ds_read_b128 v[120:123], v109 offset:2048
	ds_read_b128 v[124:127], v109 offset:4096
	ds_read_b128 v[130:133], v109 offset:6144
	ds_read_b128 v[134:137], v108 offset:32768
	ds_read_b128 v[138:141], v108 offset:34816
	ds_read_b128 v[142:145], v108 offset:36864
	ds_read_b128 v[146:149], v108 offset:38912
	s_waitcnt vmcnt(0)
	s_waitcnt vmcnt(0) lgkmcnt(0)
	s_barrier
	global_load_lds_dwordx4 v[90:91], off
	v_lshl_add_u64 v[90:91], v[28:29], 0, s[66:67]
	s_mov_b32 m0, s3
	s_mov_b64 s[66:67], 0x8200
	global_load_lds_dwordx4 v[90:91], off
	v_lshl_add_u64 v[90:91], v[8:9], 0, s[66:67]
	s_mov_b32 m0, s72
	v_mfma_f32_16x16x32_bf16 v[62:65], v[134:137], v[116:119], v[62:65]
	global_load_lds_dwordx4 v[90:91], off
	v_lshl_add_u64 v[90:91], v[28:29], 0, s[66:67]
	s_mov_b32 m0, s73
	s_mov_b64 s[66:67], 0x10200
	global_load_lds_dwordx4 v[90:91], off
	v_lshl_add_u64 v[90:91], v[8:9], 0, s[66:67]
	s_mov_b32 m0, s33
	v_mfma_f32_16x16x32_bf16 v[66:69], v[138:141], v[116:119], v[66:69]
	global_load_lds_dwordx4 v[90:91], off
	v_lshl_add_u64 v[90:91], v[28:29], 0, s[66:67]
	s_mov_b32 m0, s64
	s_mov_b64 s[66:67], 0x18200
	global_load_lds_dwordx4 v[90:91], off
	v_lshl_add_u64 v[90:91], v[8:9], 0, s[66:67]
	s_mov_b32 m0, s65
	v_mfma_f32_16x16x32_bf16 v[70:73], v[142:145], v[116:119], v[70:73]
	global_load_lds_dwordx4 v[90:91], off
	v_lshl_add_u64 v[90:91], v[28:29], 0, s[66:67]
	s_mov_b32 m0, s58
	v_mfma_f32_16x16x32_bf16 v[30:33], v[146:149], v[116:119], v[30:33]
	global_load_lds_dwordx4 v[90:91], off
	s_mov_b64 s[66:67], 0x280
	v_mfma_f32_16x16x32_bf16 v[58:61], v[134:137], v[120:123], v[58:61]
	v_lshl_add_u64 v[90:91], v[8:9], 0, s[66:67]
	s_mov_b32 m0, s0
	v_mfma_f32_16x16x32_bf16 v[74:77], v[138:141], v[120:123], v[74:77]
	v_mfma_f32_16x16x32_bf16 v[78:81], v[142:145], v[120:123], v[78:81]
	v_mfma_f32_16x16x32_bf16 v[34:37], v[146:149], v[120:123], v[34:37]
	v_mfma_f32_16x16x32_bf16 v[82:85], v[134:137], v[124:127], v[82:85]
	v_mfma_f32_16x16x32_bf16 v[86:89], v[138:141], v[124:127], v[86:89]
	v_mfma_f32_16x16x32_bf16 v[112:115], v[142:145], v[124:127], v[112:115]
	v_mfma_f32_16x16x32_bf16 v[38:41], v[146:149], v[124:127], v[38:41]
	v_mfma_f32_16x16x32_bf16 v[46:49], v[134:137], v[130:133], v[46:49]
	v_mfma_f32_16x16x32_bf16 v[50:53], v[138:141], v[130:133], v[50:53]
	v_mfma_f32_16x16x32_bf16 v[54:57], v[142:145], v[130:133], v[54:57]
	v_mfma_f32_16x16x32_bf16 v[42:45], v[146:149], v[130:133], v[42:45]
	ds_read_b128 v[134:137], v111 offset:49152
	ds_read_b128 v[138:141], v111 offset:51200
	ds_read_b128 v[142:145], v111 offset:53248
	ds_read_b128 v[146:149], v111 offset:55296
	ds_read_b128 v[116:119], v110 offset:16384
	ds_read_b128 v[120:123], v110 offset:18432
	ds_read_b128 v[124:127], v110 offset:20480
	ds_read_b128 v[130:133], v110 offset:22528
	s_waitcnt lgkmcnt(3)
	v_mfma_f32_16x16x32_bf16 v[62:65], v[134:137], v[116:119], v[62:65]
	v_mfma_f32_16x16x32_bf16 v[66:69], v[138:141], v[116:119], v[66:69]
	v_mfma_f32_16x16x32_bf16 v[70:73], v[142:145], v[116:119], v[70:73]
	v_mfma_f32_16x16x32_bf16 v[30:33], v[146:149], v[116:119], v[30:33]
	s_waitcnt lgkmcnt(2)
	v_mfma_f32_16x16x32_bf16 v[58:61], v[134:137], v[120:123], v[58:61]
	v_mfma_f32_16x16x32_bf16 v[74:77], v[138:141], v[120:123], v[74:77]
	v_mfma_f32_16x16x32_bf16 v[78:81], v[142:145], v[120:123], v[78:81]
	v_mfma_f32_16x16x32_bf16 v[34:37], v[146:149], v[120:123], v[34:37]
	s_waitcnt lgkmcnt(1)
	v_mfma_f32_16x16x32_bf16 v[82:85], v[134:137], v[124:127], v[82:85]
	v_mfma_f32_16x16x32_bf16 v[86:89], v[138:141], v[124:127], v[86:89]
	v_mfma_f32_16x16x32_bf16 v[112:115], v[142:145], v[124:127], v[112:115]
	v_mfma_f32_16x16x32_bf16 v[38:41], v[146:149], v[124:127], v[38:41]
	s_waitcnt lgkmcnt(0)
	v_mfma_f32_16x16x32_bf16 v[46:49], v[134:137], v[130:133], v[46:49]
	v_mfma_f32_16x16x32_bf16 v[50:53], v[138:141], v[130:133], v[50:53]
	v_mfma_f32_16x16x32_bf16 v[54:57], v[142:145], v[130:133], v[54:57]
	v_mfma_f32_16x16x32_bf16 v[42:45], v[146:149], v[130:133], v[42:45]
	ds_read_b128 v[116:119], v109 offset:16384
	ds_read_b128 v[120:123], v109 offset:18432
	ds_read_b128 v[124:127], v109 offset:20480
	ds_read_b128 v[130:133], v109 offset:22528
	ds_read_b128 v[134:137], v108 offset:49152
	ds_read_b128 v[138:141], v108 offset:51200
	ds_read_b128 v[142:145], v108 offset:53248
	ds_read_b128 v[146:149], v108 offset:55296
	s_waitcnt vmcnt(0)
	s_waitcnt vmcnt(0) lgkmcnt(0)
	s_barrier
	global_load_lds_dwordx4 v[90:91], off
	v_lshl_add_u64 v[90:91], v[28:29], 0, s[66:67]
	s_mov_b32 m0, s1
	s_mov_b64 s[66:67], 0x8280
	global_load_lds_dwordx4 v[90:91], off
	v_lshl_add_u64 v[90:91], v[8:9], 0, s[66:67]
	s_mov_b32 m0, s75
	v_mfma_f32_16x16x32_bf16 v[62:65], v[134:137], v[116:119], v[62:65]
	global_load_lds_dwordx4 v[90:91], off
	v_lshl_add_u64 v[90:91], v[28:29], 0, s[66:67]
	s_mov_b32 m0, s81
	s_mov_b64 s[66:67], 0x10280
	global_load_lds_dwordx4 v[90:91], off
	v_lshl_add_u64 v[90:91], v[8:9], 0, s[66:67]
	s_mov_b32 m0, s86
	v_mfma_f32_16x16x32_bf16 v[66:69], v[138:141], v[116:119], v[66:69]
	global_load_lds_dwordx4 v[90:91], off
	v_lshl_add_u64 v[90:91], v[28:29], 0, s[66:67]
	s_mov_b32 m0, s87
	s_mov_b64 s[66:67], 0x18280
	global_load_lds_dwordx4 v[90:91], off
	v_lshl_add_u64 v[90:91], v[8:9], 0, s[66:67]
	s_mov_b32 m0, s60
	v_mfma_f32_16x16x32_bf16 v[70:73], v[142:145], v[116:119], v[70:73]
	global_load_lds_dwordx4 v[90:91], off
	v_lshl_add_u64 v[90:91], v[28:29], 0, s[66:67]
	s_mov_b32 m0, s61
	v_mfma_f32_16x16x32_bf16 v[30:33], v[146:149], v[116:119], v[30:33]
	global_load_lds_dwordx4 v[90:91], off
	s_mov_b64 s[66:67], 0x300
	v_mfma_f32_16x16x32_bf16 v[58:61], v[134:137], v[120:123], v[58:61]
	v_lshl_add_u64 v[90:91], v[8:9], 0, s[66:67]
	s_mov_b32 m0, s2
	v_mfma_f32_16x16x32_bf16 v[74:77], v[138:141], v[120:123], v[74:77]
	v_mfma_f32_16x16x32_bf16 v[78:81], v[142:145], v[120:123], v[78:81]
	v_mfma_f32_16x16x32_bf16 v[34:37], v[146:149], v[120:123], v[34:37]
	v_mfma_f32_16x16x32_bf16 v[82:85], v[134:137], v[124:127], v[82:85]
	v_mfma_f32_16x16x32_bf16 v[86:89], v[138:141], v[124:127], v[86:89]
	v_mfma_f32_16x16x32_bf16 v[112:115], v[142:145], v[124:127], v[112:115]
	v_mfma_f32_16x16x32_bf16 v[38:41], v[146:149], v[124:127], v[38:41]
	v_mfma_f32_16x16x32_bf16 v[46:49], v[134:137], v[130:133], v[46:49]
	v_mfma_f32_16x16x32_bf16 v[50:53], v[138:141], v[130:133], v[50:53]
	v_mfma_f32_16x16x32_bf16 v[54:57], v[142:145], v[130:133], v[54:57]
	v_mfma_f32_16x16x32_bf16 v[42:45], v[146:149], v[130:133], v[42:45]
	ds_read_b128 v[134:137], v111 offset:32768
	ds_read_b128 v[138:141], v111 offset:34816
	ds_read_b128 v[142:145], v111 offset:36864
	ds_read_b128 v[146:149], v111 offset:38912
	ds_read_b128 v[116:119], v110
	ds_read_b128 v[120:123], v110 offset:2048
	ds_read_b128 v[124:127], v110 offset:4096
	ds_read_b128 v[130:133], v110 offset:6144
	s_waitcnt lgkmcnt(3)
	v_mfma_f32_16x16x32_bf16 v[62:65], v[134:137], v[116:119], v[62:65]
	v_mfma_f32_16x16x32_bf16 v[66:69], v[138:141], v[116:119], v[66:69]
	v_mfma_f32_16x16x32_bf16 v[70:73], v[142:145], v[116:119], v[70:73]
	v_mfma_f32_16x16x32_bf16 v[30:33], v[146:149], v[116:119], v[30:33]
	s_waitcnt lgkmcnt(2)
	v_mfma_f32_16x16x32_bf16 v[58:61], v[134:137], v[120:123], v[58:61]
	v_mfma_f32_16x16x32_bf16 v[74:77], v[138:141], v[120:123], v[74:77]
	v_mfma_f32_16x16x32_bf16 v[78:81], v[142:145], v[120:123], v[78:81]
	v_mfma_f32_16x16x32_bf16 v[34:37], v[146:149], v[120:123], v[34:37]
	s_waitcnt lgkmcnt(1)
	v_mfma_f32_16x16x32_bf16 v[82:85], v[134:137], v[124:127], v[82:85]
	v_mfma_f32_16x16x32_bf16 v[86:89], v[138:141], v[124:127], v[86:89]
	v_mfma_f32_16x16x32_bf16 v[112:115], v[142:145], v[124:127], v[112:115]
	v_mfma_f32_16x16x32_bf16 v[38:41], v[146:149], v[124:127], v[38:41]
	s_waitcnt lgkmcnt(0)
	v_mfma_f32_16x16x32_bf16 v[46:49], v[134:137], v[130:133], v[46:49]
	v_mfma_f32_16x16x32_bf16 v[50:53], v[138:141], v[130:133], v[50:53]
	v_mfma_f32_16x16x32_bf16 v[54:57], v[142:145], v[130:133], v[54:57]
	v_mfma_f32_16x16x32_bf16 v[42:45], v[146:149], v[130:133], v[42:45]
	ds_read_b128 v[116:119], v109
	ds_read_b128 v[120:123], v109 offset:2048
	ds_read_b128 v[124:127], v109 offset:4096
	ds_read_b128 v[130:133], v109 offset:6144
	ds_read_b128 v[134:137], v108 offset:32768
	ds_read_b128 v[138:141], v108 offset:34816
	ds_read_b128 v[142:145], v108 offset:36864
	ds_read_b128 v[146:149], v108 offset:38912
	s_waitcnt vmcnt(0)
	s_waitcnt vmcnt(0) lgkmcnt(0)
	s_barrier
	global_load_lds_dwordx4 v[90:91], off
	v_lshl_add_u64 v[90:91], v[28:29], 0, s[66:67]
	s_mov_b32 m0, s3
	s_mov_b64 s[2:3], 0x8300
	global_load_lds_dwordx4 v[90:91], off
	v_lshl_add_u64 v[90:91], v[8:9], 0, s[2:3]
	s_mov_b32 m0, s72
	v_mfma_f32_16x16x32_bf16 v[62:65], v[134:137], v[116:119], v[62:65]
	global_load_lds_dwordx4 v[90:91], off
	v_lshl_add_u64 v[90:91], v[28:29], 0, s[2:3]
	s_mov_b32 m0, s73
	s_mov_b64 s[2:3], 0x10300
	global_load_lds_dwordx4 v[90:91], off
	v_lshl_add_u64 v[90:91], v[8:9], 0, s[2:3]
	s_mov_b32 m0, s33
	v_mfma_f32_16x16x32_bf16 v[66:69], v[138:141], v[116:119], v[66:69]
	global_load_lds_dwordx4 v[90:91], off
	v_lshl_add_u64 v[90:91], v[28:29], 0, s[2:3]
	s_mov_b32 m0, s64
	s_mov_b64 s[2:3], 0x18300
	global_load_lds_dwordx4 v[90:91], off
	v_lshl_add_u64 v[90:91], v[8:9], 0, s[2:3]
	s_mov_b32 m0, s65
	v_mfma_f32_16x16x32_bf16 v[70:73], v[142:145], v[116:119], v[70:73]
	global_load_lds_dwordx4 v[90:91], off
	v_lshl_add_u64 v[90:91], v[28:29], 0, s[2:3]
	s_mov_b32 m0, s58
	v_mfma_f32_16x16x32_bf16 v[30:33], v[146:149], v[116:119], v[30:33]
	global_load_lds_dwordx4 v[90:91], off
	s_mov_b64 s[2:3], 0x380
	v_mfma_f32_16x16x32_bf16 v[58:61], v[134:137], v[120:123], v[58:61]
	v_lshl_add_u64 v[90:91], v[8:9], 0, s[2:3]
	s_mov_b32 m0, s0
	v_mfma_f32_16x16x32_bf16 v[74:77], v[138:141], v[120:123], v[74:77]
	v_mfma_f32_16x16x32_bf16 v[78:81], v[142:145], v[120:123], v[78:81]
	v_mfma_f32_16x16x32_bf16 v[34:37], v[146:149], v[120:123], v[34:37]
	v_mfma_f32_16x16x32_bf16 v[82:85], v[134:137], v[124:127], v[82:85]
	v_mfma_f32_16x16x32_bf16 v[86:89], v[138:141], v[124:127], v[86:89]
	v_mfma_f32_16x16x32_bf16 v[112:115], v[142:145], v[124:127], v[112:115]
	v_mfma_f32_16x16x32_bf16 v[38:41], v[146:149], v[124:127], v[38:41]
	v_mfma_f32_16x16x32_bf16 v[46:49], v[134:137], v[130:133], v[46:49]
	v_mfma_f32_16x16x32_bf16 v[50:53], v[138:141], v[130:133], v[50:53]
	v_mfma_f32_16x16x32_bf16 v[54:57], v[142:145], v[130:133], v[54:57]
	v_mfma_f32_16x16x32_bf16 v[42:45], v[146:149], v[130:133], v[42:45]
	ds_read_b128 v[134:137], v111 offset:49152
	ds_read_b128 v[138:141], v111 offset:51200
	ds_read_b128 v[142:145], v111 offset:53248
	ds_read_b128 v[146:149], v111 offset:55296
	ds_read_b128 v[116:119], v110 offset:16384
	ds_read_b128 v[120:123], v110 offset:18432
	ds_read_b128 v[124:127], v110 offset:20480
	ds_read_b128 v[130:133], v110 offset:22528
	s_waitcnt lgkmcnt(3)
	v_mfma_f32_16x16x32_bf16 v[62:65], v[134:137], v[116:119], v[62:65]
	v_mfma_f32_16x16x32_bf16 v[66:69], v[138:141], v[116:119], v[66:69]
	v_mfma_f32_16x16x32_bf16 v[70:73], v[142:145], v[116:119], v[70:73]
	v_mfma_f32_16x16x32_bf16 v[30:33], v[146:149], v[116:119], v[30:33]
	s_waitcnt lgkmcnt(2)
	v_mfma_f32_16x16x32_bf16 v[58:61], v[134:137], v[120:123], v[58:61]
	v_mfma_f32_16x16x32_bf16 v[74:77], v[138:141], v[120:123], v[74:77]
	v_mfma_f32_16x16x32_bf16 v[78:81], v[142:145], v[120:123], v[78:81]
	v_mfma_f32_16x16x32_bf16 v[34:37], v[146:149], v[120:123], v[34:37]
	s_waitcnt lgkmcnt(1)
	v_mfma_f32_16x16x32_bf16 v[82:85], v[134:137], v[124:127], v[82:85]
	v_mfma_f32_16x16x32_bf16 v[86:89], v[138:141], v[124:127], v[86:89]
	v_mfma_f32_16x16x32_bf16 v[112:115], v[142:145], v[124:127], v[112:115]
	v_mfma_f32_16x16x32_bf16 v[38:41], v[146:149], v[124:127], v[38:41]
	s_waitcnt lgkmcnt(0)
	v_mfma_f32_16x16x32_bf16 v[46:49], v[134:137], v[130:133], v[46:49]
	v_mfma_f32_16x16x32_bf16 v[50:53], v[138:141], v[130:133], v[50:53]
	v_mfma_f32_16x16x32_bf16 v[54:57], v[142:145], v[130:133], v[54:57]
	v_mfma_f32_16x16x32_bf16 v[42:45], v[146:149], v[130:133], v[42:45]
	ds_read_b128 v[116:119], v109 offset:16384
	ds_read_b128 v[120:123], v109 offset:18432
	ds_read_b128 v[124:127], v109 offset:20480
	ds_read_b128 v[130:133], v109 offset:22528
	ds_read_b128 v[134:137], v108 offset:49152
	ds_read_b128 v[138:141], v108 offset:51200
	ds_read_b128 v[142:145], v108 offset:53248
	ds_read_b128 v[146:149], v108 offset:55296
	s_waitcnt vmcnt(0)
	s_waitcnt vmcnt(0) lgkmcnt(0)
	s_barrier
	global_load_lds_dwordx4 v[90:91], off
	v_lshl_add_u64 v[90:91], v[28:29], 0, s[2:3]
	s_mov_b32 m0, s1
	s_mov_b64 s[0:1], 0x8380
	global_load_lds_dwordx4 v[90:91], off
	v_lshl_add_u64 v[90:91], v[8:9], 0, s[0:1]
	s_mov_b32 m0, s75
	v_mfma_f32_16x16x32_bf16 v[62:65], v[134:137], v[116:119], v[62:65]
	global_load_lds_dwordx4 v[90:91], off
	v_lshl_add_u64 v[90:91], v[28:29], 0, s[0:1]
	s_mov_b32 m0, s81
	s_mov_b64 s[0:1], 0x10380
	global_load_lds_dwordx4 v[90:91], off
	v_lshl_add_u64 v[90:91], v[8:9], 0, s[0:1]
	s_mov_b32 m0, s86
	v_mfma_f32_16x16x32_bf16 v[66:69], v[138:141], v[116:119], v[66:69]
	global_load_lds_dwordx4 v[90:91], off
	v_lshl_add_u64 v[90:91], v[28:29], 0, s[0:1]
	s_mov_b32 m0, s87
	s_mov_b64 s[0:1], 0x18380
	global_load_lds_dwordx4 v[90:91], off
	v_lshl_add_u64 v[8:9], v[8:9], 0, s[0:1]
	s_mov_b32 m0, s60
	v_mfma_f32_16x16x32_bf16 v[70:73], v[142:145], v[116:119], v[70:73]
	global_load_lds_dwordx4 v[8:9], off
	v_lshl_add_u64 v[8:9], v[28:29], 0, s[0:1]
	s_mov_b32 m0, s61
	s_and_b64 s[0:1], s[76:77], exec
	global_load_lds_dwordx4 v[8:9], off
	s_cselect_b32 s2, s80, 0
	s_and_b64 s[0:1], s[78:79], exec
	s_cselect_b32 s2, s57, s2
	s_and_b64 s[0:1], s[82:83], exec
	s_cselect_b32 s2, s56, s2
	s_and_b64 s[0:1], s[84:85], exec
	s_cselect_b32 s2, s97, s2
	s_and_b64 s[0:1], s[88:89], exec
	s_cselect_b32 s2, s96, s2
	s_and_b64 s[0:1], s[90:91], exec
	s_cselect_b32 s0, s63, s2
	v_mov_b32_e32 v8, s0
	v_cndmask_b32_e32 v8, v8, v10, vcc
	v_cndmask_b32_e64 v8, v8, v11, s[4:5]
	v_cndmask_b32_e64 v4, v8, v4, s[6:7]
	v_cndmask_b32_e64 v4, v4, v5, s[8:9]
	v_cndmask_b32_e64 v4, v4, v6, s[10:11]
	v_cndmask_b32_e64 v4, v4, v7, s[12:13]
	v_cndmask_b32_e64 v0, v4, v0, s[14:15]
	v_cndmask_b32_e64 v0, v0, v1, s[16:17]
	v_cndmask_b32_e64 v0, v0, v2, s[18:19]
	v_cndmask_b32_e64 v0, v0, v3, s[20:21]
	v_cndmask_b32_e64 v0, v0, v24, s[22:23]
	v_cndmask_b32_e64 v0, v0, v25, s[24:25]
	v_cndmask_b32_e64 v0, v0, v26, s[26:27]
	v_cndmask_b32_e64 v0, v0, v27, s[28:29]
	v_cndmask_b32_e64 v0, v0, v20, s[30:31]
	v_cndmask_b32_e64 v0, v0, v21, s[34:35]
	v_mfma_f32_16x16x32_bf16 v[30:33], v[146:149], v[116:119], v[30:33]
	v_cndmask_b32_e64 v0, v0, v22, s[36:37]
	v_cndmask_b32_e64 v0, v0, v23, s[38:39]
	v_cndmask_b32_e64 v0, v0, v16, s[40:41]
	v_mfma_f32_16x16x32_bf16 v[58:61], v[134:137], v[120:123], v[58:61]
	v_cndmask_b32_e64 v0, v0, v17, s[42:43]
	v_cndmask_b32_e64 v0, v0, v18, s[44:45]
	v_cndmask_b32_e64 v0, v0, v19, s[46:47]
	v_mfma_f32_16x16x32_bf16 v[74:77], v[138:141], v[120:123], v[74:77]
	v_cndmask_b32_e64 v0, v0, v12, s[48:49]
	v_cndmask_b32_e64 v0, v0, v13, s[50:51]
	v_cndmask_b32_e64 v0, v0, v14, s[52:53]
	v_mfma_f32_16x16x32_bf16 v[78:81], v[142:145], v[120:123], v[78:81]
	v_cndmask_b32_e64 v1, v107, v106, s[52:53]
	s_lshl_b32 s70, s70, 1
	v_mfma_f32_16x16x32_bf16 v[34:37], v[146:149], v[120:123], v[34:37]
	v_mfma_f32_16x16x32_bf16 v[82:85], v[134:137], v[124:127], v[82:85]
	v_mfma_f32_16x16x32_bf16 v[86:89], v[138:141], v[124:127], v[86:89]
	v_mfma_f32_16x16x32_bf16 v[112:115], v[142:145], v[124:127], v[112:115]
	v_mfma_f32_16x16x32_bf16 v[38:41], v[146:149], v[124:127], v[38:41]
	v_mfma_f32_16x16x32_bf16 v[46:49], v[134:137], v[130:133], v[46:49]
	v_mfma_f32_16x16x32_bf16 v[50:53], v[138:141], v[130:133], v[50:53]
	v_mfma_f32_16x16x32_bf16 v[54:57], v[142:145], v[130:133], v[54:57]
	v_mfma_f32_16x16x32_bf16 v[42:45], v[146:149], v[130:133], v[42:45]
	ds_read_b128 v[134:137], v111 offset:32768
	ds_read_b128 v[138:141], v111 offset:34816
	ds_read_b128 v[142:145], v111 offset:36864
	ds_read_b128 v[146:149], v111 offset:38912
	ds_read_b128 v[116:119], v110
	ds_read_b128 v[120:123], v110 offset:2048
	ds_read_b128 v[124:127], v110 offset:4096
	ds_read_b128 v[130:133], v110 offset:6144
	s_waitcnt lgkmcnt(3)
	v_mfma_f32_16x16x32_bf16 v[62:65], v[134:137], v[116:119], v[62:65]
	v_mfma_f32_16x16x32_bf16 v[66:69], v[138:141], v[116:119], v[66:69]
	v_mfma_f32_16x16x32_bf16 v[70:73], v[142:145], v[116:119], v[70:73]
	v_mfma_f32_16x16x32_bf16 v[28:31], v[146:149], v[116:119], v[30:33]
	s_waitcnt lgkmcnt(2)
	v_mfma_f32_16x16x32_bf16 v[58:61], v[134:137], v[120:123], v[58:61]
	v_mfma_f32_16x16x32_bf16 v[116:119], v[138:141], v[120:123], v[74:77]
	v_mfma_f32_16x16x32_bf16 v[150:153], v[142:145], v[120:123], v[78:81]
	v_mfma_f32_16x16x32_bf16 v[32:35], v[146:149], v[120:123], v[34:37]
	s_waitcnt lgkmcnt(1)
	v_mfma_f32_16x16x32_bf16 v[120:123], v[134:137], v[124:127], v[82:85]
	v_mfma_f32_16x16x32_bf16 v[154:157], v[138:141], v[124:127], v[86:89]
	v_mfma_f32_16x16x32_bf16 v[112:115], v[142:145], v[124:127], v[112:115]
	v_mfma_f32_16x16x32_bf16 v[36:39], v[146:149], v[124:127], v[38:41]
	s_waitcnt lgkmcnt(0)
	v_mfma_f32_16x16x32_bf16 v[124:127], v[134:137], v[130:133], v[46:49]
	v_mfma_f32_16x16x32_bf16 v[134:137], v[138:141], v[130:133], v[50:53]
	v_mfma_f32_16x16x32_bf16 v[138:141], v[142:145], v[130:133], v[54:57]
	v_mfma_f32_16x16x32_bf16 v[130:133], v[146:149], v[130:133], v[42:45]
	s_nop 2
	ds_read_b128 v[40:43], v109
	ds_read_b128 v[44:47], v109 offset:2048
	ds_read_b128 v[142:145], v109 offset:4096
	ds_read_b128 v[146:149], v109 offset:6144
	ds_read_b128 v[160:163], v108 offset:32768
	ds_read_b128 v[164:167], v108 offset:34816
	ds_read_b128 v[168:171], v108 offset:36864
	ds_read_b128 v[172:175], v108 offset:38912
	s_waitcnt vmcnt(0)
	s_waitcnt vmcnt(0) lgkmcnt(0)
	v_mfma_f32_16x16x32_bf16 v[48:51], v[168:171], v[142:145], v[112:115]
	s_barrier
	s_nop 1
	v_cndmask_b32_e64 v112, v0, v15, s[54:55]
	v_sub_u32_e32 v0, s74, v95
	v_mfma_f32_16x16x32_bf16 v[84:87], v[164:167], v[40:43], v[66:69]
	v_cndmask_b32_e64 v95, v1, v0, s[54:55]
	v_mfma_f32_16x16x32_bf16 v[80:83], v[168:171], v[40:43], v[70:73]
	v_mfma_f32_16x16x32_bf16 v[68:71], v[164:167], v[44:47], v[116:119]
	ds_read_b128 v[0:3], v110 offset:16384
	ds_read_b128 v[4:7], v110 offset:18432
	ds_read_b128 v[8:11], v110 offset:20480
	ds_read_b128 v[12:15], v110 offset:22528
	ds_read_b128 v[16:19], v111 offset:49152
	ds_read_b128 v[20:23], v111 offset:51200
	ds_read_b128 v[24:27], v111 offset:53248
	ds_read_b128 v[114:117], v111 offset:55296
	v_mfma_f32_16x16x32_bf16 v[88:91], v[160:163], v[40:43], v[62:65]
	v_mfma_f32_16x16x32_bf16 v[76:79], v[172:175], v[40:43], v[28:31]
	v_mfma_f32_16x16x32_bf16 v[72:75], v[160:163], v[44:47], v[58:61]
	v_mfma_f32_16x16x32_bf16 v[64:67], v[168:171], v[44:47], v[150:153]
	v_mfma_f32_16x16x32_bf16 v[60:63], v[172:175], v[44:47], v[32:35]
	v_mfma_f32_16x16x32_bf16 v[56:59], v[160:163], v[142:145], v[120:123]
	v_mfma_f32_16x16x32_bf16 v[52:55], v[164:167], v[142:145], v[154:157]
	v_mfma_f32_16x16x32_bf16 v[44:47], v[172:175], v[142:145], v[36:39]
	v_mfma_f32_16x16x32_bf16 v[40:43], v[160:163], v[146:149], v[124:127]
	v_mfma_f32_16x16x32_bf16 v[36:39], v[164:167], v[146:149], v[134:137]
	v_mfma_f32_16x16x32_bf16 v[28:31], v[168:171], v[146:149], v[138:141]
	v_mfma_f32_16x16x32_bf16 v[32:35], v[172:175], v[146:149], v[130:133]
	s_waitcnt lgkmcnt(3)
	v_mfma_f32_16x16x32_bf16 v[88:91], v[16:19], v[0:3], v[88:91]
	s_waitcnt lgkmcnt(2)
	v_mfma_f32_16x16x32_bf16 v[84:87], v[20:23], v[0:3], v[84:87]
	s_waitcnt lgkmcnt(1)
	v_mfma_f32_16x16x32_bf16 v[80:83], v[24:27], v[0:3], v[80:83]
	s_waitcnt lgkmcnt(0)
	v_mfma_f32_16x16x32_bf16 v[0:3], v[114:117], v[0:3], v[76:79]
	v_mfma_f32_16x16x32_bf16 v[72:75], v[16:19], v[4:7], v[72:75]
	v_mfma_f32_16x16x32_bf16 v[68:71], v[20:23], v[4:7], v[68:71]
	v_mfma_f32_16x16x32_bf16 v[64:67], v[24:27], v[4:7], v[64:67]
	v_mfma_f32_16x16x32_bf16 v[4:7], v[114:117], v[4:7], v[60:63]
	v_mfma_f32_16x16x32_bf16 v[76:79], v[16:19], v[8:11], v[56:59]
	v_mfma_f32_16x16x32_bf16 v[118:121], v[20:23], v[8:11], v[52:55]
	v_mfma_f32_16x16x32_bf16 v[122:125], v[24:27], v[8:11], v[48:51]
	v_mfma_f32_16x16x32_bf16 v[8:11], v[114:117], v[8:11], v[44:47]
	v_mfma_f32_16x16x32_bf16 v[130:133], v[16:19], v[12:15], v[40:43]
	v_mfma_f32_16x16x32_bf16 v[134:137], v[20:23], v[12:15], v[36:39]
	v_mfma_f32_16x16x32_bf16 v[138:141], v[24:27], v[12:15], v[28:31]
	v_mfma_f32_16x16x32_bf16 v[12:15], v[114:117], v[12:15], v[32:35]
	ds_read_b128 v[16:19], v109 offset:16384
	ds_read_b128 v[20:23], v109 offset:18432
	ds_read_b128 v[28:31], v109 offset:20480
	ds_read_b128 v[114:117], v109 offset:22528
	ds_read_b128 v[142:145], v108 offset:49152
	ds_read_b128 v[146:149], v108 offset:51200
	ds_read_b128 v[150:153], v108 offset:53248
	ds_read_b128 v[106:109], v108 offset:55296
	s_waitcnt lgkmcnt(3)
	v_mfma_f32_16x16x32_bf16 v[60:63], v[142:145], v[16:19], v[88:91]
	s_waitcnt lgkmcnt(2)
	v_mfma_f32_16x16x32_bf16 v[56:59], v[146:149], v[16:19], v[84:87]
	s_waitcnt lgkmcnt(1)
	v_mfma_f32_16x16x32_bf16 v[52:55], v[150:153], v[16:19], v[80:83]
	s_waitcnt lgkmcnt(0)
	v_mfma_f32_16x16x32_bf16 v[48:51], v[106:109], v[16:19], v[0:3]
	v_mfma_f32_16x16x32_bf16 v[32:35], v[142:145], v[20:23], v[72:75]
	v_mfma_f32_16x16x32_bf16 v[36:39], v[146:149], v[20:23], v[68:71]
	v_mfma_f32_16x16x32_bf16 v[40:43], v[150:153], v[20:23], v[64:67]
	v_mfma_f32_16x16x32_bf16 v[44:47], v[106:109], v[20:23], v[4:7]
	s_nop 1
	v_lshl_add_u32 v67, v95, 7, v158
	v_lshlrev_b32_e32 v66, 14, v92
	v_lshl_add_u64 v[64:65], v[98:99], 0, s[70:71]
	v_mfma_f32_16x16x32_bf16 v[16:19], v[142:145], v[28:31], v[76:79]
	v_cmp_lt_i32_e32 vcc, v67, v112
	v_mfma_f32_16x16x32_bf16 v[20:23], v[146:149], v[28:31], v[118:121]
	v_mfma_f32_16x16x32_bf16 v[24:27], v[150:153], v[28:31], v[122:125]
	v_mfma_f32_16x16x32_bf16 v[28:31], v[106:109], v[28:31], v[8:11]
	v_mfma_f32_16x16x32_bf16 v[0:3], v[142:145], v[114:117], v[130:133]
	v_mfma_f32_16x16x32_bf16 v[4:7], v[146:149], v[114:117], v[134:137]
	v_mfma_f32_16x16x32_bf16 v[8:11], v[150:153], v[114:117], v[138:141]
	v_mfma_f32_16x16x32_bf16 v[12:15], v[106:109], v[114:117], v[12:15]
	s_and_saveexec_b64 s[0:1], vcc
	s_cbranch_execz .LBB0_961
	v_add_u32_e32 v68, v67, v66
	v_readlane_b32 s2, v242, 54
	v_ashrrev_i32_e32 v69, 31, v68
	v_readlane_b32 s3, v242, 55
	s_nop 1
	v_lshl_add_u64 v[68:69], v[68:69], 2, s[2:3]
	global_load_dword v68, v[68:69], off
	v_readlane_b32 s2, v242, 58
	v_readlane_b32 s3, v242, 59
	s_waitcnt vmcnt(0)
	v_ashrrev_i32_e32 v69, 31, v68
	v_lshl_add_u64 v[70:71], v[68:69], 2, s[2:3]
	global_load_dword v70, v[70:71], off
	v_lshlrev_b64 v[68:69], 12, v[68:69]
	v_lshl_add_u64 v[68:69], v[64:65], 0, v[68:69]
	s_waitcnt vmcnt(0)
	v_pk_mul_f32 v[60:61], v[60:61], v[70:71] op_sel_hi:[1,0]
	v_pk_mul_f32 v[62:63], v[62:63], v[70:71] op_sel_hi:[1,0]
	v_pk_mul_f32 v[56:57], v[56:57], v[70:71] op_sel_hi:[1,0]
	v_pk_mul_f32 v[58:59], v[58:59], v[70:71] op_sel_hi:[1,0]
	v_pk_mul_f32 v[52:53], v[52:53], v[70:71] op_sel_hi:[1,0]
	v_pk_mul_f32 v[54:55], v[54:55], v[70:71] op_sel_hi:[1,0]
	v_pk_mul_f32 v[48:49], v[48:49], v[70:71] op_sel_hi:[1,0]
	v_pk_mul_f32 v[50:51], v[50:51], v[70:71] op_sel_hi:[1,0]
	v_cvt_pk_bf16_f32 v60, v60, v61
	v_cvt_pk_bf16_f32 v61, v62, v63
	v_cvt_pk_bf16_f32 v56, v56, v57
	v_cvt_pk_bf16_f32 v57, v58, v59
	v_cvt_pk_bf16_f32 v52, v52, v53
	v_cvt_pk_bf16_f32 v53, v54, v55
	v_cvt_pk_bf16_f32 v48, v48, v49
	v_cvt_pk_bf16_f32 v49, v50, v51
	global_store_dwordx2 v[68:69], v[60:61], off
	global_store_dwordx2 v[68:69], v[56:57], off offset:32
	global_store_dwordx2 v[68:69], v[52:53], off offset:64
	global_store_dwordx2 v[68:69], v[48:49], off offset:96

.LBB0_969:
	v_cvt_pk_bf16_f32 v163, v2, v3
	v_cvt_pk_bf16_f32 v164, v6, v7
	v_cvt_pk_bf16_f32 v165, v10, v11
	v_cvt_pk_bf16_f32 v166, v14, v15
	v_cvt_pk_bf16_f32 v167, v18, v19
	v_cvt_pk_bf16_f32 v168, v22, v23
	v_cvt_pk_bf16_f32 v169, v26, v27
	v_cvt_pk_bf16_f32 v170, v30, v31
	v_cvt_pk_bf16_f32 v148, v34, v35
	v_cvt_pk_bf16_f32 v146, v38, v39
	v_cvt_pk_bf16_f32 v145, v42, v43
	v_cvt_pk_bf16_f32 v144, v46, v47
	v_cvt_pk_bf16_f32 v143, v50, v51
	v_cvt_pk_bf16_f32 v142, v54, v55
	v_cvt_pk_bf16_f32 v55, v58, v59
	v_cvt_pk_bf16_f32 v54, v62, v63
	v_cvt_pk_bf16_f32 v171, v0, v1
	v_cvt_pk_bf16_f32 v172, v4, v5
	v_cvt_pk_bf16_f32 v173, v8, v9
	v_cvt_pk_bf16_f32 v174, v12, v13
	v_cvt_pk_bf16_f32 v175, v16, v17
	v_cvt_pk_bf16_f32 v176, v20, v21
	v_cvt_pk_bf16_f32 v177, v24, v25
	v_cvt_pk_bf16_f32 v178, v28, v29
	v_cvt_pk_bf16_f32 v149, v32, v33
	v_cvt_pk_bf16_f32 v147, v36, v37
	v_cvt_pk_bf16_f32 v63, v40, v41
	v_cvt_pk_bf16_f32 v62, v44, v45
	v_cvt_pk_bf16_f32 v59, v48, v49
	v_cvt_pk_bf16_f32 v58, v52, v53
	v_cvt_pk_bf16_f32 v53, v56, v57
	v_cvt_pk_bf16_f32 v52, v60, v61
	v_add_u32_e32 v12, v160, v162
	v_add_u32_e32 v28, v159, v162
	ds_read_b128 v[16:19], v28 offset:49152
	ds_read_b128 v[20:23], v28 offset:51200
	ds_read_b128 v[24:27], v28 offset:53248
	ds_read_b128 v[28:31], v28 offset:55296
	ds_read_b128 v[0:3], v12 offset:16384
	ds_read_b128 v[4:7], v12 offset:18432
	ds_read_b128 v[8:11], v12 offset:20480
	ds_read_b128 v[12:15], v12 offset:22528
	s_setprio 1
	s_waitcnt lgkmcnt(3)
	v_mfma_f32_16x16x32_bf16 v[32:35], v[16:19], v[0:3], v[64:67]
	v_mfma_f32_16x16x32_bf16 v[36:39], v[20:23], v[0:3], v[68:71]
	v_mfma_f32_16x16x32_bf16 v[40:43], v[24:27], v[0:3], v[72:75]
	v_mfma_f32_16x16x32_bf16 v[0:3], v[28:31], v[0:3], v[76:79]
	s_waitcnt lgkmcnt(2)
	v_mfma_f32_16x16x32_bf16 v[44:47], v[16:19], v[4:7], v[80:83]
	v_mfma_f32_16x16x32_bf16 v[48:51], v[20:23], v[4:7], v[84:87]
	v_mfma_f32_16x16x32_bf16 v[64:67], v[24:27], v[4:7], v[88:91]
	v_mfma_f32_16x16x32_bf16 v[4:7], v[28:31], v[4:7], v[92:95]
	s_waitcnt lgkmcnt(1)
	v_mfma_f32_16x16x32_bf16 v[68:71], v[16:19], v[8:11], v[96:99]
	v_mfma_f32_16x16x32_bf16 v[72:75], v[20:23], v[8:11], v[100:103]
	v_mfma_f32_16x16x32_bf16 v[76:79], v[24:27], v[8:11], v[104:107]
	v_mfma_f32_16x16x32_bf16 v[8:11], v[28:31], v[8:11], v[108:111]
	s_waitcnt lgkmcnt(0)
	v_mfma_f32_16x16x32_bf16 v[80:83], v[16:19], v[12:15], v[112:115]
	v_mfma_f32_16x16x32_bf16 v[84:87], v[20:23], v[12:15], v[116:119]
	v_mfma_f32_16x16x32_bf16 v[88:91], v[24:27], v[12:15], v[120:123]
	v_mfma_f32_16x16x32_bf16 v[92:95], v[28:31], v[12:15], v[124:127]
	s_setprio 0
	v_add_u32_e32 v20, v160, v161
	ds_read_b128 v[12:15], v20 offset:16384
	ds_read_b128 v[16:19], v20 offset:18432
	ds_read_b128 v[96:99], v20 offset:20480
	ds_read_b128 v[100:103], v20 offset:22528
	v_add_u32_e32 v20, v159, v161
	ds_read_b128 v[104:107], v20 offset:49152
	ds_read_b128 v[108:111], v20 offset:51200
	ds_read_b128 v[112:115], v20 offset:53248
	ds_read_b128 v[116:119], v20 offset:55296
	s_setprio 1
	s_waitcnt lgkmcnt(0)
	v_mfma_f32_16x16x32_bf16 v[120:123], v[104:107], v[12:15], v[32:35]
	v_mfma_f32_16x16x32_bf16 v[124:127], v[108:111], v[12:15], v[36:39]
	v_mfma_f32_16x16x32_bf16 v[150:153], v[112:115], v[12:15], v[40:43]
	v_mfma_f32_16x16x32_bf16 v[154:157], v[116:119], v[12:15], v[0:3]
	v_mfma_f32_16x16x32_bf16 v[44:47], v[104:107], v[16:19], v[44:47]
	v_mfma_f32_16x16x32_bf16 v[40:43], v[108:111], v[16:19], v[48:51]
	v_mfma_f32_16x16x32_bf16 v[36:39], v[112:115], v[16:19], v[64:67]
	v_mfma_f32_16x16x32_bf16 v[32:35], v[116:119], v[16:19], v[4:7]
	v_mfma_f32_16x16x32_bf16 v[28:31], v[104:107], v[96:99], v[68:71]
	v_mfma_f32_16x16x32_bf16 v[24:27], v[108:111], v[96:99], v[72:75]
	v_mfma_f32_16x16x32_bf16 v[20:23], v[112:115], v[96:99], v[76:79]
	v_mfma_f32_16x16x32_bf16 v[16:19], v[116:119], v[96:99], v[8:11]
	v_mfma_f32_16x16x32_bf16 v[12:15], v[104:107], v[100:103], v[80:83]
	v_mfma_f32_16x16x32_bf16 v[8:11], v[108:111], v[100:103], v[84:87]
	v_mfma_f32_16x16x32_bf16 v[4:7], v[112:115], v[100:103], v[88:91]
	v_mfma_f32_16x16x32_bf16 v[0:3], v[116:119], v[100:103], v[92:95]
	s_setprio 0
	v_add_u32_e32 v50, s22, v158
	v_or_b32_e32 v48, s23, v129
	v_ashrrev_i32_e32 v51, 31, v50
	v_readlane_b32 s16, v242, 52
	v_lshlrev_b64 v[56:57], 13, v[50:51]
	v_readlane_b32 s17, v242, 53
	v_ashrrev_i32_e32 v49, 31, v48
	v_lshlrev_b64 v[48:49], 2, v[48:49]
	v_lshl_add_u64 v[60:61], s[16:17], 0, v[56:57]
	v_lshl_add_u64 v[60:61], v[60:61], 0, v[48:49]
	global_load_dwordx4 v[64:67], v[60:61], off
	v_mul_f32_e32 v51, 0xbfb8aa3b, v120
	v_mul_f32_e32 v72, 0xbfb8aa3b, v121
	v_mul_f32_e32 v73, 0xbfb8aa3b, v122
	v_mul_f32_e32 v74, 0xbfb8aa3b, v123
	v_exp_f32_e32 v51, v51
	v_exp_f32_e32 v72, v72
	v_exp_f32_e32 v73, v73
	v_exp_f32_e32 v74, v74
	v_add_f32_e32 v51, 1.0, v51
	v_add_f32_e32 v75, 1.0, v72
	v_add_f32_e32 v76, 1.0, v73
	v_add_f32_e32 v77, 1.0, v74
	v_rcp_f32_e32 v72, v51
	v_rcp_f32_e32 v73, v75
	v_rcp_f32_e32 v74, v76
	v_rcp_f32_e32 v75, v77
	v_lshlrev_b32_e32 v68, 16, v171
	v_and_b32_e32 v69, 0xffff0000, v171
	v_lshlrev_b32_e32 v70, 16, v163
	v_and_b32_e32 v71, 0xffff0000, v163
	v_lshl_add_u64 v[56:57], s[92:93], 0, v[56:57]
	v_lshl_add_u64 v[56:57], v[56:57], 0, v[48:49]
	v_mul_f32_e32 v51, 0xbfb8aa3b, v124
	v_exp_f32_e32 v51, v51
	v_mul_f32_e32 v44, 0xbfb8aa3b, v44
	v_mul_f32_e32 v45, 0xbfb8aa3b, v45
	v_mul_f32_e32 v46, 0xbfb8aa3b, v46
	v_add_f32_e32 v51, 1.0, v51
	v_mul_f32_e32 v47, 0xbfb8aa3b, v47
	v_exp_f32_e32 v46, v46
	v_exp_f32_e32 v47, v47
	v_mul_f32_e32 v40, 0xbfb8aa3b, v40
	v_mul_f32_e32 v41, 0xbfb8aa3b, v41
	v_add_f32_e32 v46, 1.0, v46
	v_add_f32_e32 v47, 1.0, v47
	v_rcp_f32_e32 v46, v46
	v_rcp_f32_e32 v47, v47
	v_mul_f32_e32 v42, 0xbfb8aa3b, v42
	v_mul_f32_e32 v43, 0xbfb8aa3b, v43
	v_exp_f32_e32 v40, v40
	v_exp_f32_e32 v41, v41
	v_exp_f32_e32 v42, v42
	v_exp_f32_e32 v43, v43
	v_add_f32_e32 v40, 1.0, v40
	v_add_f32_e32 v41, 1.0, v41
	v_add_f32_e32 v42, 1.0, v42
	v_add_f32_e32 v43, 1.0, v43
	v_rcp_f32_e32 v40, v40
	v_rcp_f32_e32 v41, v41
	v_rcp_f32_e32 v42, v42
	v_rcp_f32_e32 v43, v43
	v_mul_f32_e32 v36, 0xbfb8aa3b, v36
	v_mul_f32_e32 v37, 0xbfb8aa3b, v37
	v_mul_f32_e32 v38, 0xbfb8aa3b, v38
	v_mul_f32_e32 v39, 0xbfb8aa3b, v39
	v_exp_f32_e32 v36, v36
	v_exp_f32_e32 v37, v37
	v_exp_f32_e32 v38, v38
	v_exp_f32_e32 v39, v39
	v_add_f32_e32 v36, 1.0, v36
	v_add_f32_e32 v37, 1.0, v37
	v_add_f32_e32 v38, 1.0, v38
	v_add_f32_e32 v39, 1.0, v39
	v_rcp_f32_e32 v36, v36
	v_rcp_f32_e32 v37, v37
	v_rcp_f32_e32 v38, v38
	v_rcp_f32_e32 v39, v39
	v_mul_f32_e32 v32, 0xbfb8aa3b, v32
	v_mul_f32_e32 v33, 0xbfb8aa3b, v33
	v_mul_f32_e32 v34, 0xbfb8aa3b, v34
	v_mul_f32_e32 v35, 0xbfb8aa3b, v35
	v_exp_f32_e32 v34, v34
	v_exp_f32_e32 v35, v35
	v_mul_f32_e32 v28, 0xbfb8aa3b, v28
	v_mul_f32_e32 v29, 0xbfb8aa3b, v29
	v_add_f32_e32 v34, 1.0, v34
	v_add_f32_e32 v35, 1.0, v35
	v_rcp_f32_e32 v34, v34
	v_rcp_f32_e32 v35, v35
	s_waitcnt vmcnt(0)
	v_pk_mul_f32 v[66:67], v[66:67], s[12:13] op_sel_hi:[1,0]
	v_pk_mul_f32 v[64:65], v[64:65], s[12:13] op_sel_hi:[1,0]
	v_pk_fma_f32 v[66:67], v[74:75], v[70:71], v[66:67]
	v_pk_fma_f32 v[64:65], v[72:73], v[68:69], v[64:65]
	global_store_dwordx4 v[56:57], v[64:67], off
	global_load_dwordx4 v[64:67], v[60:61], off offset:64
	v_mul_f32_e32 v72, 0xbfb8aa3b, v125
	v_mul_f32_e32 v73, 0xbfb8aa3b, v126
	v_mul_f32_e32 v74, 0xbfb8aa3b, v127
	v_exp_f32_e32 v72, v72
	v_exp_f32_e32 v73, v73
	v_exp_f32_e32 v74, v74
	v_lshlrev_b32_e32 v68, 16, v172
	v_add_f32_e32 v75, 1.0, v72
	v_add_f32_e32 v76, 1.0, v73
	v_add_f32_e32 v77, 1.0, v74
	v_rcp_f32_e32 v72, v51
	v_rcp_f32_e32 v73, v75
	v_rcp_f32_e32 v74, v76
	v_rcp_f32_e32 v75, v77
	v_and_b32_e32 v69, 0xffff0000, v172
	v_lshlrev_b32_e32 v70, 16, v164
	v_and_b32_e32 v71, 0xffff0000, v164
	v_mul_f32_e32 v51, 0xbfb8aa3b, v150
	v_exp_f32_e32 v51, v51
	v_mul_f32_e32 v30, 0xbfb8aa3b, v30
	v_mul_f32_e32 v31, 0xbfb8aa3b, v31
	v_exp_f32_e32 v30, v30
	v_add_f32_e32 v51, 1.0, v51
	v_exp_f32_e32 v31, v31
	v_mul_f32_e32 v24, 0xbfb8aa3b, v24
	v_add_f32_e32 v30, 1.0, v30
	v_rcp_f32_e32 v30, v30
	v_add_f32_e32 v31, 1.0, v31
	v_rcp_f32_e32 v31, v31
	v_mul_f32_e32 v25, 0xbfb8aa3b, v25
	v_mul_f32_e32 v26, 0xbfb8aa3b, v26
	v_mul_f32_e32 v27, 0xbfb8aa3b, v27
	v_exp_f32_e32 v24, v24
	v_exp_f32_e32 v25, v25
	v_exp_f32_e32 v26, v26
	v_exp_f32_e32 v27, v27
	v_add_f32_e32 v24, 1.0, v24
	v_add_f32_e32 v25, 1.0, v25
	v_add_f32_e32 v26, 1.0, v26
	v_add_f32_e32 v27, 1.0, v27
	v_rcp_f32_e32 v24, v24
	v_rcp_f32_e32 v25, v25
	v_rcp_f32_e32 v26, v26
	v_rcp_f32_e32 v27, v27
	v_mul_f32_e32 v20, 0xbfb8aa3b, v20
	v_mul_f32_e32 v21, 0xbfb8aa3b, v21
	v_mul_f32_e32 v22, 0xbfb8aa3b, v22
	v_mul_f32_e32 v23, 0xbfb8aa3b, v23
	v_exp_f32_e32 v20, v20
	v_exp_f32_e32 v21, v21
	v_exp_f32_e32 v22, v22
	v_exp_f32_e32 v23, v23
	v_add_f32_e32 v20, 1.0, v20
	v_add_f32_e32 v21, 1.0, v21
	v_add_f32_e32 v22, 1.0, v22
	v_add_f32_e32 v23, 1.0, v23
	v_rcp_f32_e32 v20, v20
	v_rcp_f32_e32 v21, v21
	v_rcp_f32_e32 v22, v22
	v_rcp_f32_e32 v23, v23
	v_mul_f32_e32 v16, 0xbfb8aa3b, v16
	v_mul_f32_e32 v17, 0xbfb8aa3b, v17
	v_mul_f32_e32 v18, 0xbfb8aa3b, v18
	v_mul_f32_e32 v19, 0xbfb8aa3b, v19
	v_exp_f32_e32 v18, v18
	v_exp_f32_e32 v19, v19
	v_mul_f32_e32 v12, 0xbfb8aa3b, v12
	v_mul_f32_e32 v13, 0xbfb8aa3b, v13
	v_add_f32_e32 v18, 1.0, v18
	v_add_f32_e32 v19, 1.0, v19
	v_rcp_f32_e32 v18, v18
	v_rcp_f32_e32 v19, v19
	v_mul_f32_e32 v14, 0xbfb8aa3b, v14
	v_mul_f32_e32 v15, 0xbfb8aa3b, v15
	v_exp_f32_e32 v14, v14
	v_exp_f32_e32 v15, v15
	v_mul_f32_e32 v8, 0xbfb8aa3b, v8
	v_mul_f32_e32 v9, 0xbfb8aa3b, v9
	v_add_f32_e32 v14, 1.0, v14
	s_waitcnt vmcnt(0)
	v_pk_mul_f32 v[66:67], v[66:67], s[12:13] op_sel_hi:[1,0]
	v_pk_mul_f32 v[64:65], v[64:65], s[12:13] op_sel_hi:[1,0]
	v_pk_fma_f32 v[66:67], v[74:75], v[70:71], v[66:67]
	v_pk_fma_f32 v[64:65], v[72:73], v[68:69], v[64:65]
	global_store_dwordx4 v[56:57], v[64:67], off offset:64
	global_load_dwordx4 v[64:67], v[60:61], off offset:128
	v_mul_f32_e32 v72, 0xbfb8aa3b, v151
	v_mul_f32_e32 v73, 0xbfb8aa3b, v152
	v_mul_f32_e32 v74, 0xbfb8aa3b, v153
	v_exp_f32_e32 v72, v72
	v_exp_f32_e32 v73, v73
	v_exp_f32_e32 v74, v74
	v_lshlrev_b32_e32 v68, 16, v173
	v_add_f32_e32 v75, 1.0, v72
	v_add_f32_e32 v76, 1.0, v73
	v_add_f32_e32 v77, 1.0, v74
	v_rcp_f32_e32 v72, v51
	v_rcp_f32_e32 v73, v75
	v_rcp_f32_e32 v74, v76
	v_rcp_f32_e32 v75, v77
	v_and_b32_e32 v69, 0xffff0000, v173
	v_lshlrev_b32_e32 v70, 16, v165
	v_and_b32_e32 v71, 0xffff0000, v165
	v_mul_f32_e32 v51, 0xbfb8aa3b, v154
	v_exp_f32_e32 v51, v51
	v_add_f32_e32 v15, 1.0, v15
	v_rcp_f32_e32 v14, v14
	v_rcp_f32_e32 v15, v15
	v_add_f32_e32 v51, 1.0, v51
	v_mul_f32_e32 v10, 0xbfb8aa3b, v10
	v_mul_f32_e32 v11, 0xbfb8aa3b, v11
	v_exp_f32_e32 v8, v8
	v_exp_f32_e32 v9, v9
	v_exp_f32_e32 v10, v10
	v_exp_f32_e32 v11, v11
	v_add_f32_e32 v8, 1.0, v8
	v_add_f32_e32 v9, 1.0, v9
	v_add_f32_e32 v10, 1.0, v10
	v_add_f32_e32 v11, 1.0, v11
	v_rcp_f32_e32 v8, v8
	v_rcp_f32_e32 v9, v9
	v_rcp_f32_e32 v10, v10
	v_rcp_f32_e32 v11, v11
	v_mul_f32_e32 v4, 0xbfb8aa3b, v4
	v_mul_f32_e32 v5, 0xbfb8aa3b, v5
	v_mul_f32_e32 v6, 0xbfb8aa3b, v6
	v_mul_f32_e32 v7, 0xbfb8aa3b, v7
	v_exp_f32_e32 v4, v4
	v_exp_f32_e32 v5, v5
	v_exp_f32_e32 v6, v6
	v_exp_f32_e32 v7, v7
	v_add_f32_e32 v4, 1.0, v4
	v_add_f32_e32 v5, 1.0, v5
	v_add_f32_e32 v6, 1.0, v6
	v_add_f32_e32 v7, 1.0, v7
	v_rcp_f32_e32 v4, v4
	v_rcp_f32_e32 v5, v5
	v_rcp_f32_e32 v6, v6
	v_rcp_f32_e32 v7, v7
	v_mul_f32_e32 v0, 0xbfb8aa3b, v0
	v_mul_f32_e32 v1, 0xbfb8aa3b, v1
	v_mul_f32_e32 v2, 0xbfb8aa3b, v2
	v_mul_f32_e32 v3, 0xbfb8aa3b, v3
	v_exp_f32_e32 v0, v0
	v_exp_f32_e32 v1, v1
	v_exp_f32_e32 v2, v2
	v_exp_f32_e32 v3, v3
	v_add_f32_e32 v0, 1.0, v0
	v_add_f32_e32 v1, 1.0, v1
	v_add_f32_e32 v2, 1.0, v2
	v_add_f32_e32 v3, 1.0, v3
	v_rcp_f32_e32 v0, v0
	v_rcp_f32_e32 v1, v1
	v_rcp_f32_e32 v2, v2
	v_rcp_f32_e32 v3, v3
	s_andn2_b64 vcc, exec, s[14:15]
	s_mov_b64 s[18:19], 0
	s_waitcnt vmcnt(0)
	v_pk_mul_f32 v[66:67], v[66:67], s[12:13] op_sel_hi:[1,0]
	v_pk_mul_f32 v[64:65], v[64:65], s[12:13] op_sel_hi:[1,0]
	v_pk_fma_f32 v[66:67], v[74:75], v[70:71], v[66:67]
	v_pk_fma_f32 v[64:65], v[72:73], v[68:69], v[64:65]
	global_store_dwordx4 v[56:57], v[64:67], off offset:128
	global_load_dwordx4 v[64:67], v[60:61], off offset:192
	v_mul_f32_e32 v70, 0xbfb8aa3b, v155
	v_mul_f32_e32 v71, 0xbfb8aa3b, v156
	v_mul_f32_e32 v72, 0xbfb8aa3b, v157
	v_exp_f32_e32 v74, v70
	v_exp_f32_e32 v75, v71
	v_exp_f32_e32 v76, v72
	v_or_b32_e32 v70, 16, v50
	v_add_f32_e32 v77, 1.0, v74
	v_add_f32_e32 v78, 1.0, v75
	v_add_f32_e32 v79, 1.0, v76
	v_rcp_f32_e32 v74, v51
	v_rcp_f32_e32 v75, v77
	v_rcp_f32_e32 v76, v78
	v_rcp_f32_e32 v77, v79
	v_ashrrev_i32_e32 v71, 31, v70
	v_lshlrev_b32_e32 v60, 16, v174
	v_and_b32_e32 v61, 0xffff0000, v174
	v_lshlrev_b32_e32 v68, 16, v166
	v_and_b32_e32 v69, 0xffff0000, v166
	v_lshlrev_b64 v[70:71], 13, v[70:71]
	v_lshl_add_u64 v[72:73], s[16:17], 0, v[70:71]
	v_lshl_add_u64 v[72:73], v[72:73], 0, v[48:49]
	v_exp_f32_e32 v51, v44
	s_waitcnt vmcnt(0)
	v_pk_mul_f32 v[66:67], v[66:67], s[12:13] op_sel_hi:[1,0]
	v_pk_mul_f32 v[64:65], v[64:65], s[12:13] op_sel_hi:[1,0]
	v_pk_fma_f32 v[66:67], v[76:77], v[68:69], v[66:67]
	v_pk_fma_f32 v[64:65], v[74:75], v[60:61], v[64:65]
	global_store_dwordx4 v[56:57], v[64:67], off offset:192
	global_load_dwordx4 v[64:67], v[72:73], off
	v_exp_f32_e32 v68, v45
	v_lshl_add_u64 v[44:45], s[92:93], 0, v[70:71]
	v_add_f32_e32 v51, 1.0, v51
	v_lshlrev_b32_e32 v56, 16, v175
	v_add_f32_e32 v70, 1.0, v68
	v_lshl_add_u64 v[68:69], v[44:45], 0, v[48:49]
	v_rcp_f32_e32 v44, v51
	v_rcp_f32_e32 v45, v70
	v_and_b32_e32 v57, 0xffff0000, v175
	v_lshlrev_b32_e32 v60, 16, v167
	v_and_b32_e32 v61, 0xffff0000, v167
	s_waitcnt vmcnt(0)
	v_pk_mul_f32 v[66:67], v[66:67], s[12:13] op_sel_hi:[1,0]
	v_pk_mul_f32 v[64:65], v[64:65], s[12:13] op_sel_hi:[1,0]
	v_pk_fma_f32 v[46:47], v[46:47], v[60:61], v[66:67]
	v_pk_fma_f32 v[44:45], v[44:45], v[56:57], v[64:65]
	global_store_dwordx4 v[68:69], v[44:47], off
	global_load_dwordx4 v[44:47], v[72:73], off offset:64
	v_lshlrev_b32_e32 v56, 16, v176
	v_and_b32_e32 v57, 0xffff0000, v176
	v_lshlrev_b32_e32 v60, 16, v168
	v_and_b32_e32 v61, 0xffff0000, v168
	s_waitcnt vmcnt(0)
	v_pk_mul_f32 v[46:47], v[46:47], s[12:13] op_sel_hi:[1,0]
	v_pk_mul_f32 v[44:45], v[44:45], s[12:13] op_sel_hi:[1,0]
	v_pk_fma_f32 v[42:43], v[42:43], v[60:61], v[46:47]
	v_pk_fma_f32 v[40:41], v[40:41], v[56:57], v[44:45]
	global_store_dwordx4 v[68:69], v[40:43], off offset:64
	global_load_dwordx4 v[40:43], v[72:73], off offset:128
	v_lshlrev_b32_e32 v44, 16, v177
	v_and_b32_e32 v45, 0xffff0000, v177
	v_lshlrev_b32_e32 v46, 16, v169
	v_and_b32_e32 v47, 0xffff0000, v169
	s_waitcnt vmcnt(0)
	v_pk_mul_f32 v[42:43], v[42:43], s[12:13] op_sel_hi:[1,0]
	v_pk_mul_f32 v[40:41], v[40:41], s[12:13] op_sel_hi:[1,0]
	v_pk_fma_f32 v[38:39], v[38:39], v[46:47], v[42:43]
	v_pk_fma_f32 v[36:37], v[36:37], v[44:45], v[40:41]
	global_store_dwordx4 v[68:69], v[36:39], off offset:128
	global_load_dwordx4 v[36:39], v[72:73], off offset:192
	v_exp_f32_e32 v46, v32
	v_exp_f32_e32 v47, v33
	v_or_b32_e32 v32, 32, v50
	v_ashrrev_i32_e32 v33, 31, v32
	v_lshlrev_b64 v[44:45], 13, v[32:33]
	v_lshl_add_u64 v[32:33], s[16:17], 0, v[44:45]
	v_add_f32_e32 v51, 1.0, v46
	v_add_f32_e32 v56, 1.0, v47
	v_lshl_add_u64 v[46:47], v[32:33], 0, v[48:49]
	v_rcp_f32_e32 v32, v51
	v_rcp_f32_e32 v33, v56
	v_lshlrev_b32_e32 v40, 16, v178
	v_and_b32_e32 v41, 0xffff0000, v178
	v_lshlrev_b32_e32 v42, 16, v170
	v_and_b32_e32 v43, 0xffff0000, v170
	s_waitcnt vmcnt(0)
	v_pk_mul_f32 v[38:39], v[38:39], s[12:13] op_sel_hi:[1,0]
	v_pk_mul_f32 v[36:37], v[36:37], s[12:13] op_sel_hi:[1,0]
	v_pk_fma_f32 v[34:35], v[34:35], v[42:43], v[38:39]
	v_pk_fma_f32 v[32:33], v[32:33], v[40:41], v[36:37]
	global_store_dwordx4 v[68:69], v[32:35], off offset:192
	global_load_dwordx4 v[32:35], v[46:47], off
	v_exp_f32_e32 v40, v28
	v_exp_f32_e32 v41, v29
	v_lshl_add_u64 v[28:29], s[92:93], 0, v[44:45]
	v_lshlrev_b32_e32 v36, 16, v149
	v_add_f32_e32 v42, 1.0, v40
	v_add_f32_e32 v43, 1.0, v41
	v_lshl_add_u64 v[40:41], v[28:29], 0, v[48:49]
	v_rcp_f32_e32 v28, v42
	v_rcp_f32_e32 v29, v43
	v_and_b32_e32 v37, 0xffff0000, v149
	v_lshlrev_b32_e32 v38, 16, v148
	v_and_b32_e32 v39, 0xffff0000, v148
	s_waitcnt vmcnt(0)
	v_pk_mul_f32 v[34:35], v[34:35], s[12:13] op_sel_hi:[1,0]
	v_pk_mul_f32 v[32:33], v[32:33], s[12:13] op_sel_hi:[1,0]
	v_pk_fma_f32 v[30:31], v[30:31], v[38:39], v[34:35]
	v_pk_fma_f32 v[28:29], v[28:29], v[36:37], v[32:33]
	global_store_dwordx4 v[40:41], v[28:31], off
	global_load_dwordx4 v[28:31], v[46:47], off offset:64
	v_lshlrev_b32_e32 v32, 16, v147
	v_and_b32_e32 v33, 0xffff0000, v147
	v_lshlrev_b32_e32 v34, 16, v146
	v_and_b32_e32 v35, 0xffff0000, v146
	s_waitcnt vmcnt(0)
	v_pk_mul_f32 v[30:31], v[30:31], s[12:13] op_sel_hi:[1,0]
	v_pk_mul_f32 v[28:29], v[28:29], s[12:13] op_sel_hi:[1,0]
	v_pk_fma_f32 v[26:27], v[26:27], v[34:35], v[30:31]
	v_pk_fma_f32 v[24:25], v[24:25], v[32:33], v[28:29]
	global_store_dwordx4 v[40:41], v[24:27], off offset:64
	global_load_dwordx4 v[24:27], v[46:47], off offset:128
	v_lshlrev_b32_e32 v28, 16, v63
	v_and_b32_e32 v29, 0xffff0000, v63
	v_lshlrev_b32_e32 v30, 16, v145
	v_and_b32_e32 v31, 0xffff0000, v145
	s_waitcnt vmcnt(0)
	v_pk_mul_f32 v[26:27], v[26:27], s[12:13] op_sel_hi:[1,0]
	v_pk_mul_f32 v[24:25], v[24:25], s[12:13] op_sel_hi:[1,0]
	v_pk_fma_f32 v[22:23], v[22:23], v[30:31], v[26:27]
	v_pk_fma_f32 v[20:21], v[20:21], v[28:29], v[24:25]
	global_store_dwordx4 v[40:41], v[20:23], off offset:128
	global_load_dwordx4 v[20:23], v[46:47], off offset:192
	v_exp_f32_e32 v30, v16
	v_exp_f32_e32 v31, v17
	v_or_b32_e32 v16, 48, v50
	v_ashrrev_i32_e32 v17, 31, v16
	v_lshlrev_b64 v[28:29], 13, v[16:17]
	v_lshl_add_u64 v[16:17], s[16:17], 0, v[28:29]
	v_add_f32_e32 v32, 1.0, v30
	v_add_f32_e32 v33, 1.0, v31
	v_lshl_add_u64 v[30:31], v[16:17], 0, v[48:49]
	v_rcp_f32_e32 v16, v32
	v_rcp_f32_e32 v17, v33
	v_lshlrev_b32_e32 v24, 16, v62
	v_and_b32_e32 v25, 0xffff0000, v62
	v_lshlrev_b32_e32 v26, 16, v144
	v_and_b32_e32 v27, 0xffff0000, v144
	s_waitcnt vmcnt(0)
	v_pk_mul_f32 v[22:23], v[22:23], s[12:13] op_sel_hi:[1,0]
	v_pk_mul_f32 v[20:21], v[20:21], s[12:13] op_sel_hi:[1,0]
	v_pk_fma_f32 v[18:19], v[18:19], v[26:27], v[22:23]
	v_pk_fma_f32 v[16:17], v[16:17], v[24:25], v[20:21]
	global_store_dwordx4 v[40:41], v[16:19], off offset:192
	global_load_dwordx4 v[16:19], v[30:31], off
	v_exp_f32_e32 v24, v12
	v_exp_f32_e32 v25, v13
	v_lshl_add_u64 v[12:13], s[92:93], 0, v[28:29]
	v_lshlrev_b32_e32 v20, 16, v59
	v_add_f32_e32 v26, 1.0, v24
	v_add_f32_e32 v27, 1.0, v25
	v_lshl_add_u64 v[24:25], v[12:13], 0, v[48:49]
	v_rcp_f32_e32 v12, v26
	v_rcp_f32_e32 v13, v27
	v_and_b32_e32 v21, 0xffff0000, v59
	v_lshlrev_b32_e32 v22, 16, v143
	v_and_b32_e32 v23, 0xffff0000, v143
	s_waitcnt vmcnt(0)
	v_pk_mul_f32 v[18:19], v[18:19], s[12:13] op_sel_hi:[1,0]
	v_pk_mul_f32 v[16:17], v[16:17], s[12:13] op_sel_hi:[1,0]
	v_pk_fma_f32 v[14:15], v[14:15], v[22:23], v[18:19]
	v_pk_fma_f32 v[12:13], v[12:13], v[20:21], v[16:17]
	global_store_dwordx4 v[24:25], v[12:15], off
	global_load_dwordx4 v[12:15], v[30:31], off offset:64
	v_lshlrev_b32_e32 v16, 16, v58
	v_and_b32_e32 v17, 0xffff0000, v58
	v_lshlrev_b32_e32 v18, 16, v142
	v_and_b32_e32 v19, 0xffff0000, v142
	s_waitcnt vmcnt(0)
	v_pk_mul_f32 v[14:15], v[14:15], s[12:13] op_sel_hi:[1,0]
	v_pk_mul_f32 v[12:13], v[12:13], s[12:13] op_sel_hi:[1,0]
	v_pk_fma_f32 v[10:11], v[10:11], v[18:19], v[14:15]
	v_pk_fma_f32 v[8:9], v[8:9], v[16:17], v[12:13]
	global_store_dwordx4 v[24:25], v[8:11], off offset:64
	global_load_dwordx4 v[8:11], v[30:31], off offset:128
	v_lshlrev_b32_e32 v12, 16, v53
	v_and_b32_e32 v13, 0xffff0000, v53
	v_lshlrev_b32_e32 v14, 16, v55
	v_and_b32_e32 v15, 0xffff0000, v55
	s_waitcnt vmcnt(0)
	v_pk_mul_f32 v[10:11], v[10:11], s[12:13] op_sel_hi:[1,0]
	v_pk_mul_f32 v[8:9], v[8:9], s[12:13] op_sel_hi:[1,0]
	v_pk_fma_f32 v[6:7], v[6:7], v[14:15], v[10:11]
	v_pk_fma_f32 v[4:5], v[4:5], v[12:13], v[8:9]
	global_store_dwordx4 v[24:25], v[4:7], off offset:128
	global_load_dwordx4 v[4:7], v[30:31], off offset:192
	v_lshlrev_b32_e32 v8, 16, v52
	v_and_b32_e32 v9, 0xffff0000, v52
	v_lshlrev_b32_e32 v10, 16, v54
	v_and_b32_e32 v11, 0xffff0000, v54
	s_waitcnt vmcnt(0)
	v_pk_mul_f32 v[6:7], v[6:7], s[12:13] op_sel_hi:[1,0]
	v_pk_mul_f32 v[4:5], v[4:5], s[12:13] op_sel_hi:[1,0]
	v_pk_fma_f32 v[2:3], v[2:3], v[10:11], v[6:7]
	v_pk_fma_f32 v[0:1], v[0:1], v[8:9], v[4:5]
	global_store_dwordx4 v[24:25], v[0:3], off offset:192
	s_cbranch_vccz .LBB0_980

.LBB0_976:
	v_lshlrev_b32_e32 v159, 1, v37
	v_add_u32_e32 v36, 0x4000, v159
	v_lshl_add_u64 v[38:39], v[0:1], 0, s[0:1]
	v_readfirstlane_b32 s21, v36
	s_mov_b32 m0, s21
	s_waitcnt vmcnt(0)
	s_waitcnt vmcnt(0) lgkmcnt(0)
	s_barrier
	global_load_lds_dwordx4 v[38:39], off
	v_add_u32_e32 v38, 0xc000, v159
	v_lshlrev_b32_e32 v160, 1, v35
	v_readfirstlane_b32 s18, v38
	v_add_u32_e32 v35, 0x4000, v160
	v_lshl_add_u64 v[36:37], v[2:3], 0, s[0:1]
	s_mov_b32 m0, s18
	v_readfirstlane_b32 s19, v35
	v_add_u32_e32 v35, 0xc000, v160
	v_lshlrev_b32_e32 v161, 1, v34
	global_load_lds_dwordx4 v[36:37], off
	v_lshl_add_u64 v[36:37], v[4:5], 0, s[0:1]
	s_mov_b32 m0, s19
	v_readfirstlane_b32 s26, v35
	v_add_u32_e32 v34, 0x4000, v161
	global_load_lds_dwordx4 v[36:37], off
	v_lshl_add_u64 v[36:37], v[6:7], 0, s[0:1]
	s_mov_b32 m0, s26
	v_readfirstlane_b32 s27, v34
	global_load_lds_dwordx4 v[36:37], off
	v_lshl_add_u64 v[36:37], v[8:9], 0, s[0:1]
	s_mov_b32 m0, s27
	v_lshlrev_b32_e32 v162, 1, v33
	global_load_lds_dwordx4 v[36:37], off
	v_add_u32_e32 v36, 0xc000, v161
	v_add_u32_e32 v33, 0x4000, v162
	v_readfirstlane_b32 s28, v36
	v_lshl_add_u64 v[34:35], v[10:11], 0, s[0:1]
	s_mov_b32 m0, s28
	v_readfirstlane_b32 s29, v33
	v_add_u32_e32 v33, 0xc000, v162
	global_load_lds_dwordx4 v[34:35], off
	v_lshl_add_u64 v[34:35], v[12:13], 0, s[0:1]
	s_mov_b32 m0, s29
	v_readfirstlane_b32 s30, v33
	global_load_lds_dwordx4 v[34:35], off
	v_lshl_add_u64 v[34:35], v[14:15], 0, s[0:1]
	s_mov_b32 m0, s30
	v_and_b32_e32 v33, 15, v32
	global_load_lds_dwordx4 v[34:35], off
	v_lshrrev_b32_e32 v37, 1, v32
	v_lshlrev_b64 v[64:65], 12, v[16:17]
	v_lshlrev_b64 v[66:67], 12, v[18:19]
	v_lshlrev_b64 v[68:69], 12, v[20:21]
	v_lshlrev_b64 v[70:71], 12, v[22:23]
	v_lshlrev_b64 v[72:73], 12, v[24:25]
	v_lshlrev_b64 v[74:75], 12, v[26:27]
	v_lshlrev_b64 v[76:77], 12, v[28:29]
	v_lshlrev_b64 v[78:79], 12, v[30:31]
	v_lshrrev_b32_e32 v34, 4, v32
	v_bfe_u32 v35, v32, 4, 2
	v_bfe_u32 v36, v32, 1, 3
	v_and_or_b32 v33, v37, s13, v33
	v_lshlrev_b32_e32 v32, 7, v32
	v_lshl_add_u64 v[16:17], v[134:135], 0, v[64:65]
	v_lshl_add_u64 v[18:19], v[136:137], 0, v[66:67]
	v_lshl_add_u64 v[20:21], v[134:135], 0, v[68:69]
	v_lshl_add_u64 v[22:23], v[136:137], 0, v[70:71]
	v_lshl_add_u64 v[24:25], v[134:135], 0, v[72:73]
	v_lshl_add_u64 v[26:27], v[136:137], 0, v[74:75]
	v_lshl_add_u64 v[28:29], v[134:135], 0, v[76:77]
	v_lshl_add_u64 v[30:31], v[136:137], 0, v[78:79]
	v_lshlrev_b32_e32 v116, 7, v33
	v_and_b32_e32 v142, 0x2780, v32
	v_bitop3_b32 v32, v34, v36, 3 bitop3:0x6c
	v_bitop3_b32 v117, v35, v36, 4 bitop3:0x36
	v_lshlrev_b32_e32 v48, 4, v32
	v_or_b32_e32 v163, v116, v48
	v_or_b32_e32 v164, v142, v48
	ds_read_b128 v[32:35], v163
	ds_read_b128 v[36:39], v163 offset:2048
	ds_read_b128 v[40:43], v163 offset:4096
	ds_read_b128 v[44:47], v163 offset:6144
	ds_read_b128 v[48:51], v164 offset:32768
	ds_read_b128 v[52:55], v164 offset:34816
	ds_read_b128 v[56:59], v164 offset:36864
	ds_read_b128 v[60:63], v164 offset:38912
	s_setprio 1
	s_waitcnt lgkmcnt(0)
	v_mfma_f32_16x16x32_bf16 v[80:83], v[48:51], v[32:35], 0
	s_mov_b32 s20, 0
	v_mfma_f32_16x16x32_bf16 v[84:87], v[52:55], v[32:35], 0
	v_mfma_f32_16x16x32_bf16 v[88:91], v[56:59], v[32:35], 0
	v_mfma_f32_16x16x32_bf16 v[32:35], v[60:63], v[32:35], 0
	v_mfma_f32_16x16x32_bf16 v[92:95], v[48:51], v[36:39], 0
	v_mfma_f32_16x16x32_bf16 v[96:99], v[52:55], v[36:39], 0
	v_mfma_f32_16x16x32_bf16 v[100:103], v[56:59], v[36:39], 0
	v_mfma_f32_16x16x32_bf16 v[36:39], v[60:63], v[36:39], 0
	v_mfma_f32_16x16x32_bf16 v[104:107], v[48:51], v[40:43], 0
	v_mfma_f32_16x16x32_bf16 v[108:111], v[52:55], v[40:43], 0
	v_mfma_f32_16x16x32_bf16 v[112:115], v[56:59], v[40:43], 0
	v_mfma_f32_16x16x32_bf16 v[40:43], v[60:63], v[40:43], 0
	v_mfma_f32_16x16x32_bf16 v[48:51], v[48:51], v[44:47], 0
	v_mfma_f32_16x16x32_bf16 v[52:55], v[52:55], v[44:47], 0
	v_mfma_f32_16x16x32_bf16 v[56:59], v[56:59], v[44:47], 0
	v_mfma_f32_16x16x32_bf16 v[44:47], v[60:63], v[44:47], 0
	s_setprio 0
	v_lshlrev_b32_e32 v143, 4, v117
	v_or_b32_e32 v165, v116, v143
	v_or_b32_e32 v166, v142, v143
	ds_read_b128 v[142:145], v166 offset:32768
	ds_read_b128 v[146:149], v166 offset:34816
	ds_read_b128 v[150:153], v166 offset:36864
	ds_read_b128 v[154:157], v166 offset:38912
	ds_read_b128 v[60:63], v165
	ds_read_b128 v[116:119], v165 offset:2048
	ds_read_b128 v[120:123], v165 offset:4096
	ds_read_b128 v[124:127], v165 offset:6144
	s_setprio 1
	s_waitcnt lgkmcnt(3)
	v_mfma_f32_16x16x32_bf16 v[80:83], v[142:145], v[60:63], v[80:83]
	v_mfma_f32_16x16x32_bf16 v[84:87], v[146:149], v[60:63], v[84:87]
	v_mfma_f32_16x16x32_bf16 v[88:91], v[150:153], v[60:63], v[88:91]
	v_mfma_f32_16x16x32_bf16 v[32:35], v[154:157], v[60:63], v[32:35]
	s_waitcnt lgkmcnt(2)
	v_mfma_f32_16x16x32_bf16 v[60:63], v[142:145], v[116:119], v[92:95]
	v_mfma_f32_16x16x32_bf16 v[92:95], v[146:149], v[116:119], v[96:99]
	v_mfma_f32_16x16x32_bf16 v[96:99], v[150:153], v[116:119], v[100:103]
	v_mfma_f32_16x16x32_bf16 v[36:39], v[154:157], v[116:119], v[36:39]
	s_waitcnt lgkmcnt(1)
	v_mfma_f32_16x16x32_bf16 v[100:103], v[142:145], v[120:123], v[104:107]
	v_mfma_f32_16x16x32_bf16 v[104:107], v[146:149], v[120:123], v[108:111]
	v_mfma_f32_16x16x32_bf16 v[108:111], v[150:153], v[120:123], v[112:115]
	v_mfma_f32_16x16x32_bf16 v[40:43], v[154:157], v[120:123], v[40:43]
	s_waitcnt lgkmcnt(0)
	v_mfma_f32_16x16x32_bf16 v[48:51], v[142:145], v[124:127], v[48:51]
	v_mfma_f32_16x16x32_bf16 v[52:55], v[146:149], v[124:127], v[52:55]
	v_mfma_f32_16x16x32_bf16 v[56:59], v[150:153], v[124:127], v[56:59]
	v_mfma_f32_16x16x32_bf16 v[44:47], v[154:157], v[124:127], v[44:47]
	s_setprio 0
	v_readfirstlane_b32 s31, v159
	v_add_u32_e32 v114, 0x8000, v159
	v_lshl_add_u64 v[112:113], v[0:1], 0, s[2:3]
	s_mov_b32 m0, s31
	v_readfirstlane_b32 s33, v114
	s_waitcnt vmcnt(0)
	s_waitcnt vmcnt(0)
	s_barrier
	global_load_lds_dwordx4 v[112:113], off
	v_lshl_add_u64 v[112:113], v[2:3], 0, s[2:3]
	s_mov_b32 m0, s33
	v_readfirstlane_b32 s34, v160
	v_add_u32_e32 v114, 0x8000, v160
	global_load_lds_dwordx4 v[112:113], off
	v_lshl_add_u64 v[112:113], v[4:5], 0, s[2:3]
	s_mov_b32 m0, s34
	v_readfirstlane_b32 s35, v114
	global_load_lds_dwordx4 v[112:113], off
	v_lshl_add_u64 v[112:113], v[6:7], 0, s[2:3]
	s_mov_b32 m0, s35
	v_readfirstlane_b32 s36, v161
	v_add_u32_e32 v114, 0x8000, v161
	global_load_lds_dwordx4 v[112:113], off
	v_lshl_add_u64 v[112:113], v[8:9], 0, s[2:3]
	s_mov_b32 m0, s36
	v_readfirstlane_b32 s37, v114
	global_load_lds_dwordx4 v[112:113], off
	v_lshl_add_u64 v[112:113], v[10:11], 0, s[2:3]
	s_mov_b32 m0, s37
	v_readfirstlane_b32 s38, v162
	v_add_u32_e32 v114, 0x8000, v162
	global_load_lds_dwordx4 v[112:113], off
	v_lshl_add_u64 v[112:113], v[12:13], 0, s[2:3]
	s_mov_b32 m0, s38
	v_readfirstlane_b32 s39, v114
	global_load_lds_dwordx4 v[112:113], off
	v_lshl_add_u64 v[112:113], v[14:15], 0, s[2:3]
	s_mov_b32 m0, s39
	s_nop 0
	global_load_lds_dwordx4 v[112:113], off
	ds_read_b128 v[142:145], v164 offset:49152
	ds_read_b128 v[146:149], v164 offset:51200
	ds_read_b128 v[150:153], v164 offset:53248
	ds_read_b128 v[154:157], v164 offset:55296
	ds_read_b128 v[112:115], v163 offset:16384
	ds_read_b128 v[116:119], v163 offset:18432
	ds_read_b128 v[120:123], v163 offset:20480
	ds_read_b128 v[124:127], v163 offset:22528
	s_setprio 1
	s_waitcnt lgkmcnt(3)
	v_mfma_f32_16x16x32_bf16 v[80:83], v[142:145], v[112:115], v[80:83]
	v_mfma_f32_16x16x32_bf16 v[84:87], v[146:149], v[112:115], v[84:87]
	v_mfma_f32_16x16x32_bf16 v[88:91], v[150:153], v[112:115], v[88:91]
	v_mfma_f32_16x16x32_bf16 v[32:35], v[154:157], v[112:115], v[32:35]
	s_waitcnt lgkmcnt(2)
	v_mfma_f32_16x16x32_bf16 v[60:63], v[142:145], v[116:119], v[60:63]
	v_mfma_f32_16x16x32_bf16 v[92:95], v[146:149], v[116:119], v[92:95]
	v_mfma_f32_16x16x32_bf16 v[96:99], v[150:153], v[116:119], v[96:99]
	v_mfma_f32_16x16x32_bf16 v[36:39], v[154:157], v[116:119], v[36:39]
	s_waitcnt lgkmcnt(1)
	v_mfma_f32_16x16x32_bf16 v[100:103], v[142:145], v[120:123], v[100:103]
	v_mfma_f32_16x16x32_bf16 v[104:107], v[146:149], v[120:123], v[104:107]
	v_mfma_f32_16x16x32_bf16 v[108:111], v[150:153], v[120:123], v[108:111]
	v_mfma_f32_16x16x32_bf16 v[40:43], v[154:157], v[120:123], v[40:43]
	s_waitcnt lgkmcnt(0)
	v_mfma_f32_16x16x32_bf16 v[48:51], v[142:145], v[124:127], v[48:51]
	v_mfma_f32_16x16x32_bf16 v[52:55], v[146:149], v[124:127], v[52:55]
	v_mfma_f32_16x16x32_bf16 v[56:59], v[150:153], v[124:127], v[56:59]
	v_mfma_f32_16x16x32_bf16 v[44:47], v[154:157], v[124:127], v[44:47]
	s_setprio 0
	ds_read_b128 v[142:145], v166 offset:49152
	ds_read_b128 v[146:149], v166 offset:51200
	ds_read_b128 v[150:153], v166 offset:53248
	ds_read_b128 v[154:157], v166 offset:55296
	ds_read_b128 v[112:115], v165 offset:16384
	ds_read_b128 v[116:119], v165 offset:18432
	ds_read_b128 v[120:123], v165 offset:20480
	ds_read_b128 v[124:127], v165 offset:22528
	s_setprio 1
	s_waitcnt lgkmcnt(3)
	v_mfma_f32_16x16x32_bf16 v[80:83], v[142:145], v[112:115], v[80:83]
	v_mfma_f32_16x16x32_bf16 v[84:87], v[146:149], v[112:115], v[84:87]
	v_mfma_f32_16x16x32_bf16 v[88:91], v[150:153], v[112:115], v[88:91]
	v_mfma_f32_16x16x32_bf16 v[32:35], v[154:157], v[112:115], v[32:35]
	s_waitcnt lgkmcnt(2)
	v_mfma_f32_16x16x32_bf16 v[60:63], v[142:145], v[116:119], v[60:63]
	v_mfma_f32_16x16x32_bf16 v[92:95], v[146:149], v[116:119], v[92:95]
	v_mfma_f32_16x16x32_bf16 v[96:99], v[150:153], v[116:119], v[96:99]
	v_mfma_f32_16x16x32_bf16 v[36:39], v[154:157], v[116:119], v[36:39]
	s_waitcnt lgkmcnt(1)
	v_mfma_f32_16x16x32_bf16 v[100:103], v[142:145], v[120:123], v[100:103]
	v_mfma_f32_16x16x32_bf16 v[104:107], v[146:149], v[120:123], v[104:107]
	v_mfma_f32_16x16x32_bf16 v[108:111], v[150:153], v[120:123], v[108:111]
	v_mfma_f32_16x16x32_bf16 v[40:43], v[154:157], v[120:123], v[40:43]
	s_waitcnt lgkmcnt(0)
	v_mfma_f32_16x16x32_bf16 v[48:51], v[142:145], v[124:127], v[48:51]
	v_mfma_f32_16x16x32_bf16 v[52:55], v[146:149], v[124:127], v[52:55]
	v_mfma_f32_16x16x32_bf16 v[56:59], v[150:153], v[124:127], v[56:59]
	v_mfma_f32_16x16x32_bf16 v[44:47], v[154:157], v[124:127], v[44:47]
	s_setprio 0
	s_mov_b32 m0, s21
	v_lshl_add_u64 v[0:1], v[0:1], 0, s[4:5]
	s_waitcnt vmcnt(0)
	s_waitcnt vmcnt(0)
	s_barrier
	global_load_lds_dwordx4 v[0:1], off
	v_lshl_add_u64 v[0:1], v[2:3], 0, s[4:5]
	s_mov_b32 m0, s18
	s_nop 0
	global_load_lds_dwordx4 v[0:1], off
	v_lshl_add_u64 v[0:1], v[4:5], 0, s[4:5]
	s_mov_b32 m0, s19
	s_nop 0
	global_load_lds_dwordx4 v[0:1], off
	v_lshl_add_u64 v[0:1], v[6:7], 0, s[4:5]
	s_mov_b32 m0, s26
	s_nop 0
	global_load_lds_dwordx4 v[0:1], off
	v_lshl_add_u64 v[0:1], v[8:9], 0, s[4:5]
	s_mov_b32 m0, s27
	s_nop 0
	global_load_lds_dwordx4 v[0:1], off
	v_lshl_add_u64 v[0:1], v[10:11], 0, s[4:5]
	s_mov_b32 m0, s28
	s_nop 0
	global_load_lds_dwordx4 v[0:1], off
	v_lshl_add_u64 v[0:1], v[12:13], 0, s[4:5]
	s_mov_b32 m0, s29
	s_nop 0
	global_load_lds_dwordx4 v[0:1], off
	v_lshl_add_u64 v[0:1], v[14:15], 0, s[4:5]
	s_mov_b32 m0, s30
	s_nop 0
	global_load_lds_dwordx4 v[0:1], off
	ds_read_b128 v[112:115], v164 offset:32768
	ds_read_b128 v[116:119], v164 offset:34816
	ds_read_b128 v[120:123], v164 offset:36864
	ds_read_b128 v[124:127], v164 offset:38912
	ds_read_b128 v[0:3], v163
	ds_read_b128 v[4:7], v163 offset:2048
	ds_read_b128 v[8:11], v163 offset:4096
	ds_read_b128 v[12:15], v163 offset:6144
	s_setprio 1
	s_waitcnt lgkmcnt(3)
	v_mfma_f32_16x16x32_bf16 v[80:83], v[112:115], v[0:3], v[80:83]
	v_mfma_f32_16x16x32_bf16 v[84:87], v[116:119], v[0:3], v[84:87]
	v_mfma_f32_16x16x32_bf16 v[88:91], v[120:123], v[0:3], v[88:91]
	v_mfma_f32_16x16x32_bf16 v[0:3], v[124:127], v[0:3], v[32:35]
	s_waitcnt lgkmcnt(2)
	v_mfma_f32_16x16x32_bf16 v[32:35], v[112:115], v[4:7], v[60:63]
	v_mfma_f32_16x16x32_bf16 v[60:63], v[116:119], v[4:7], v[92:95]
	v_mfma_f32_16x16x32_bf16 v[92:95], v[120:123], v[4:7], v[96:99]
	v_mfma_f32_16x16x32_bf16 v[4:7], v[124:127], v[4:7], v[36:39]
	s_waitcnt lgkmcnt(1)
	v_mfma_f32_16x16x32_bf16 v[36:39], v[112:115], v[8:11], v[100:103]
	v_mfma_f32_16x16x32_bf16 v[96:99], v[116:119], v[8:11], v[104:107]
	v_mfma_f32_16x16x32_bf16 v[100:103], v[120:123], v[8:11], v[108:111]
	v_mfma_f32_16x16x32_bf16 v[8:11], v[124:127], v[8:11], v[40:43]
	s_waitcnt lgkmcnt(0)
	v_mfma_f32_16x16x32_bf16 v[40:43], v[112:115], v[12:15], v[48:51]
	v_mfma_f32_16x16x32_bf16 v[48:51], v[116:119], v[12:15], v[52:55]
	v_mfma_f32_16x16x32_bf16 v[52:55], v[120:123], v[12:15], v[56:59]
	v_mfma_f32_16x16x32_bf16 v[12:15], v[124:127], v[12:15], v[44:47]
	s_setprio 0
	s_nop 1
	ds_read_b128 v[112:115], v166 offset:32768
	ds_read_b128 v[116:119], v166 offset:34816
	ds_read_b128 v[120:123], v166 offset:36864
	ds_read_b128 v[124:127], v166 offset:38912
	ds_read_b128 v[44:47], v165
	ds_read_b128 v[56:59], v165 offset:2048
	ds_read_b128 v[104:107], v165 offset:4096
	ds_read_b128 v[108:111], v165 offset:6144
	s_setprio 1
	s_waitcnt lgkmcnt(3)
	v_mfma_f32_16x16x32_bf16 v[80:83], v[112:115], v[44:47], v[80:83]
	v_mfma_f32_16x16x32_bf16 v[84:87], v[116:119], v[44:47], v[84:87]
	v_mfma_f32_16x16x32_bf16 v[88:91], v[120:123], v[44:47], v[88:91]
	v_mfma_f32_16x16x32_bf16 v[0:3], v[124:127], v[44:47], v[0:3]
	s_waitcnt lgkmcnt(2)
	v_mfma_f32_16x16x32_bf16 v[32:35], v[112:115], v[56:59], v[32:35]
	v_mfma_f32_16x16x32_bf16 v[44:47], v[116:119], v[56:59], v[60:63]
	v_mfma_f32_16x16x32_bf16 v[60:63], v[120:123], v[56:59], v[92:95]
	v_mfma_f32_16x16x32_bf16 v[4:7], v[124:127], v[56:59], v[4:7]
	s_waitcnt lgkmcnt(1)
	v_mfma_f32_16x16x32_bf16 v[36:39], v[112:115], v[104:107], v[36:39]
	v_mfma_f32_16x16x32_bf16 v[56:59], v[116:119], v[104:107], v[96:99]
	v_mfma_f32_16x16x32_bf16 v[92:95], v[120:123], v[104:107], v[100:103]
	v_mfma_f32_16x16x32_bf16 v[8:11], v[124:127], v[104:107], v[8:11]
	s_waitcnt lgkmcnt(0)
	v_mfma_f32_16x16x32_bf16 v[40:43], v[112:115], v[108:111], v[40:43]
	v_mfma_f32_16x16x32_bf16 v[48:51], v[116:119], v[108:111], v[48:51]
	v_mfma_f32_16x16x32_bf16 v[52:55], v[120:123], v[108:111], v[52:55]
	v_mfma_f32_16x16x32_bf16 v[12:15], v[124:127], v[108:111], v[12:15]
	s_setprio 0
	s_mov_b32 m0, s31
	s_waitcnt vmcnt(0)
	s_waitcnt vmcnt(0)
	s_barrier
	global_load_lds_dwordx4 v[16:17], off
	s_mov_b32 m0, s33
	s_nop 0
	global_load_lds_dwordx4 v[18:19], off
	s_mov_b32 m0, s34
	s_nop 0
	global_load_lds_dwordx4 v[20:21], off
	s_mov_b32 m0, s35
	s_nop 0
	global_load_lds_dwordx4 v[22:23], off
	s_mov_b32 m0, s36
	s_nop 0
	global_load_lds_dwordx4 v[24:25], off
	s_mov_b32 m0, s37
	s_nop 0
	global_load_lds_dwordx4 v[26:27], off
	s_mov_b32 m0, s38
	s_nop 0
	global_load_lds_dwordx4 v[28:29], off
	s_mov_b32 m0, s39
	s_nop 0
	global_load_lds_dwordx4 v[30:31], off
	ds_read_b128 v[96:99], v164 offset:49152
	ds_read_b128 v[100:103], v164 offset:51200
	ds_read_b128 v[104:107], v164 offset:53248
	ds_read_b128 v[108:111], v164 offset:55296
	ds_read_b128 v[16:19], v163 offset:16384
	ds_read_b128 v[20:23], v163 offset:18432
	ds_read_b128 v[24:27], v163 offset:20480
	ds_read_b128 v[28:31], v163 offset:22528
	s_setprio 1
	s_waitcnt lgkmcnt(3)
	v_mfma_f32_16x16x32_bf16 v[80:83], v[96:99], v[16:19], v[80:83]
	v_mfma_f32_16x16x32_bf16 v[84:87], v[100:103], v[16:19], v[84:87]
	v_mfma_f32_16x16x32_bf16 v[88:91], v[104:107], v[16:19], v[88:91]
	v_mfma_f32_16x16x32_bf16 v[16:19], v[108:111], v[16:19], v[0:3]
	s_waitcnt lgkmcnt(2)
	v_mfma_f32_16x16x32_bf16 v[32:35], v[96:99], v[20:23], v[32:35]
	v_mfma_f32_16x16x32_bf16 v[44:47], v[100:103], v[20:23], v[44:47]
	v_mfma_f32_16x16x32_bf16 v[60:63], v[104:107], v[20:23], v[60:63]
	v_mfma_f32_16x16x32_bf16 v[112:115], v[108:111], v[20:23], v[4:7]
	s_waitcnt lgkmcnt(1)
	v_mfma_f32_16x16x32_bf16 v[36:39], v[96:99], v[24:27], v[36:39]
	v_mfma_f32_16x16x32_bf16 v[56:59], v[100:103], v[24:27], v[56:59]
	v_mfma_f32_16x16x32_bf16 v[92:95], v[104:107], v[24:27], v[92:95]
	v_mfma_f32_16x16x32_bf16 v[116:119], v[108:111], v[24:27], v[8:11]
	s_waitcnt lgkmcnt(0)
	v_mfma_f32_16x16x32_bf16 v[96:99], v[96:99], v[28:31], v[40:43]
	v_mfma_f32_16x16x32_bf16 v[100:103], v[100:103], v[28:31], v[48:51]
	v_mfma_f32_16x16x32_bf16 v[104:107], v[104:107], v[28:31], v[52:55]
	v_mfma_f32_16x16x32_bf16 v[108:111], v[108:111], v[28:31], v[12:15]
	s_setprio 0
	s_nop 1
	ds_read_b128 v[52:55], v166 offset:49152
	ds_read_b128 v[124:127], v166 offset:51200
	ds_read_b128 v[142:145], v166 offset:53248
	ds_read_b128 v[146:149], v166 offset:55296
	ds_read_b128 v[12:15], v165 offset:16384
	ds_read_b128 v[28:31], v165 offset:18432
	ds_read_b128 v[48:51], v165 offset:20480
	ds_read_b128 v[120:123], v165 offset:22528
	s_setprio 1
	s_waitcnt lgkmcnt(3)
	v_mfma_f32_16x16x32_bf16 v[0:3], v[52:55], v[12:15], v[80:83]
	v_mfma_f32_16x16x32_bf16 v[4:7], v[124:127], v[12:15], v[84:87]
	v_mfma_f32_16x16x32_bf16 v[8:11], v[142:145], v[12:15], v[88:91]
	v_mfma_f32_16x16x32_bf16 v[12:15], v[146:149], v[12:15], v[16:19]
	s_waitcnt lgkmcnt(2)
	v_mfma_f32_16x16x32_bf16 v[16:19], v[52:55], v[28:31], v[32:35]
	v_mfma_f32_16x16x32_bf16 v[20:23], v[124:127], v[28:31], v[44:47]
	v_mfma_f32_16x16x32_bf16 v[24:27], v[142:145], v[28:31], v[60:63]
	v_mfma_f32_16x16x32_bf16 v[28:31], v[146:149], v[28:31], v[112:115]
	s_waitcnt lgkmcnt(1)
	v_mfma_f32_16x16x32_bf16 v[32:35], v[52:55], v[48:51], v[36:39]
	v_mfma_f32_16x16x32_bf16 v[36:39], v[124:127], v[48:51], v[56:59]
	v_mfma_f32_16x16x32_bf16 v[40:43], v[142:145], v[48:51], v[92:95]
	v_mfma_f32_16x16x32_bf16 v[44:47], v[146:149], v[48:51], v[116:119]
	s_waitcnt lgkmcnt(0)
	v_mfma_f32_16x16x32_bf16 v[48:51], v[52:55], v[120:123], v[96:99]
	v_mfma_f32_16x16x32_bf16 v[52:55], v[124:127], v[120:123], v[100:103]
	v_mfma_f32_16x16x32_bf16 v[56:59], v[142:145], v[120:123], v[104:107]
	v_mfma_f32_16x16x32_bf16 v[60:63], v[146:149], v[120:123], v[108:111]
	s_setprio 0
	v_mov_b32_e32 v80, v199
	v_lshl_add_u64 v[142:143], v[138:139], 0, v[64:65]
	v_and_b32_e32 v81, 15, v80
	v_lshrrev_b32_e32 v85, 1, v80
	v_and_or_b32 v81, v85, s13, v81
	v_lshrrev_b32_e32 v82, 4, v80
	v_bfe_u32 v83, v80, 4, 2
	v_bfe_u32 v84, v80, 1, 3
	v_lshlrev_b32_e32 v160, 7, v81
	v_lshlrev_b32_e32 v81, 7, v80
	v_and_b32_e32 v159, 0x2780, v81
	v_bitop3_b32 v81, v82, v84, 3 bitop3:0x6c
	v_bitop3_b32 v82, v83, v84, 4 bitop3:0x36
	v_lshlrev_b32_e32 v81, 3, v81
	v_lshlrev_b32_e32 v82, 3, v82
	v_mov_b32_e32 v64, 0
	v_lshlrev_b32_e32 v163, 4, v80
	v_lshl_add_u64 v[144:145], v[140:141], 0, v[66:67]
	v_lshl_add_u64 v[146:147], v[138:139], 0, v[68:69]
	v_lshl_add_u64 v[148:149], v[140:141], 0, v[70:71]
	v_lshl_add_u64 v[150:151], v[138:139], 0, v[72:73]
	v_lshl_add_u64 v[152:153], v[140:141], 0, v[74:75]
	v_lshl_add_u64 v[154:155], v[138:139], 0, v[76:77]
	v_lshl_add_u64 v[156:157], v[140:141], 0, v[78:79]
	s_mov_b64 s[18:19], 0
	v_lshlrev_b32_e32 v162, 1, v81
	v_lshlrev_b32_e32 v161, 1, v82
	v_mov_b32_e32 v65, v64
	v_mov_b32_e32 v66, v64
	v_mov_b32_e32 v67, v64
	v_mov_b32_e32 v68, v64
	v_mov_b32_e32 v69, v64
	v_mov_b32_e32 v70, v64
	v_mov_b32_e32 v71, v64
	v_mov_b32_e32 v72, v64
	v_mov_b32_e32 v73, v64
	v_mov_b32_e32 v74, v64
	v_mov_b32_e32 v75, v64
	v_mov_b32_e32 v76, v64
	v_mov_b32_e32 v77, v64
	v_mov_b32_e32 v78, v64
	v_mov_b32_e32 v79, v64
	v_mov_b32_e32 v80, v64
	v_mov_b32_e32 v81, v64
	v_mov_b32_e32 v82, v64
	v_mov_b32_e32 v83, v64
	v_mov_b32_e32 v84, v64
	v_mov_b32_e32 v85, v64
	v_mov_b32_e32 v86, v64
	v_mov_b32_e32 v87, v64
	v_mov_b32_e32 v88, v64
	v_mov_b32_e32 v89, v64
	v_mov_b32_e32 v90, v64
	v_mov_b32_e32 v91, v64
	v_mov_b32_e32 v92, v64
	v_mov_b32_e32 v93, v64
	v_mov_b32_e32 v94, v64
	v_mov_b32_e32 v95, v64
	v_mov_b32_e32 v96, v64
	v_mov_b32_e32 v97, v64
	v_mov_b32_e32 v98, v64
	v_mov_b32_e32 v99, v64
	v_mov_b32_e32 v100, v64
	v_mov_b32_e32 v101, v64
	v_mov_b32_e32 v102, v64
	v_mov_b32_e32 v103, v64
	v_mov_b32_e32 v104, v64
	v_mov_b32_e32 v105, v64
	v_mov_b32_e32 v106, v64
	v_mov_b32_e32 v107, v64
	v_mov_b32_e32 v108, v64
	v_mov_b32_e32 v109, v64
	v_mov_b32_e32 v110, v64
	v_mov_b32_e32 v111, v64
	v_mov_b32_e32 v112, v64
	v_mov_b32_e32 v113, v64
	v_mov_b32_e32 v114, v64
	v_mov_b32_e32 v115, v64
	v_mov_b32_e32 v116, v64
	v_mov_b32_e32 v117, v64
	v_mov_b32_e32 v118, v64
	v_mov_b32_e32 v119, v64
	v_mov_b32_e32 v120, v64
	v_mov_b32_e32 v121, v64
	v_mov_b32_e32 v122, v64
	v_mov_b32_e32 v123, v64
	v_mov_b32_e32 v124, v64
	v_mov_b32_e32 v125, v64
	v_mov_b32_e32 v126, v64
	v_mov_b32_e32 v127, v64
.LBB0_977:
	s_and_b32 s21, s20, 0x2000
	s_xor_b32 s26, s21, 0x2000
	v_lshl_add_u32 v166, s26, 1, v163
	v_add_u32_e32 v167, 0x8000, v166
	v_readfirstlane_b32 s26, v166
	v_lshl_add_u64 v[164:165], v[142:143], 0, s[18:19]
	s_mov_b32 m0, s26
	v_readfirstlane_b32 s26, v167
	v_add_u32_e32 v167, 0x1000, v166
	s_waitcnt vmcnt(0)
	s_waitcnt vmcnt(0)
	s_barrier
	global_load_lds_dwordx4 v[164:165], off
	v_lshl_add_u64 v[164:165], v[144:145], 0, s[18:19]
	s_mov_b32 m0, s26
	v_readfirstlane_b32 s26, v167
	v_add_u32_e32 v167, 0x9000, v166
	global_load_lds_dwordx4 v[164:165], off
	v_lshl_add_u64 v[164:165], v[146:147], 0, s[18:19]
	s_mov_b32 m0, s26
	v_readfirstlane_b32 s26, v167
	v_add_u32_e32 v167, 0x2000, v166
	global_load_lds_dwordx4 v[164:165], off
	v_lshl_add_u64 v[164:165], v[148:149], 0, s[18:19]
	s_mov_b32 m0, s26
	v_readfirstlane_b32 s26, v167
	v_add_u32_e32 v167, 0xa000, v166
	global_load_lds_dwordx4 v[164:165], off
	v_lshl_add_u64 v[164:165], v[150:151], 0, s[18:19]
	s_mov_b32 m0, s26
	v_readfirstlane_b32 s26, v167
	v_add_u32_e32 v167, 0x3000, v166
	global_load_lds_dwordx4 v[164:165], off
	v_lshl_add_u64 v[164:165], v[152:153], 0, s[18:19]
	s_mov_b32 m0, s26
	v_readfirstlane_b32 s26, v167
	v_add_u32_e32 v166, 0xb000, v166
	global_load_lds_dwordx4 v[164:165], off
	v_lshl_add_u64 v[164:165], v[154:155], 0, s[18:19]
	s_mov_b32 m0, s26
	v_readfirstlane_b32 s26, v166
	global_load_lds_dwordx4 v[164:165], off
	v_lshl_add_u64 v[164:165], v[156:157], 0, s[18:19]
	s_mov_b32 m0, s26
	s_nop 0
	global_load_lds_dwordx4 v[164:165], off
	s_lshl_b32 s21, s21, 1
	v_add_u32_e32 v196, s21, v160
	v_or_b32_e32 v197, s21, v159
	v_add_u32_e32 v176, v196, v162
	v_add_u32_e32 v192, v197, v162
	ds_read_b128 v[180:183], v192 offset:32768
	ds_read_b128 v[184:187], v192 offset:34816
	ds_read_b128 v[188:191], v192 offset:36864
	ds_read_b128 v[192:195], v192 offset:38912
	ds_read_b128 v[164:167], v176
	ds_read_b128 v[168:171], v176 offset:2048
	ds_read_b128 v[172:175], v176 offset:4096
	ds_read_b128 v[176:179], v176 offset:6144
	s_setprio 1
	s_waitcnt lgkmcnt(3)
	v_mfma_f32_16x16x32_bf16 v[64:67], v[180:183], v[164:167], v[64:67]
	v_mfma_f32_16x16x32_bf16 v[68:71], v[184:187], v[164:167], v[68:71]
	v_mfma_f32_16x16x32_bf16 v[72:75], v[188:191], v[164:167], v[72:75]
	v_mfma_f32_16x16x32_bf16 v[76:79], v[192:195], v[164:167], v[76:79]
	s_waitcnt lgkmcnt(2)
	v_mfma_f32_16x16x32_bf16 v[80:83], v[180:183], v[168:171], v[80:83]
	v_mfma_f32_16x16x32_bf16 v[84:87], v[184:187], v[168:171], v[84:87]
	v_mfma_f32_16x16x32_bf16 v[88:91], v[188:191], v[168:171], v[88:91]
	v_mfma_f32_16x16x32_bf16 v[92:95], v[192:195], v[168:171], v[92:95]
	s_waitcnt lgkmcnt(1)
	v_mfma_f32_16x16x32_bf16 v[96:99], v[180:183], v[172:175], v[96:99]
	v_mfma_f32_16x16x32_bf16 v[100:103], v[184:187], v[172:175], v[100:103]
	v_mfma_f32_16x16x32_bf16 v[104:107], v[188:191], v[172:175], v[104:107]
	v_mfma_f32_16x16x32_bf16 v[108:111], v[192:195], v[172:175], v[108:111]
	s_waitcnt lgkmcnt(0)
	v_mfma_f32_16x16x32_bf16 v[112:115], v[180:183], v[176:179], v[112:115]
	v_mfma_f32_16x16x32_bf16 v[116:119], v[184:187], v[176:179], v[116:119]
	v_mfma_f32_16x16x32_bf16 v[120:123], v[188:191], v[176:179], v[120:123]
	v_mfma_f32_16x16x32_bf16 v[124:127], v[192:195], v[176:179], v[124:127]
	s_setprio 0
	v_add_u32_e32 v176, v196, v161
	v_add_u32_e32 v192, v197, v161
	ds_read_b128 v[180:183], v192 offset:32768
	ds_read_b128 v[184:187], v192 offset:34816
	ds_read_b128 v[188:191], v192 offset:36864
	ds_read_b128 v[192:195], v192 offset:38912
	ds_read_b128 v[164:167], v176
	ds_read_b128 v[168:171], v176 offset:2048
	ds_read_b128 v[172:175], v176 offset:4096
	ds_read_b128 v[176:179], v176 offset:6144
	s_setprio 1
	s_waitcnt lgkmcnt(3)
	v_mfma_f32_16x16x32_bf16 v[64:67], v[180:183], v[164:167], v[64:67]
	v_mfma_f32_16x16x32_bf16 v[68:71], v[184:187], v[164:167], v[68:71]
	v_mfma_f32_16x16x32_bf16 v[72:75], v[188:191], v[164:167], v[72:75]
	v_mfma_f32_16x16x32_bf16 v[76:79], v[192:195], v[164:167], v[76:79]
	s_waitcnt lgkmcnt(2)
	v_mfma_f32_16x16x32_bf16 v[80:83], v[180:183], v[168:171], v[80:83]
	v_mfma_f32_16x16x32_bf16 v[84:87], v[184:187], v[168:171], v[84:87]
	v_mfma_f32_16x16x32_bf16 v[88:91], v[188:191], v[168:171], v[88:91]
	v_mfma_f32_16x16x32_bf16 v[92:95], v[192:195], v[168:171], v[92:95]
	s_waitcnt lgkmcnt(1)
	v_mfma_f32_16x16x32_bf16 v[96:99], v[180:183], v[172:175], v[96:99]
	v_mfma_f32_16x16x32_bf16 v[100:103], v[184:187], v[172:175], v[100:103]
	v_mfma_f32_16x16x32_bf16 v[104:107], v[188:191], v[172:175], v[104:107]
	v_mfma_f32_16x16x32_bf16 v[108:111], v[192:195], v[172:175], v[108:111]
	s_waitcnt lgkmcnt(0)
	v_mfma_f32_16x16x32_bf16 v[112:115], v[180:183], v[176:179], v[112:115]
	v_mfma_f32_16x16x32_bf16 v[116:119], v[184:187], v[176:179], v[116:119]
	v_mfma_f32_16x16x32_bf16 v[120:123], v[188:191], v[176:179], v[120:123]
	v_mfma_f32_16x16x32_bf16 v[124:127], v[192:195], v[176:179], v[124:127]
	s_setprio 0
	s_add_u32 s18, s18, 0x80
	s_addc_u32 s19, s19, 0
	s_addk_i32 s20, 0x2000
	s_cmpk_lg_i32 s18, 0xf80
	s_cbranch_scc1 .LBB0_977
	s_waitcnt vmcnt(0)
	s_andn2_b64 vcc, exec, s[16:17]
	s_waitcnt vmcnt(0)
	s_barrier
	s_cbranch_vccnz .LBB0_969
	v_add_u32_e32 v142, s24, v128
	v_ashrrev_i32_e32 v143, 31, v142
	v_lshlrev_b64 v[142:143], 9, v[142:143]
	v_readfirstlane_b32 s16, v163
	v_add_u32_e32 v144, s25, v128
	v_lshl_add_u64 v[142:143], v[130:131], 0, v[142:143]
	s_mov_b32 m0, s16
	v_ashrrev_i32_e32 v145, 31, v144
	v_lshl_add_u64 v[146:147], v[142:143], 0, s[6:7]
	v_lshl_add_u64 v[150:151], v[142:143], 0, s[8:9]
	v_lshl_add_u64 v[154:155], v[142:143], 0, s[10:11]
	global_load_lds_dwordx4 v[142:143], off
	v_add_u32_e32 v142, 0x8000, v163
	v_lshlrev_b64 v[144:145], 9, v[144:145]
	v_readfirstlane_b32 s16, v142
	v_add_u32_e32 v142, 0x1000, v163
	v_lshl_add_u64 v[144:145], v[132:133], 0, v[144:145]
	s_mov_b32 m0, s16
	v_readfirstlane_b32 s16, v142
	v_add_u32_e32 v142, 0x9000, v163
	global_load_lds_dwordx4 v[144:145], off
	s_mov_b32 m0, s16
	v_readfirstlane_b32 s16, v142
	v_add_u32_e32 v142, 0x2000, v163
	v_lshl_add_u64 v[148:149], v[144:145], 0, s[6:7]
	global_load_lds_dwordx4 v[146:147], off
	s_mov_b32 m0, s16
	v_readfirstlane_b32 s16, v142
	v_add_u32_e32 v142, 0xa000, v163
	global_load_lds_dwordx4 v[148:149], off
	s_mov_b32 m0, s16
	v_readfirstlane_b32 s16, v142
	v_add_u32_e32 v142, 0x3000, v163
	v_lshl_add_u64 v[152:153], v[144:145], 0, s[8:9]
	global_load_lds_dwordx4 v[150:151], off
	s_mov_b32 m0, s16
	v_readfirstlane_b32 s16, v142
	v_add_u32_e32 v142, 0xb000, v163
	global_load_lds_dwordx4 v[152:153], off
	s_mov_b32 m0, s16
	v_readfirstlane_b32 s16, v142
	v_lshl_add_u64 v[156:157], v[144:145], 0, s[10:11]
	global_load_lds_dwordx4 v[154:155], off
	s_mov_b32 m0, s16
	s_nop 0
	global_load_lds_dwordx4 v[156:157], off
	s_branch .LBB0_969
